# phase 9 ctx pre-pass as split-K (8 K-slices per 128x128 sub-tile, f32 partial tiles in the dead cat buffer), row phase 10 sums the partials for ctx rows
# speedup vs baseline: 1.2477x; 1.0044x over previous
; __device__ __forceinline__ void gemm256_tile(const u16* Ab, int lda, const u16* Bb, int ldb, int K, char* smem,
;                                              f32x16 (&acc)[2][4]) {
;     ...
;   const int drow = wid * 16 + (lane >> 2);
;   const int dk = ((lane & 3) ^ ((lane >> 4) & 3)) * 8;
;   const unsigned ga0 = (unsigned)(drow * lda + dk), ga1 = (unsigned)((drow + 128) * lda + dk);
;   const unsigned gb0 = (unsigned)(drow * ldb + dk), gb1 = (unsigned)((drow + 128) * ldb + dk);
;   const unsigned dl0 = (unsigned)((wid * 64 + lane) * 16), dl1 = (unsigned)(((8 + wid) * 64 + lane) * 16);
;     ...
;   const int xsw = (lane >> 2) & 3, hh = lane >> 5;
;   const unsigned fo0 = (unsigned)((hh ^ xsw) * 16), fo1 = (unsigned)(((2 + hh) ^ xsw) * 16);
;   const unsigned fa = (unsigned)((wm * 64 + (lane & 31)) * 64);
;   const unsigned fb = (unsigned)(16384 + (wn * 128 + (lane & 31)) * 64);
;     ...
;   asm volatile("s_waitcnt vmcnt(0)" ::: "memory");
;   const bool h1 = __builtin_amdgcn_readfirstlane(wid) >= 4;
;     ...
;   DMA_STAGE(0)
;   if (nks > 1) DMA_STAGE(1)
;   if (nks > 2) DMA_STAGE(2)
;   if (nks > 3) DMA_STAGE(3)
; __device__ __forceinline__ void gemm_nt_phase(const u16* A, int lda, const u16* Bt, int ldb, u16* C, int ldc,
;                               int Mt, int Nt, int K, int qcols, float qscale, u16* smem,
;                               u16* vtx = nullptr, u16* vtc = nullptr, u16* smv = nullptr) {
;   if (smv != nullptr) {
;     const int NtS = Nt * 2, nS = 8 * NtS;
;     for (int t = VBID; t < nS; t += VGRID) {
;       const int ms = t / NtS, ns = t - ms * NtS;
;       const u16* Ab = A + (long)(N_X + ms * 128) * lda;
;       const u16* Bb = Bt + (long)ns * 128 * ldb;
;       auto al = [=](int r, int k) { return ldg16(Ab + (unsigned)(r * lda + k)); };
;       auto bl = [=](int r, int k) { return ldg16(Bb + (unsigned)(r * ldb + k)); };
;       f32x16 acc[2][2];
;       gemm_tile<false>(al, bl, K, smv, acc);
.LBB0_1127:
	s_cmp_gt_i32 s34, 9
	s_cselect_b64 s[0:1], -1, 0
	s_cmp_lt_i32 s35, 10
	s_cselect_b64 s[4:5], -1, 0
	s_or_b64 s[0:1], s[0:1], s[4:5]
	s_and_b64 vcc, exec, s[0:1]
	s_cbranch_vccnz .LBB0_1247
	v_mov_b32_e32 v0, v153
	s_cmp_eq_u32 16, -1
	s_cbranch_scc1 .LBB0_1141
	s_waitcnt vmcnt(0)
	s_barrier
	v_readfirstlane_b32 s98, v153
	v_bfe_u32 v108, v152, 6, 2
	v_readlane_b32 s100, v252, 0
	v_readlane_b32 s101, v252, 1
	v_readfirstlane_b32 s99, v108
	s_nop 3
	s_sub_u32 s100, s100, 0x170
	s_subb_u32 s101, s101, 0
	s_lshl_b32 vcc_lo, s2, 1
	s_add_u32 vcc_lo, vcc_lo, s98
	s_lshr_b32 s3, vcc_lo, 6
	s_and_b32 vcc_lo, vcc_lo, 63
	s_lshr_b32 vcc_hi, vcc_lo, 3
	s_and_b32 vcc_lo, vcc_lo, 7
	s_mul_i32 s4, s3, 0x2c0
	v_mul_u32_u24_e32 v108, 0x12000, v153
	v_add_u32_e32 v108, 16, v108
	v_and_b32_e32 v109, 31, v152
	v_bfe_u32 v110, v152, 2, 2
	v_bfe_u32 v111, v152, 5, 1
	v_xor_b32_e32 v112, v111, v110
	v_lshlrev_b32_e32 v112, 4, v112
	v_xor_b32_e32 v113, 32, v112
	v_bfe_u32 v114, v152, 7, 1
	v_lshl_add_u32 v114, v114, 6, v109
	v_lshl_add_u32 v114, v114, 6, v108
	v_bfe_u32 v115, v152, 6, 1
	v_lshl_add_u32 v115, v115, 6, v109
	v_lshl_add_u32 v115, v115, 6, v108
	v_add_u32_e32 v104, v114, v112
	v_add_u32_e32 v105, v114, v113
	v_add_u32_e32 v115, 0x2000, v115
	v_add_u32_e32 v106, v115, v112
	v_add_u32_e32 v107, v115, v113
	v_bfe_u32 v109, v152, 2, 4
	v_bfe_u32 v110, v152, 4, 2
	v_and_b32_e32 v111, 3, v152
	v_xor_b32_e32 v110, v111, v110
	v_bfe_u32 v111, v152, 6, 2
	v_lshl_add_u32 v109, v111, 5, v109
	s_mov_b32 m0, 0x1600
	v_mul_lo_u32 v112, v109, m0
	v_lshl_add_u32 v112, v110, 4, v112
	s_lshl_b32 vcc_hi, vcc_hi, 8
	s_or_b32 s98, s98, vcc_hi
	s_lshl_b32 vcc_lo, vcc_lo, 16
	s_or_b32 s98, s98, vcc_lo
	s_load_dwordx2 s[100:101], s[100:101], 0x148
	s_bfe_u32 m0, s98, 0x80008
	s_lshl_b32 m0, m0, 7
	s_add_u32 m0, m0, 0x8000
	s_mul_i32 m0, m0, 0x1600
	s_add_u32 m0, m0, s4
	s_waitcnt lgkmcnt(0)
	s_add_u32 s100, s100, m0
	s_addc_u32 s101, s101, 0
	v_mov_b32_e32 v113, s101
	v_add_co_u32_e32 v96, vcc, s100, v112
	s_nop 1
	v_addc_co_u32_e32 v97, vcc, 0, v113, vcc
	v_add_co_u32_e32 v98, vcc, 0x16000, v96
	s_nop 1
	v_addc_co_u32_e32 v99, vcc, 0, v97, vcc
	v_readlane_b32 s100, v252, 0
	v_readlane_b32 s101, v252, 1
	s_nop 3
	s_sub_u32 s100, s100, 0x170
	s_subb_u32 s101, s101, 0
	s_load_dwordx2 s[100:101], s[100:101], 0xf8
	s_bfe_u32 m0, s98, 0x80010
	s_lshl_b32 m0, m0, 7
	s_mul_i32 m0, m0, 0x1600
	s_add_u32 m0, m0, s4
	s_waitcnt lgkmcnt(0)
	s_add_u32 s100, s100, m0
	s_addc_u32 s101, s101, 0
	v_mov_b32_e32 v113, s101
	v_add_co_u32_e32 v100, vcc, s100, v112
	s_nop 1
	v_addc_co_u32_e32 v101, vcc, 0, v113, vcc
	v_add_co_u32_e32 v102, vcc, 0x16000, v100
	s_nop 1
	v_addc_co_u32_e32 v103, vcc, 0, v101, vcc
	v_readlane_b32 s100, v252, 0
	v_readlane_b32 s101, v252, 1
	s_nop 3
	s_sub_u32 s100, s100, 0x170
	s_subb_u32 s101, s101, 0
	s_load_dwordx2 s[10:11], s[100:101], 0x158
	s_bfe_u32 s12, s98, 0x80008
	s_lshl_b32 s12, s12, 7
	s_lshr_b32 s13, s99, 1
	s_lshl_b32 s13, s13, 6
	s_add_u32 s12, s12, s13
	s_lshl_b32 s12, s12, 12
	s_bfe_u32 s13, s98, 0x80010
	s_lshl_b32 s13, s13, 9
	s_add_u32 s12, s12, s13
	s_and_b32 s13, s99, 1
	s_lshl_b32 s13, s13, 8
	s_add_u32 s12, s12, s13
	s_lshl_b32 s13, s3, 22
	s_add_u32 s12, s12, s13
	s_waitcnt lgkmcnt(0)
	s_add_u32 s10, s10, s12
	s_addc_u32 s11, s11, 0
	v_bfe_u32 v116, v152, 5, 1
	v_lshlrev_b32_e32 v116, 14, v116
	v_and_b32_e32 v117, 31, v152
	v_lshl_add_u32 v116, v117, 2, v116
	v_add_u32_e32 v117, 0x1000, v116
	v_add_u32_e32 v118, 0x2000, v116
	v_add_u32_e32 v119, 0x3000, v116
	s_and_b32 m0, s98, 1
	s_mul_i32 m0, m0, 0x12000
	s_lshl_b32 s99, s99, 11
	s_add_u32 s98, m0, s99
	s_add_u32 s98, s98, 16
	s_add_u32 m0, s98, 0x0
	s_nop 0
	global_load_lds_dwordx4 v[96:97], off
	s_add_u32 m0, s98, 0x400
	s_nop 0
	global_load_lds_dwordx4 v[98:99], off
	s_add_u32 m0, s98, 0x2000
	s_nop 0
	global_load_lds_dwordx4 v[100:101], off
	s_add_u32 m0, s98, 0x2400
	s_nop 0
	global_load_lds_dwordx4 v[102:103], off
	v_lshl_add_u64 v[96:97], v[96:97], 0, 64
	v_lshl_add_u64 v[98:99], v[98:99], 0, 64
	v_lshl_add_u64 v[100:101], v[100:101], 0, 64
	v_lshl_add_u64 v[102:103], v[102:103], 0, 64
	s_add_u32 m0, s98, 0x4000
	s_nop 0
	global_load_lds_dwordx4 v[96:97], off
	s_add_u32 m0, s98, 0x4400
	s_nop 0
	global_load_lds_dwordx4 v[98:99], off
	s_add_u32 m0, s98, 0x6000
	s_nop 0
	global_load_lds_dwordx4 v[100:101], off
	s_add_u32 m0, s98, 0x6400
	s_nop 0
	global_load_lds_dwordx4 v[102:103], off
	v_lshl_add_u64 v[96:97], v[96:97], 0, 64
	v_lshl_add_u64 v[98:99], v[98:99], 0, 64
	v_lshl_add_u64 v[100:101], v[100:101], 0, 64
	v_lshl_add_u64 v[102:103], v[102:103], 0, 64
	s_add_u32 m0, s98, 0x8000
	s_nop 0
	global_load_lds_dwordx4 v[96:97], off
	s_add_u32 m0, s98, 0x8400
	s_nop 0
	global_load_lds_dwordx4 v[98:99], off
	s_add_u32 m0, s98, 0xa000
	s_nop 0
	global_load_lds_dwordx4 v[100:101], off
	s_add_u32 m0, s98, 0xa400
	s_nop 0
	global_load_lds_dwordx4 v[102:103], off
	v_lshl_add_u64 v[96:97], v[96:97], 0, 64
	v_lshl_add_u64 v[98:99], v[98:99], 0, 64
	v_lshl_add_u64 v[100:101], v[100:101], 0, 64
	v_lshl_add_u64 v[102:103], v[102:103], 0, 64
	s_waitcnt vmcnt(8)
	s_barrier
; #define LGKM0_BAR asm volatile("s_waitcnt lgkmcnt(0)\n\ts_barrier" ::: "memory");
; __device__ __forceinline__ void gemm256_tile(const u16* Ab, int lda, const u16* Bb, int ldb, int K, char* smem,
;                                              f32x16 (&acc)[2][4]) {
;     ...
;   DMA_STAGE(0)
;   if (nks > 1) DMA_STAGE(1)
;   if (nks > 2) DMA_STAGE(2)
;   if (nks > 3) DMA_STAGE(3)
;   if (nks > 3)      asm volatile("s_waitcnt vmcnt(12)\n\ts_barrier" ::: "memory");
;   else if (nks > 2) asm volatile("s_waitcnt vmcnt(8)\n\ts_barrier" ::: "memory");
;   else if (nks > 1) asm volatile("s_waitcnt vmcnt(4)\n\ts_barrier" ::: "memory");
;   else              asm volatile("s_waitcnt vmcnt(0)\n\ts_barrier" ::: "memory");
;   bf16x8 afA[2], bfA[4], afB[2], bfB[4];
;   if (!h1) {
;     G_FRAGS(afA, bfA, 0, fo0)
;     LGKM0_BAR
;     for (int s = 0; s < nks; ++s) {
;       const int q = s & 3;
;       G_MMA(afA, bfA)
;       __builtin_amdgcn_sched_barrier(0);
;       LGKM0_BAR
;       G_FRAGS(afB, bfB, q, fo1)
;       __builtin_amdgcn_sched_barrier(0);
;       LGKM0_BAR
;       G_MMA(afB, bfB)
;       __builtin_amdgcn_sched_barrier(0);
;       G_WAIT_BAR(s)
;       if (s + 4 < nks) DMA_STAGE(s + 4)
;       if (s + 1 < nks) G_FRAGS(afA, bfA, (s + 1) & 3, fo0)
;       __builtin_amdgcn_sched_barrier(0);
;       LGKM0_BAR
;     }
	ds_read_b128 v[64:67], v104 offset:0
	ds_read_b128 v[68:71], v104 offset:2048
	ds_read_b128 v[72:75], v106 offset:0
	ds_read_b128 v[76:79], v106 offset:2048
	s_add_u32 m0, s98, 0xc000
	s_nop 0
	global_load_lds_dwordx4 v[96:97], off
	s_add_u32 m0, s98, 0xc400
	s_nop 0
	global_load_lds_dwordx4 v[98:99], off
	s_add_u32 m0, s98, 0xe000
	s_nop 0
	global_load_lds_dwordx4 v[100:101], off
	s_add_u32 m0, s98, 0xe400
	s_nop 0
	global_load_lds_dwordx4 v[102:103], off
	v_lshl_add_u64 v[96:97], v[96:97], 0, 64
	v_lshl_add_u64 v[98:99], v[98:99], 0, 64
	v_lshl_add_u64 v[100:101], v[100:101], 0, 64
	v_lshl_add_u64 v[102:103], v[102:103], 0, 64
	s_waitcnt lgkmcnt(0)
	v_mfma_f32_32x32x16_bf16 v[48:63], v[64:67], v[72:75], 0
	ds_read_b128 v[80:83], v105 offset:0
	v_mfma_f32_32x32x16_bf16 v[32:47], v[64:67], v[76:79], 0
	ds_read_b128 v[84:87], v105 offset:2048
	v_mfma_f32_32x32x16_bf16 v[16:31], v[68:71], v[72:75], 0
	ds_read_b128 v[88:91], v107 offset:0
	v_mfma_f32_32x32x16_bf16 v[0:15], v[68:71], v[76:79], 0
	ds_read_b128 v[92:95], v107 offset:2048
	s_waitcnt vmcnt(8)
	s_waitcnt lgkmcnt(0)
	s_barrier
	ds_read_b128 v[64:67], v104 offset:16384
	ds_read_b128 v[68:71], v104 offset:18432
	ds_read_b128 v[72:75], v106 offset:16384
	ds_read_b128 v[76:79], v106 offset:18432
	s_add_u32 m0, s98, 0x0
	v_mfma_f32_32x32x16_bf16 v[48:63], v[80:83], v[88:91], v[48:63]
	global_load_lds_dwordx4 v[96:97], off
	s_add_u32 m0, s98, 0x400
	v_mfma_f32_32x32x16_bf16 v[32:47], v[80:83], v[92:95], v[32:47]
	global_load_lds_dwordx4 v[98:99], off
	s_add_u32 m0, s98, 0x2000
	v_mfma_f32_32x32x16_bf16 v[16:31], v[84:87], v[88:91], v[16:31]
	global_load_lds_dwordx4 v[100:101], off
	s_add_u32 m0, s98, 0x2400
	v_mfma_f32_32x32x16_bf16 v[0:15], v[84:87], v[92:95], v[0:15]
	global_load_lds_dwordx4 v[102:103], off
	v_lshl_add_u64 v[96:97], v[96:97], 0, 64
	v_lshl_add_u64 v[98:99], v[98:99], 0, 64
	v_lshl_add_u64 v[100:101], v[100:101], 0, 64
	v_lshl_add_u64 v[102:103], v[102:103], 0, 64
	s_waitcnt lgkmcnt(0)
	v_mfma_f32_32x32x16_bf16 v[48:63], v[64:67], v[72:75], v[48:63]
	ds_read_b128 v[80:83], v105 offset:16384
	v_mfma_f32_32x32x16_bf16 v[32:47], v[64:67], v[76:79], v[32:47]
	ds_read_b128 v[84:87], v105 offset:18432
	v_mfma_f32_32x32x16_bf16 v[16:31], v[68:71], v[72:75], v[16:31]
	ds_read_b128 v[88:91], v107 offset:16384
	v_mfma_f32_32x32x16_bf16 v[0:15], v[68:71], v[76:79], v[0:15]
	ds_read_b128 v[92:95], v107 offset:18432
	s_waitcnt vmcnt(8)
	s_waitcnt lgkmcnt(0)
	s_barrier
	ds_read_b128 v[64:67], v104 offset:32768
	ds_read_b128 v[68:71], v104 offset:34816
	ds_read_b128 v[72:75], v106 offset:32768
	ds_read_b128 v[76:79], v106 offset:34816
	s_add_u32 m0, s98, 0x4000
	v_mfma_f32_32x32x16_bf16 v[48:63], v[80:83], v[88:91], v[48:63]
	global_load_lds_dwordx4 v[96:97], off
	s_add_u32 m0, s98, 0x4400
	v_mfma_f32_32x32x16_bf16 v[32:47], v[80:83], v[92:95], v[32:47]
	global_load_lds_dwordx4 v[98:99], off
	s_add_u32 m0, s98, 0x6000
	v_mfma_f32_32x32x16_bf16 v[16:31], v[84:87], v[88:91], v[16:31]
	global_load_lds_dwordx4 v[100:101], off
	s_add_u32 m0, s98, 0x6400
	v_mfma_f32_32x32x16_bf16 v[0:15], v[84:87], v[92:95], v[0:15]
	global_load_lds_dwordx4 v[102:103], off
	v_lshl_add_u64 v[96:97], v[96:97], 0, 64
	v_lshl_add_u64 v[98:99], v[98:99], 0, 64
	v_lshl_add_u64 v[100:101], v[100:101], 0, 64
	v_lshl_add_u64 v[102:103], v[102:103], 0, 64
	s_waitcnt lgkmcnt(0)
	v_mfma_f32_32x32x16_bf16 v[48:63], v[64:67], v[72:75], v[48:63]
	ds_read_b128 v[80:83], v105 offset:32768
	v_mfma_f32_32x32x16_bf16 v[32:47], v[64:67], v[76:79], v[32:47]
	ds_read_b128 v[84:87], v105 offset:34816
	v_mfma_f32_32x32x16_bf16 v[16:31], v[68:71], v[72:75], v[16:31]
	ds_read_b128 v[88:91], v107 offset:32768
	v_mfma_f32_32x32x16_bf16 v[0:15], v[68:71], v[76:79], v[0:15]
	ds_read_b128 v[92:95], v107 offset:34816
	s_waitcnt vmcnt(8)
	s_waitcnt lgkmcnt(0)
	s_barrier
	ds_read_b128 v[64:67], v104 offset:49152
	ds_read_b128 v[68:71], v104 offset:51200
	ds_read_b128 v[72:75], v106 offset:49152
	ds_read_b128 v[76:79], v106 offset:51200
	s_add_u32 m0, s98, 0x8000
	v_mfma_f32_32x32x16_bf16 v[48:63], v[80:83], v[88:91], v[48:63]
	global_load_lds_dwordx4 v[96:97], off
	s_add_u32 m0, s98, 0x8400
	v_mfma_f32_32x32x16_bf16 v[32:47], v[80:83], v[92:95], v[32:47]
	global_load_lds_dwordx4 v[98:99], off
	s_add_u32 m0, s98, 0xa000
	v_mfma_f32_32x32x16_bf16 v[16:31], v[84:87], v[88:91], v[16:31]
	global_load_lds_dwordx4 v[100:101], off
	s_add_u32 m0, s98, 0xa400
	v_mfma_f32_32x32x16_bf16 v[0:15], v[84:87], v[92:95], v[0:15]
	global_load_lds_dwordx4 v[102:103], off
	v_lshl_add_u64 v[96:97], v[96:97], 0, 64
	v_lshl_add_u64 v[98:99], v[98:99], 0, 64
	v_lshl_add_u64 v[100:101], v[100:101], 0, 64
	v_lshl_add_u64 v[102:103], v[102:103], 0, 64
	s_waitcnt lgkmcnt(0)
	v_mfma_f32_32x32x16_bf16 v[48:63], v[64:67], v[72:75], v[48:63]
	ds_read_b128 v[80:83], v105 offset:49152
	v_mfma_f32_32x32x16_bf16 v[32:47], v[64:67], v[76:79], v[32:47]
	ds_read_b128 v[84:87], v105 offset:51200
	v_mfma_f32_32x32x16_bf16 v[16:31], v[68:71], v[72:75], v[16:31]
	ds_read_b128 v[88:91], v107 offset:49152
	v_mfma_f32_32x32x16_bf16 v[0:15], v[68:71], v[76:79], v[0:15]
	ds_read_b128 v[92:95], v107 offset:51200
	s_waitcnt vmcnt(8)
	s_waitcnt lgkmcnt(0)
	s_barrier
; #define LGKM0_BAR asm volatile("s_waitcnt lgkmcnt(0)\n\ts_barrier" ::: "memory");
; __device__ __forceinline__ void gemm256_tile(const u16* Ab, int lda, const u16* Bb, int ldb, int K, char* smem,
;                                              f32x16 (&acc)[2][4]) {
;     ...
;     for (int s = 0; s < nks; ++s) {
;       const int q = s & 3;
;       G_MMA(afA, bfA)
;       __builtin_amdgcn_sched_barrier(0);
;       LGKM0_BAR
;       G_FRAGS(afB, bfB, q, fo1)
;       __builtin_amdgcn_sched_barrier(0);
;       LGKM0_BAR
;       G_MMA(afB, bfB)
;       __builtin_amdgcn_sched_barrier(0);
;       G_WAIT_BAR(s)
;       if (s + 4 < nks) DMA_STAGE(s + 4)
;       if (s + 1 < nks) G_FRAGS(afA, bfA, (s + 1) & 3, fo0)
;       __builtin_amdgcn_sched_barrier(0);
;       LGKM0_BAR
;     }
	ds_read_b128 v[64:67], v104 offset:0
	ds_read_b128 v[68:71], v104 offset:2048
	ds_read_b128 v[72:75], v106 offset:0
	ds_read_b128 v[76:79], v106 offset:2048
	s_add_u32 m0, s98, 0xc000
	v_mfma_f32_32x32x16_bf16 v[48:63], v[80:83], v[88:91], v[48:63]
	global_load_lds_dwordx4 v[96:97], off
	s_add_u32 m0, s98, 0xc400
	v_mfma_f32_32x32x16_bf16 v[32:47], v[80:83], v[92:95], v[32:47]
	global_load_lds_dwordx4 v[98:99], off
	s_add_u32 m0, s98, 0xe000
	v_mfma_f32_32x32x16_bf16 v[16:31], v[84:87], v[88:91], v[16:31]
	global_load_lds_dwordx4 v[100:101], off
	s_add_u32 m0, s98, 0xe400
	v_mfma_f32_32x32x16_bf16 v[0:15], v[84:87], v[92:95], v[0:15]
	global_load_lds_dwordx4 v[102:103], off
	v_lshl_add_u64 v[96:97], v[96:97], 0, 64
	v_lshl_add_u64 v[98:99], v[98:99], 0, 64
	v_lshl_add_u64 v[100:101], v[100:101], 0, 64
	v_lshl_add_u64 v[102:103], v[102:103], 0, 64
	s_waitcnt lgkmcnt(0)
	v_mfma_f32_32x32x16_bf16 v[48:63], v[64:67], v[72:75], v[48:63]
	ds_read_b128 v[80:83], v105 offset:0
	v_mfma_f32_32x32x16_bf16 v[32:47], v[64:67], v[76:79], v[32:47]
	ds_read_b128 v[84:87], v105 offset:2048
	v_mfma_f32_32x32x16_bf16 v[16:31], v[68:71], v[72:75], v[16:31]
	ds_read_b128 v[88:91], v107 offset:0
	v_mfma_f32_32x32x16_bf16 v[0:15], v[68:71], v[76:79], v[0:15]
	ds_read_b128 v[92:95], v107 offset:2048
	s_waitcnt vmcnt(8)
	s_waitcnt lgkmcnt(0)
	s_barrier
	ds_read_b128 v[64:67], v104 offset:16384
	ds_read_b128 v[68:71], v104 offset:18432
	ds_read_b128 v[72:75], v106 offset:16384
	ds_read_b128 v[76:79], v106 offset:18432
	s_add_u32 m0, s98, 0x0
	v_mfma_f32_32x32x16_bf16 v[48:63], v[80:83], v[88:91], v[48:63]
	global_load_lds_dwordx4 v[96:97], off
	s_add_u32 m0, s98, 0x400
	v_mfma_f32_32x32x16_bf16 v[32:47], v[80:83], v[92:95], v[32:47]
	global_load_lds_dwordx4 v[98:99], off
	s_add_u32 m0, s98, 0x2000
	v_mfma_f32_32x32x16_bf16 v[16:31], v[84:87], v[88:91], v[16:31]
	global_load_lds_dwordx4 v[100:101], off
	s_add_u32 m0, s98, 0x2400
	v_mfma_f32_32x32x16_bf16 v[0:15], v[84:87], v[92:95], v[0:15]
	global_load_lds_dwordx4 v[102:103], off
	v_lshl_add_u64 v[96:97], v[96:97], 0, 64
	v_lshl_add_u64 v[98:99], v[98:99], 0, 64
	v_lshl_add_u64 v[100:101], v[100:101], 0, 64
	v_lshl_add_u64 v[102:103], v[102:103], 0, 64
	s_waitcnt lgkmcnt(0)
	v_mfma_f32_32x32x16_bf16 v[48:63], v[64:67], v[72:75], v[48:63]
	ds_read_b128 v[80:83], v105 offset:16384
	v_mfma_f32_32x32x16_bf16 v[32:47], v[64:67], v[76:79], v[32:47]
	ds_read_b128 v[84:87], v105 offset:18432
	v_mfma_f32_32x32x16_bf16 v[16:31], v[68:71], v[72:75], v[16:31]
	ds_read_b128 v[88:91], v107 offset:16384
	v_mfma_f32_32x32x16_bf16 v[0:15], v[68:71], v[76:79], v[0:15]
	ds_read_b128 v[92:95], v107 offset:18432
	s_waitcnt vmcnt(8)
	s_waitcnt lgkmcnt(0)
	s_barrier
	ds_read_b128 v[64:67], v104 offset:32768
	ds_read_b128 v[68:71], v104 offset:34816
	ds_read_b128 v[72:75], v106 offset:32768
	ds_read_b128 v[76:79], v106 offset:34816
	s_add_u32 m0, s98, 0x4000
	v_mfma_f32_32x32x16_bf16 v[48:63], v[80:83], v[88:91], v[48:63]
	global_load_lds_dwordx4 v[96:97], off
	s_add_u32 m0, s98, 0x4400
	v_mfma_f32_32x32x16_bf16 v[32:47], v[80:83], v[92:95], v[32:47]
	global_load_lds_dwordx4 v[98:99], off
	s_add_u32 m0, s98, 0x6000
	v_mfma_f32_32x32x16_bf16 v[16:31], v[84:87], v[88:91], v[16:31]
	global_load_lds_dwordx4 v[100:101], off
	s_add_u32 m0, s98, 0x6400
	v_mfma_f32_32x32x16_bf16 v[0:15], v[84:87], v[92:95], v[0:15]
	global_load_lds_dwordx4 v[102:103], off
	v_lshl_add_u64 v[96:97], v[96:97], 0, 64
	v_lshl_add_u64 v[98:99], v[98:99], 0, 64
	v_lshl_add_u64 v[100:101], v[100:101], 0, 64
	v_lshl_add_u64 v[102:103], v[102:103], 0, 64
	s_waitcnt lgkmcnt(0)
	v_mfma_f32_32x32x16_bf16 v[48:63], v[64:67], v[72:75], v[48:63]
	ds_read_b128 v[80:83], v105 offset:32768
	v_mfma_f32_32x32x16_bf16 v[32:47], v[64:67], v[76:79], v[32:47]
	ds_read_b128 v[84:87], v105 offset:34816
	v_mfma_f32_32x32x16_bf16 v[16:31], v[68:71], v[72:75], v[16:31]
	ds_read_b128 v[88:91], v107 offset:32768
	v_mfma_f32_32x32x16_bf16 v[0:15], v[68:71], v[76:79], v[0:15]
	ds_read_b128 v[92:95], v107 offset:34816
	s_waitcnt vmcnt(8)
	s_waitcnt lgkmcnt(0)
	s_barrier
	ds_read_b128 v[64:67], v104 offset:49152
	ds_read_b128 v[68:71], v104 offset:51200
	ds_read_b128 v[72:75], v106 offset:49152
	ds_read_b128 v[76:79], v106 offset:51200
	s_add_u32 m0, s98, 0x8000
	v_mfma_f32_32x32x16_bf16 v[48:63], v[80:83], v[88:91], v[48:63]
	global_load_lds_dwordx4 v[96:97], off
	s_add_u32 m0, s98, 0x8400
	v_mfma_f32_32x32x16_bf16 v[32:47], v[80:83], v[92:95], v[32:47]
	global_load_lds_dwordx4 v[98:99], off
	s_add_u32 m0, s98, 0xa000
	v_mfma_f32_32x32x16_bf16 v[16:31], v[84:87], v[88:91], v[16:31]
	global_load_lds_dwordx4 v[100:101], off
	s_add_u32 m0, s98, 0xa400
	v_mfma_f32_32x32x16_bf16 v[0:15], v[84:87], v[92:95], v[0:15]
	global_load_lds_dwordx4 v[102:103], off
	v_lshl_add_u64 v[96:97], v[96:97], 0, 64
	v_lshl_add_u64 v[98:99], v[98:99], 0, 64
	v_lshl_add_u64 v[100:101], v[100:101], 0, 64
	v_lshl_add_u64 v[102:103], v[102:103], 0, 64
	s_waitcnt lgkmcnt(0)
	v_mfma_f32_32x32x16_bf16 v[48:63], v[64:67], v[72:75], v[48:63]
	ds_read_b128 v[80:83], v105 offset:49152
	v_mfma_f32_32x32x16_bf16 v[32:47], v[64:67], v[76:79], v[32:47]
	ds_read_b128 v[84:87], v105 offset:51200
	v_mfma_f32_32x32x16_bf16 v[16:31], v[68:71], v[72:75], v[16:31]
	ds_read_b128 v[88:91], v107 offset:49152
	v_mfma_f32_32x32x16_bf16 v[0:15], v[68:71], v[76:79], v[0:15]
	ds_read_b128 v[92:95], v107 offset:51200
	s_waitcnt vmcnt(8)
	s_waitcnt lgkmcnt(0)
	s_barrier
; #define LGKM0_BAR asm volatile("s_waitcnt lgkmcnt(0)\n\ts_barrier" ::: "memory");
; __device__ __forceinline__ void gemm256_tile(const u16* Ab, int lda, const u16* Bb, int ldb, int K, char* smem,
;                                              f32x16 (&acc)[2][4]) {
;     ...
;     for (int s = 0; s < nks; ++s) {
;       const int q = s & 3;
;       G_MMA(afA, bfA)
;       __builtin_amdgcn_sched_barrier(0);
;       LGKM0_BAR
;       G_FRAGS(afB, bfB, q, fo1)
;       __builtin_amdgcn_sched_barrier(0);
;       LGKM0_BAR
;       G_MMA(afB, bfB)
;       __builtin_amdgcn_sched_barrier(0);
;       G_WAIT_BAR(s)
;       if (s + 4 < nks) DMA_STAGE(s + 4)
;       if (s + 1 < nks) G_FRAGS(afA, bfA, (s + 1) & 3, fo0)
;       __builtin_amdgcn_sched_barrier(0);
;       LGKM0_BAR
;     }
; __device__ __forceinline__ void gemm_nt_phase(const u16* A, int lda, const u16* Bt, int ldb, u16* C, int ldc,
;                               int Mt, int Nt, int K, int qcols, float qscale, u16* smem,
;                               u16* vtx = nullptr, u16* vtc = nullptr, u16* smv = nullptr) {
;     ...
;       u16* Cb = C + (long)(N_X + ms * 128) * ldc + ns * 128;
;       if (vtc != nullptr && ns >= 16) {
;         u16* Vb = vtc + (long)(ms >> 1) * 1024 * 256 + (long)(ns - 16) * 128 * 256 + (ms & 1) * 128;
;         ACC_FOREACH({ Vb[(unsigned)(col * 256 + row)] = f2bf(v); })
;       } else {
;         ACC_FOREACH({ Cb[(unsigned)(row * ldc + col)] = f2bf(v); })
	ds_read_b128 v[64:67], v104 offset:0
	ds_read_b128 v[68:71], v104 offset:2048
	ds_read_b128 v[72:75], v106 offset:0
	ds_read_b128 v[76:79], v106 offset:2048
	v_mfma_f32_32x32x16_bf16 v[48:63], v[80:83], v[88:91], v[48:63]
	v_mfma_f32_32x32x16_bf16 v[32:47], v[80:83], v[92:95], v[32:47]
	v_mfma_f32_32x32x16_bf16 v[16:31], v[84:87], v[88:91], v[16:31]
	v_mfma_f32_32x32x16_bf16 v[0:15], v[84:87], v[92:95], v[0:15]
	s_waitcnt lgkmcnt(0)
	v_mfma_f32_32x32x16_bf16 v[48:63], v[64:67], v[72:75], v[48:63]
	ds_read_b128 v[80:83], v105 offset:0
	v_mfma_f32_32x32x16_bf16 v[32:47], v[64:67], v[76:79], v[32:47]
	ds_read_b128 v[84:87], v105 offset:2048
	v_mfma_f32_32x32x16_bf16 v[16:31], v[68:71], v[72:75], v[16:31]
	ds_read_b128 v[88:91], v107 offset:0
	v_mfma_f32_32x32x16_bf16 v[0:15], v[68:71], v[76:79], v[0:15]
	ds_read_b128 v[92:95], v107 offset:2048
	s_waitcnt vmcnt(4)
	s_waitcnt lgkmcnt(0)
	s_barrier
	ds_read_b128 v[64:67], v104 offset:16384
	ds_read_b128 v[68:71], v104 offset:18432
	ds_read_b128 v[72:75], v106 offset:16384
	ds_read_b128 v[76:79], v106 offset:18432
	v_mfma_f32_32x32x16_bf16 v[48:63], v[80:83], v[88:91], v[48:63]
	v_mfma_f32_32x32x16_bf16 v[32:47], v[80:83], v[92:95], v[32:47]
	v_mfma_f32_32x32x16_bf16 v[16:31], v[84:87], v[88:91], v[16:31]
	v_mfma_f32_32x32x16_bf16 v[0:15], v[84:87], v[92:95], v[0:15]
	s_waitcnt lgkmcnt(0)
	v_mfma_f32_32x32x16_bf16 v[48:63], v[64:67], v[72:75], v[48:63]
	ds_read_b128 v[80:83], v105 offset:16384
	v_mfma_f32_32x32x16_bf16 v[32:47], v[64:67], v[76:79], v[32:47]
	ds_read_b128 v[84:87], v105 offset:18432
	v_mfma_f32_32x32x16_bf16 v[16:31], v[68:71], v[72:75], v[16:31]
	ds_read_b128 v[88:91], v107 offset:16384
	v_mfma_f32_32x32x16_bf16 v[0:15], v[68:71], v[76:79], v[0:15]
	ds_read_b128 v[92:95], v107 offset:18432
	s_waitcnt vmcnt(0)
	s_waitcnt lgkmcnt(0)
	s_barrier
	ds_read_b128 v[64:67], v104 offset:32768
	ds_read_b128 v[68:71], v104 offset:34816
	ds_read_b128 v[72:75], v106 offset:32768
	ds_read_b128 v[76:79], v106 offset:34816
	v_mfma_f32_32x32x16_bf16 v[48:63], v[80:83], v[88:91], v[48:63]
	v_mfma_f32_32x32x16_bf16 v[32:47], v[80:83], v[92:95], v[32:47]
	v_mfma_f32_32x32x16_bf16 v[16:31], v[84:87], v[88:91], v[16:31]
	v_mfma_f32_32x32x16_bf16 v[0:15], v[84:87], v[92:95], v[0:15]
	s_waitcnt lgkmcnt(0)
	v_mfma_f32_32x32x16_bf16 v[48:63], v[64:67], v[72:75], v[48:63]
	ds_read_b128 v[80:83], v105 offset:32768
	v_mfma_f32_32x32x16_bf16 v[32:47], v[64:67], v[76:79], v[32:47]
	ds_read_b128 v[84:87], v105 offset:34816
	v_mfma_f32_32x32x16_bf16 v[16:31], v[68:71], v[72:75], v[16:31]
	ds_read_b128 v[88:91], v107 offset:32768
	v_mfma_f32_32x32x16_bf16 v[0:15], v[68:71], v[76:79], v[0:15]
	ds_read_b128 v[92:95], v107 offset:34816
	s_waitcnt lgkmcnt(0)
	v_mfma_f32_32x32x16_bf16 v[48:63], v[80:83], v[88:91], v[48:63]
	v_mfma_f32_32x32x16_bf16 v[32:47], v[80:83], v[92:95], v[32:47]
	v_mfma_f32_32x32x16_bf16 v[16:31], v[84:87], v[88:91], v[16:31]
	v_mfma_f32_32x32x16_bf16 v[0:15], v[84:87], v[92:95], v[0:15]
	s_nop 15
	global_store_dword v116, v48, s[10:11] offset:0
	global_store_dword v116, v32, s[10:11] offset:128
	global_store_dword v117, v49, s[10:11] offset:0
	global_store_dword v117, v33, s[10:11] offset:128
	global_store_dword v118, v50, s[10:11] offset:0
	global_store_dword v118, v34, s[10:11] offset:128
	global_store_dword v119, v51, s[10:11] offset:0
	global_store_dword v119, v35, s[10:11] offset:128
	s_add_u32 s10, s10, 0x8000
	s_addc_u32 s11, s11, 0
	global_store_dword v116, v52, s[10:11] offset:0
	global_store_dword v116, v36, s[10:11] offset:128
	global_store_dword v117, v53, s[10:11] offset:0
	global_store_dword v117, v37, s[10:11] offset:128
	global_store_dword v118, v54, s[10:11] offset:0
	global_store_dword v118, v38, s[10:11] offset:128
	global_store_dword v119, v55, s[10:11] offset:0
	global_store_dword v119, v39, s[10:11] offset:128
	s_add_u32 s10, s10, 0x8000
	s_addc_u32 s11, s11, 0
	global_store_dword v116, v56, s[10:11] offset:0
	global_store_dword v116, v40, s[10:11] offset:128
	global_store_dword v117, v57, s[10:11] offset:0
	global_store_dword v117, v41, s[10:11] offset:128
	global_store_dword v118, v58, s[10:11] offset:0
	global_store_dword v118, v42, s[10:11] offset:128
	global_store_dword v119, v59, s[10:11] offset:0
	global_store_dword v119, v43, s[10:11] offset:128
	s_add_u32 s10, s10, 0x8000
	s_addc_u32 s11, s11, 0
	global_store_dword v116, v60, s[10:11] offset:0
	global_store_dword v116, v44, s[10:11] offset:128
	global_store_dword v117, v61, s[10:11] offset:0
	global_store_dword v117, v45, s[10:11] offset:128
	global_store_dword v118, v62, s[10:11] offset:0
	global_store_dword v118, v46, s[10:11] offset:128
	global_store_dword v119, v63, s[10:11] offset:0
	global_store_dword v119, v47, s[10:11] offset:128
	s_add_u32 s10, s10, 0x8000
	s_addc_u32 s11, s11, 0
	global_store_dword v116, v16, s[10:11] offset:0
	global_store_dword v116, v0, s[10:11] offset:128
	global_store_dword v117, v17, s[10:11] offset:0
	global_store_dword v117, v1, s[10:11] offset:128
	global_store_dword v118, v18, s[10:11] offset:0
	global_store_dword v118, v2, s[10:11] offset:128
	global_store_dword v119, v19, s[10:11] offset:0
	global_store_dword v119, v3, s[10:11] offset:128
	s_add_u32 s10, s10, 0x8000
	s_addc_u32 s11, s11, 0
	global_store_dword v116, v20, s[10:11] offset:0
	global_store_dword v116, v4, s[10:11] offset:128
	global_store_dword v117, v21, s[10:11] offset:0
	global_store_dword v117, v5, s[10:11] offset:128
	global_store_dword v118, v22, s[10:11] offset:0
	global_store_dword v118, v6, s[10:11] offset:128
	global_store_dword v119, v23, s[10:11] offset:0
	global_store_dword v119, v7, s[10:11] offset:128
	s_add_u32 s10, s10, 0x8000
	s_addc_u32 s11, s11, 0
	global_store_dword v116, v24, s[10:11] offset:0
	global_store_dword v116, v8, s[10:11] offset:128
	global_store_dword v117, v25, s[10:11] offset:0
	global_store_dword v117, v9, s[10:11] offset:128
	global_store_dword v118, v26, s[10:11] offset:0
	global_store_dword v118, v10, s[10:11] offset:128
	global_store_dword v119, v27, s[10:11] offset:0
	global_store_dword v119, v11, s[10:11] offset:128
	s_add_u32 s10, s10, 0x8000
	s_addc_u32 s11, s11, 0
	global_store_dword v116, v28, s[10:11] offset:0
	global_store_dword v116, v12, s[10:11] offset:128
	global_store_dword v117, v29, s[10:11] offset:0
	global_store_dword v117, v13, s[10:11] offset:128
	global_store_dword v118, v30, s[10:11] offset:0
	global_store_dword v118, v14, s[10:11] offset:128
	global_store_dword v119, v31, s[10:11] offset:0
	global_store_dword v119, v15, s[10:11] offset:128
	s_mov_b64 s[0:1], 0

; __device__ __forceinline__ void row_phase(const Params& P, int glayer, int layer, int xsrc, bool hasY, int gate_idx, const float* gpost,
;                           int xdst, bool doH, const float* gpre, int sh_idx, int nrows) {
;   const int lane = threadIdx.x & 63, wid = threadIdx.x >> 6;
;   const int stride = gridDim.x * 8;
;   u16* resA = reinterpret_cast<u16*>(P.out);
;   for (int rb = blockIdx.x * 8 + wid; rb < nrows; rb += 4 * stride) {
;     uint4 xr[4][4];
;     uint2 yy[4][4];
; #pragma unroll
;     for (int u = 0; u < 4; ++u) {
;       const int R = rb + u * stride;
;       if (R < nrows) {
;         if (xsrc != 0 && R < N_X) {
;           const u16* xs_ = ((xsrc == 1) ? resA : P.zf) + (long)R * 1024;
; #pragma unroll
;           for (int i = 0; i < 4; ++i) {
;             const uint2 t2 = *reinterpret_cast<const uint2*>(xs_ + (i * 64 + lane) * 4);
;             xr[u][i].x = t2.x; xr[u][i].y = t2.y;
;           }
;         } else {
;           const float* xin_;
;           if (xsrc == 0) xin_ = R < N_X ? P.x + (long)R * 1024 : P.ctx + (long)(R - N_X) * 1024;
;           else           xin_ = P.xc + (long)(R - N_X) * 1024;
; #pragma unroll
;           for (int i = 0; i < 4; ++i) xr[u][i] = *reinterpret_cast<const uint4*>(xin_ + (i * 64 + lane) * 4);
;         }
;         if (hasY) {
;           const u16* y_ = P.hy + (long)R * 1024;
; #pragma unroll
;           for (int i = 0; i < 4; ++i) yy[u][i] = *reinterpret_cast<const uint2*>(y_ + (i * 64 + lane) * 4);
;         }
;       }
;     }
; #pragma unroll
;     for (int u = 0; u < 4; ++u) {
;       const int row = rb + u * stride;
;       if (row < nrows) {
;         const int mi = row < N_X ? (row >> 13) : 4;
;         const float* modp = P.mod + (long)(layer * 5 + mi) * 6144;
;         const float* modg = P.mod + (long)(glayer * 5 + mi) * 6144;
;         float4 xv[4];
;         if (xsrc != 0 && row < N_X) {
; #pragma unroll
;           for (int i = 0; i < 4; ++i) {
;             const uint4 raw = xr[u][i];
;             xv[i].x = bf2f((u16)(raw.x & 0xffff)); xv[i].y = bf2f((u16)(raw.x >> 16));
;             xv[i].z = bf2f((u16)(raw.y & 0xffff)); xv[i].w = bf2f((u16)(raw.y >> 16));
;           }
;         } else {
; #pragma unroll
;           for (int i = 0; i < 4; ++i) {
;             xv[i].x = __uint_as_float(xr[u][i].x); xv[i].y = __uint_as_float(xr[u][i].y);
.LBB0_1247:
	s_cmp_gt_i32 s34, 10
	s_cselect_b64 s[0:1], -1, 0
	s_cmp_lt_i32 s35, 11
	s_cselect_b64 s[4:5], -1, 0
	s_or_b64 s[0:1], s[0:1], s[4:5]
	s_and_b64 vcc, exec, s[0:1]
	s_cbranch_vccnz .LBB0_1357
	v_lshl_add_u32 v22, s2, 3, v204
	s_mov_b32 s3, 0x8400
	v_mov_b32_e32 v0, v153
	v_cmp_gt_i32_e32 vcc, s3, v22
	s_and_saveexec_b64 s[10:11], vcc
	s_cbranch_execz .LBB0_1303
	v_readlane_b32 s4, v252, 0
	v_readlane_b32 s5, v252, 1
	v_readfirstlane_b32 s19, v204
	s_nop 3
	s_sub_u32 s4, s4, 0x170
	s_subb_u32 s5, s5, 0
	s_load_dwordx2 s[12:13], s[4:5], 0xc8
	s_load_dwordx2 s[14:15], s[4:5], 0x140
	s_load_dwordx2 s[16:17], s[4:5], 0xc8
	s_load_dwordx2 s[20:21], s[4:5], 0x100
	s_lshl_b32 s98, s2, 3
	s_add_u32 s19, s98, s19
	v_and_b32_e32 v136, 63, v152
	v_lshlrev_b32_e32 v137, 3, v136
	v_lshlrev_b32_e32 v136, 4, v136
	s_waitcnt lgkmcnt(0)
	s_lshl_b32 vcc_lo, s19, 11
	s_add_u32 s100, s12, vcc_lo
	s_addc_u32 s101, s13, 0
	global_load_dwordx2 v[8:9], v137, s[100:101] offset:0
	global_load_dwordx2 v[10:11], v137, s[100:101] offset:512
	global_load_dwordx2 v[12:13], v137, s[100:101] offset:1024
	global_load_dwordx2 v[14:15], v137, s[100:101] offset:1536
	s_lshl_b32 vcc_lo, s19, 11
	s_add_u32 s100, s14, vcc_lo
	s_addc_u32 s101, s15, 0
	global_load_dwordx2 v[48:49], v137, s[100:101] offset:0
	global_load_dwordx2 v[50:51], v137, s[100:101] offset:512
	global_load_dwordx2 v[52:53], v137, s[100:101] offset:1024
	global_load_dwordx2 v[54:55], v137, s[100:101] offset:1536
	s_lshl_b32 vcc_lo, s19, 11
	s_add_u32 vcc_lo, vcc_lo, 0x400000
	s_add_u32 s100, s12, vcc_lo
	s_addc_u32 s101, s13, 0
	global_load_dwordx2 v[24:25], v137, s[100:101] offset:0
	global_load_dwordx2 v[26:27], v137, s[100:101] offset:512
	global_load_dwordx2 v[28:29], v137, s[100:101] offset:1024
	global_load_dwordx2 v[30:31], v137, s[100:101] offset:1536
	s_lshl_b32 vcc_lo, s19, 11
	s_add_u32 vcc_lo, vcc_lo, 0x400000
	s_add_u32 s100, s14, vcc_lo
	s_addc_u32 s101, s15, 0
	global_load_dwordx2 v[56:57], v137, s[100:101] offset:0
	global_load_dwordx2 v[58:59], v137, s[100:101] offset:512
	global_load_dwordx2 v[60:61], v137, s[100:101] offset:1024
	global_load_dwordx2 v[62:63], v137, s[100:101] offset:1536
	s_add_u32 s100, s20, 0x5000
	s_addc_u32 s101, s21, 0
	global_load_dwordx4 v[72:75], v136, s[100:101] offset:0
	global_load_dwordx4 v[76:79], v136, s[100:101] offset:1024
	global_load_dwordx4 v[80:83], v136, s[100:101] offset:2048
	global_load_dwordx4 v[84:87], v136, s[100:101] offset:3072
	s_load_dwordx2 s[98:99], s[4:5], 0x48
	s_waitcnt lgkmcnt(0)
	global_load_dwordx4 v[120:123], v136, s[98:99] offset:0
	global_load_dwordx4 v[124:127], v136, s[98:99] offset:1024
	global_load_dwordx4 v[128:131], v136, s[98:99] offset:2048
	global_load_dwordx4 v[132:135], v136, s[98:99] offset:3072
	s_add_u32 s100, s20, 0x1e000
	s_addc_u32 s101, s21, 0
	global_load_dwordx4 v[104:107], v136, s[100:101] offset:0
	global_load_dwordx4 v[108:111], v136, s[100:101] offset:1024
	global_load_dwordx4 v[112:115], v136, s[100:101] offset:2048
	global_load_dwordx4 v[116:119], v136, s[100:101] offset:3072
	s_add_u32 s100, s100, 0x1000
	s_addc_u32 s101, s101, 0
	global_load_dwordx4 v[32:35], v136, s[100:101] offset:0
	global_load_dwordx4 v[36:39], v136, s[100:101] offset:1024
	global_load_dwordx4 v[40:43], v136, s[100:101] offset:2048
	global_load_dwordx4 v[44:47], v136, s[100:101] offset:3072
	s_load_dwordx2 s[98:99], s[4:5], 0x30
	s_waitcnt lgkmcnt(0)
	s_add_u32 s98, s98, 0x1000
	s_addc_u32 s99, s99, 0
	global_load_dwordx4 v[88:91], v136, s[98:99] offset:0
	global_load_dwordx4 v[92:95], v136, s[98:99] offset:1024
	global_load_dwordx4 v[96:99], v136, s[98:99] offset:2048
	global_load_dwordx4 v[100:103], v136, s[98:99] offset:3072
	s_waitcnt vmcnt(0)
	v_mul_f32_e32 v72, v72, v120
	v_mul_f32_e32 v73, v73, v121
	v_mul_f32_e32 v74, v74, v122
	v_mul_f32_e32 v75, v75, v123
	v_mul_f32_e32 v76, v76, v124
	v_mul_f32_e32 v77, v77, v125
	v_mul_f32_e32 v78, v78, v126
	v_mul_f32_e32 v79, v79, v127
	v_mul_f32_e32 v80, v80, v128
	v_mul_f32_e32 v81, v81, v129
	v_mul_f32_e32 v82, v82, v130
	v_mul_f32_e32 v83, v83, v131
	v_mul_f32_e32 v84, v84, v132
	v_mul_f32_e32 v85, v85, v133
	v_mul_f32_e32 v86, v86, v134
	v_mul_f32_e32 v87, v87, v135
	v_fma_f32 v88, v88, v32, v88
	v_fma_f32 v89, v89, v33, v89
	v_fma_f32 v90, v90, v34, v90
	v_fma_f32 v91, v91, v35, v91
	v_fma_f32 v92, v92, v36, v92
	v_fma_f32 v93, v93, v37, v93
	v_fma_f32 v94, v94, v38, v94
	v_fma_f32 v95, v95, v39, v95
	v_fma_f32 v96, v96, v40, v96
	v_fma_f32 v97, v97, v41, v97
	v_fma_f32 v98, v98, v42, v98
	v_fma_f32 v99, v99, v43, v99
	v_fma_f32 v100, v100, v44, v100
	v_fma_f32 v101, v101, v45, v101
	v_fma_f32 v102, v102, v46, v102
	v_fma_f32 v103, v103, v47, v103
	s_lshl_b32 vcc_lo, s19, 11
	s_add_u32 vcc_lo, vcc_lo, 0x800000
	s_add_u32 s100, s12, vcc_lo
	s_addc_u32 s101, s13, 0
	global_load_dwordx2 v[40:41], v137, s[100:101] offset:0
	global_load_dwordx2 v[42:43], v137, s[100:101] offset:512
	global_load_dwordx2 v[44:45], v137, s[100:101] offset:1024
	global_load_dwordx2 v[46:47], v137, s[100:101] offset:1536
	s_lshl_b32 vcc_lo, s19, 11
	s_add_u32 vcc_lo, vcc_lo, 0x800000
	s_add_u32 s100, s14, vcc_lo
	s_addc_u32 s101, s15, 0
	global_load_dwordx2 v[64:65], v137, s[100:101] offset:0
	global_load_dwordx2 v[66:67], v137, s[100:101] offset:512
	global_load_dwordx2 v[68:69], v137, s[100:101] offset:1024
	global_load_dwordx2 v[70:71], v137, s[100:101] offset:1536
	v_lshlrev_b32_e32 v120, 16, v48
	v_and_b32_e32 v121, 0xffff0000, v48
	v_lshlrev_b32_e32 v122, 16, v49
	v_and_b32_e32 v123, 0xffff0000, v49
	v_lshlrev_b32_e32 v124, 16, v50
	v_and_b32_e32 v125, 0xffff0000, v50
	v_lshlrev_b32_e32 v126, 16, v51
; __device__ __forceinline__ void row_phase(const Params& P, int glayer, int layer, int xsrc, bool hasY, int gate_idx, const float* gpost,
;                           int xdst, bool doH, const float* gpre, int sh_idx, int nrows) {
;     ...
;         if (hasY) {
;           float4 yv[4];
;           float ss = 0.f;
; #pragma unroll
;           for (int i = 0; i < 4; ++i) {
;             const uint2 raw = yy[u][i];
;             yv[i].x = bf2f((u16)(raw.x & 0xffff)); yv[i].y = bf2f((u16)(raw.x >> 16));
;             yv[i].z = bf2f((u16)(raw.y & 0xffff)); yv[i].w = bf2f((u16)(raw.y >> 16));
;             ss += yv[i].x * yv[i].x + yv[i].y * yv[i].y + yv[i].z * yv[i].z + yv[i].w * yv[i].w;
;           }
;           ss = wave_sum(ss);
;           const float rstd = __builtin_amdgcn_rsqf(ss * (1.f / 1024.f) + EPSF);
; #pragma unroll
;           for (int i = 0; i < 4; ++i) {
;             const int col = (i * 64 + lane) * 4;
;             const float4 gt = *reinterpret_cast<const float4*>(modg + gate_idx * 1024 + col);
;             const float4 gp = *reinterpret_cast<const float4*>(gpost + col);
;             xv[i].x += gt.x * (yv[i].x * rstd * gp.x); xv[i].y += gt.y * (yv[i].y * rstd * gp.y);
;             xv[i].z += gt.z * (yv[i].z * rstd * gp.z); xv[i].w += gt.w * (yv[i].w * rstd * gp.w);
;           }
;         }
;         if (xdst == 3 || (xdst == 1 && row >= N_X)) {
;           float* xout = (xdst == 3) ? P.out + (long)row * 1024 : P.xc + (long)(row - N_X) * 1024;
; #pragma unroll
;           for (int i = 0; i < 4; ++i) *reinterpret_cast<float4*>(xout + (i * 64 + lane) * 4) = xv[i];
;         } else if (xdst != 0) {
;           u16* xo = ((xdst == 1) ? resA : P.zf) + (long)row * 1024;
; #pragma unroll
;           for (int i = 0; i < 4; ++i) {
;             const unsigned b0 = f2bf(xv[i].x), b1 = f2bf(xv[i].y), b2 = f2bf(xv[i].z), b3 = f2bf(xv[i].w);
;             *reinterpret_cast<uint2*>(xo + (i * 64 + lane) * 4) = make_uint2(b0 | (b1 << 16), b2 | (b3 << 16));
;           }
;         }
;         if (doH) {
;           float ss = 0.f;
; #pragma unroll
;           for (int i = 0; i < 4; ++i) ss += xv[i].x * xv[i].x + xv[i].y * xv[i].y + xv[i].z * xv[i].z + xv[i].w * xv[i].w;
;           ss = wave_sum(ss);
;           const float rstd = __builtin_amdgcn_rsqf(ss * (1.f / 1024.f) + EPSF);
;           u16* h = P.hy + (long)row * 1024;
; #pragma unroll
	v_and_b32_e32 v127, 0xffff0000, v51
	v_lshlrev_b32_e32 v128, 16, v52
	v_and_b32_e32 v129, 0xffff0000, v52
	v_lshlrev_b32_e32 v130, 16, v53
	v_and_b32_e32 v131, 0xffff0000, v53
	v_lshlrev_b32_e32 v132, 16, v54
	v_and_b32_e32 v133, 0xffff0000, v54
	v_lshlrev_b32_e32 v134, 16, v55
	v_and_b32_e32 v135, 0xffff0000, v55
	v_mul_f32_e32 v138, v120, v120
	v_mul_f32_e32 v149, v121, v121
	v_mul_f32_e32 v150, v122, v122
	v_mul_f32_e32 v154, v123, v123
	v_fma_f32 v138, v124, v124, v138
	v_fma_f32 v149, v125, v125, v149
	v_fma_f32 v150, v126, v126, v150
	v_fma_f32 v154, v127, v127, v154
	v_fma_f32 v138, v128, v128, v138
	v_fma_f32 v149, v129, v129, v149
	v_fma_f32 v150, v130, v130, v150
	v_fma_f32 v154, v131, v131, v154
	v_fma_f32 v138, v132, v132, v138
	v_fma_f32 v149, v133, v133, v149
	v_fma_f32 v150, v134, v134, v150
	v_fma_f32 v154, v135, v135, v154
	v_add_f32_e32 v138, v138, v149
	v_add_f32_e32 v150, v150, v154
	v_add_f32_e32 v138, v138, v150
	s_nop 1
	v_add_f32_dpp v138, v138, v138 quad_perm:[1,0,3,2] row_mask:0xf bank_mask:0xf
	s_nop 1
	v_add_f32_dpp v138, v138, v138 quad_perm:[2,3,0,1] row_mask:0xf bank_mask:0xf
	s_nop 1
	v_add_f32_dpp v138, v138, v138 row_half_mirror row_mask:0xf bank_mask:0xf
	s_nop 1
	v_add_f32_dpp v138, v138, v138 row_mirror row_mask:0xf bank_mask:0xf
	v_mov_b32_e32 v139, v138
	s_nop 1
	v_permlane16_swap_b32_e32 v138, v139
	v_add_f32_e32 v138, v138, v139
	v_mov_b32_e32 v139, v138
	s_nop 1
	v_permlane32_swap_b32_e32 v138, v139
	v_add_f32_e32 v138, v138, v139
	v_mul_f32_e32 v138, 0x3a800000, v138
	v_add_f32_e32 v138, 0x358637bd, v138
	v_rsq_f32_e32 v140, v138
	v_lshlrev_b32_e32 v0, 16, v8
	v_and_b32_e32 v1, 0xffff0000, v8
	v_lshlrev_b32_e32 v2, 16, v9
	v_and_b32_e32 v3, 0xffff0000, v9
	v_lshlrev_b32_e32 v4, 16, v10
	v_and_b32_e32 v5, 0xffff0000, v10
	v_lshlrev_b32_e32 v6, 16, v11
	v_and_b32_e32 v7, 0xffff0000, v11
	v_lshlrev_b32_e32 v8, 16, v12
	v_and_b32_e32 v9, 0xffff0000, v12
	v_lshlrev_b32_e32 v10, 16, v13
	v_and_b32_e32 v11, 0xffff0000, v13
	v_lshlrev_b32_e32 v12, 16, v14
	v_and_b32_e32 v13, 0xffff0000, v14
	v_lshlrev_b32_e32 v14, 16, v15
	v_and_b32_e32 v15, 0xffff0000, v15
	s_nop 0
	v_mul_f32_e32 v120, v120, v140
	v_mul_f32_e32 v121, v121, v140
	v_mul_f32_e32 v122, v122, v140
	v_mul_f32_e32 v123, v123, v140
	v_mul_f32_e32 v124, v124, v140
	v_mul_f32_e32 v125, v125, v140
	v_mul_f32_e32 v126, v126, v140
	v_mul_f32_e32 v127, v127, v140
	v_mul_f32_e32 v128, v128, v140
	v_mul_f32_e32 v129, v129, v140
	v_mul_f32_e32 v130, v130, v140
	v_mul_f32_e32 v131, v131, v140
	v_mul_f32_e32 v132, v132, v140
	v_mul_f32_e32 v133, v133, v140
	v_mul_f32_e32 v134, v134, v140
	v_mul_f32_e32 v135, v135, v140
	v_fma_f32 v0, v120, v72, v0
	v_fma_f32 v1, v121, v73, v1
	v_fma_f32 v2, v122, v74, v2
	v_fma_f32 v3, v123, v75, v3
	v_fma_f32 v4, v124, v76, v4
	v_fma_f32 v5, v125, v77, v5
	v_fma_f32 v6, v126, v78, v6
	v_fma_f32 v7, v127, v79, v7
	v_fma_f32 v8, v128, v80, v8
	v_fma_f32 v9, v129, v81, v9
	v_fma_f32 v10, v130, v82, v10
	v_fma_f32 v11, v131, v83, v11
	v_fma_f32 v12, v132, v84, v12
	v_fma_f32 v13, v133, v85, v13
	v_fma_f32 v14, v134, v86, v14
	v_fma_f32 v15, v135, v87, v15
	v_cvt_pk_bf16_f32 v156, v0, v1
	v_cvt_pk_bf16_f32 v157, v2, v3
	v_cvt_pk_bf16_f32 v158, v4, v5
	v_cvt_pk_bf16_f32 v159, v6, v7
	v_cvt_pk_bf16_f32 v160, v8, v9
	v_cvt_pk_bf16_f32 v161, v10, v11
	v_cvt_pk_bf16_f32 v162, v12, v13
	v_cvt_pk_bf16_f32 v163, v14, v15
	s_lshl_b32 vcc_lo, s19, 11
	s_add_u32 s100, s16, vcc_lo
	s_addc_u32 s101, s17, 0
	global_store_dwordx2 v137, v[156:157], s[100:101] offset:0
	global_store_dwordx2 v137, v[158:159], s[100:101] offset:512
	global_store_dwordx2 v137, v[160:161], s[100:101] offset:1024
	global_store_dwordx2 v137, v[162:163], s[100:101] offset:1536
	v_mul_f32_e32 v138, v0, v0
	v_mul_f32_e32 v149, v1, v1
	v_mul_f32_e32 v150, v2, v2
	v_mul_f32_e32 v154, v3, v3
	v_fma_f32 v138, v4, v4, v138
	v_fma_f32 v149, v5, v5, v149
	v_fma_f32 v150, v6, v6, v150
	v_fma_f32 v154, v7, v7, v154
	v_fma_f32 v138, v8, v8, v138
	v_fma_f32 v149, v9, v9, v149
	v_fma_f32 v150, v10, v10, v150
	v_fma_f32 v154, v11, v11, v154
	v_fma_f32 v138, v12, v12, v138
	v_fma_f32 v149, v13, v13, v149
	v_fma_f32 v150, v14, v14, v150
	v_fma_f32 v154, v15, v15, v154
	v_add_f32_e32 v138, v138, v149
	v_add_f32_e32 v150, v150, v154
	v_add_f32_e32 v138, v138, v150
	s_nop 1
	v_add_f32_dpp v138, v138, v138 quad_perm:[1,0,3,2] row_mask:0xf bank_mask:0xf
	s_nop 1
	v_add_f32_dpp v138, v138, v138 quad_perm:[2,3,0,1] row_mask:0xf bank_mask:0xf
	s_nop 1
	v_add_f32_dpp v138, v138, v138 row_half_mirror row_mask:0xf bank_mask:0xf
	s_nop 1
	v_add_f32_dpp v138, v138, v138 row_mirror row_mask:0xf bank_mask:0xf
	v_mov_b32_e32 v139, v138
	s_nop 1
	v_permlane16_swap_b32_e32 v138, v139
	v_add_f32_e32 v138, v138, v139
	v_mov_b32_e32 v139, v138
	s_nop 1
	v_permlane32_swap_b32_e32 v138, v139
	v_add_f32_e32 v138, v138, v139
	v_mul_f32_e32 v138, 0x3a800000, v138
	v_add_f32_e32 v138, 0x358637bd, v138
	v_rsq_f32_e32 v140, v138
	s_nop 0
	v_mul_f32_e32 v120, v0, v140
	v_mul_f32_e32 v121, v1, v140
	v_mul_f32_e32 v122, v2, v140
	v_mul_f32_e32 v123, v3, v140
	v_mul_f32_e32 v124, v4, v140
	v_mul_f32_e32 v125, v5, v140
	v_mul_f32_e32 v126, v6, v140
	v_mul_f32_e32 v127, v7, v140
	v_mul_f32_e32 v128, v8, v140
	v_mul_f32_e32 v129, v9, v140
	v_mul_f32_e32 v130, v10, v140
	v_mul_f32_e32 v131, v11, v140
	v_mul_f32_e32 v132, v12, v140
	v_mul_f32_e32 v133, v13, v140
	v_mul_f32_e32 v134, v14, v140
	v_mul_f32_e32 v135, v15, v140
	v_fma_f32 v120, v120, v88, v104
	v_fma_f32 v121, v121, v89, v105
	v_fma_f32 v122, v122, v90, v106
	v_fma_f32 v123, v123, v91, v107
	v_fma_f32 v124, v124, v92, v108
	v_fma_f32 v125, v125, v93, v109
; __device__ __forceinline__ void row_phase(const Params& P, int glayer, int layer, int xsrc, bool hasY, int gate_idx, const float* gpost,
;                           int xdst, bool doH, const float* gpre, int sh_idx, int nrows) {
;     ...
;         if (xdst == 3 || (xdst == 1 && row >= N_X)) {
;           float* xout = (xdst == 3) ? P.out + (long)row * 1024 : P.xc + (long)(row - N_X) * 1024;
; #pragma unroll
;           for (int i = 0; i < 4; ++i) *reinterpret_cast<float4*>(xout + (i * 64 + lane) * 4) = xv[i];
;         } else if (xdst != 0) {
;           u16* xo = ((xdst == 1) ? resA : P.zf) + (long)row * 1024;
; #pragma unroll
;           for (int i = 0; i < 4; ++i) {
;             const unsigned b0 = f2bf(xv[i].x), b1 = f2bf(xv[i].y), b2 = f2bf(xv[i].z), b3 = f2bf(xv[i].w);
;             *reinterpret_cast<uint2*>(xo + (i * 64 + lane) * 4) = make_uint2(b0 | (b1 << 16), b2 | (b3 << 16));
;           }
;         }
;         if (doH) {
;           float ss = 0.f;
; #pragma unroll
;           for (int i = 0; i < 4; ++i) ss += xv[i].x * xv[i].x + xv[i].y * xv[i].y + xv[i].z * xv[i].z + xv[i].w * xv[i].w;
;           ss = wave_sum(ss);
;           const float rstd = __builtin_amdgcn_rsqf(ss * (1.f / 1024.f) + EPSF);
;           u16* h = P.hy + (long)row * 1024;
; #pragma unroll
;           for (int i = 0; i < 4; ++i) {
;             const int col = (i * 64 + lane) * 4;
;             const float4 g = *reinterpret_cast<const float4*>(gpre + col);
;             const float4 sh = *reinterpret_cast<const float4*>(modp + sh_idx * 1024 + col);
;             const float4 sc = *reinterpret_cast<const float4*>(modp + (sh_idx + 1) * 1024 + col);
;             const unsigned h0 = f2bf(xv[i].x * rstd * g.x * (1.f + sc.x) + sh.x);
;             const unsigned h1 = f2bf(xv[i].y * rstd * g.y * (1.f + sc.y) + sh.y);
;             const unsigned h2 = f2bf(xv[i].z * rstd * g.z * (1.f + sc.z) + sh.z);
;             const unsigned h3 = f2bf(xv[i].w * rstd * g.w * (1.f + sc.w) + sh.w);
;             *reinterpret_cast<uint2*>(h + col) = make_uint2(h0 | (h1 << 16), h2 | (h3 << 16));
	v_fma_f32 v126, v126, v94, v110
	v_fma_f32 v127, v127, v95, v111
	v_fma_f32 v128, v128, v96, v112
	v_fma_f32 v129, v129, v97, v113
	v_fma_f32 v130, v130, v98, v114
	v_fma_f32 v131, v131, v99, v115
	v_fma_f32 v132, v132, v100, v116
	v_fma_f32 v133, v133, v101, v117
	v_fma_f32 v134, v134, v102, v118
	v_fma_f32 v135, v135, v103, v119
	v_cvt_pk_bf16_f32 v156, v120, v121
	v_cvt_pk_bf16_f32 v157, v122, v123
	v_cvt_pk_bf16_f32 v158, v124, v125
	v_cvt_pk_bf16_f32 v159, v126, v127
	v_cvt_pk_bf16_f32 v160, v128, v129
	v_cvt_pk_bf16_f32 v161, v130, v131
	v_cvt_pk_bf16_f32 v162, v132, v133
	v_cvt_pk_bf16_f32 v163, v134, v135
	s_lshl_b32 vcc_lo, s19, 11
	s_add_u32 s100, s14, vcc_lo
	s_addc_u32 s101, s15, 0
	global_store_dwordx2 v137, v[156:157], s[100:101] offset:0
	global_store_dwordx2 v137, v[158:159], s[100:101] offset:512
	global_store_dwordx2 v137, v[160:161], s[100:101] offset:1024
	global_store_dwordx2 v137, v[162:163], s[100:101] offset:1536
	s_lshl_b32 vcc_lo, s19, 11
	s_add_u32 vcc_lo, vcc_lo, 0xc00000
	s_add_u32 s100, s12, vcc_lo
	s_addc_u32 s101, s13, 0
	global_load_dwordx2 v[8:9], v137, s[100:101] offset:0
	global_load_dwordx2 v[10:11], v137, s[100:101] offset:512
	global_load_dwordx2 v[12:13], v137, s[100:101] offset:1024
	global_load_dwordx2 v[14:15], v137, s[100:101] offset:1536
	s_lshl_b32 vcc_lo, s19, 11
	s_add_u32 vcc_lo, vcc_lo, 0xc00000
	s_add_u32 s100, s14, vcc_lo
	s_addc_u32 s101, s15, 0
	global_load_dwordx2 v[48:49], v137, s[100:101] offset:0
	global_load_dwordx2 v[50:51], v137, s[100:101] offset:512
	global_load_dwordx2 v[52:53], v137, s[100:101] offset:1024
	global_load_dwordx2 v[54:55], v137, s[100:101] offset:1536
	v_lshlrev_b32_e32 v120, 16, v56
	v_and_b32_e32 v121, 0xffff0000, v56
	v_lshlrev_b32_e32 v122, 16, v57
	v_and_b32_e32 v123, 0xffff0000, v57
	v_lshlrev_b32_e32 v124, 16, v58
	v_and_b32_e32 v125, 0xffff0000, v58
	v_lshlrev_b32_e32 v126, 16, v59
	v_and_b32_e32 v127, 0xffff0000, v59
	v_lshlrev_b32_e32 v128, 16, v60
	v_and_b32_e32 v129, 0xffff0000, v60
	v_lshlrev_b32_e32 v130, 16, v61
	v_and_b32_e32 v131, 0xffff0000, v61
	v_lshlrev_b32_e32 v132, 16, v62
	v_and_b32_e32 v133, 0xffff0000, v62
	v_lshlrev_b32_e32 v134, 16, v63
	v_and_b32_e32 v135, 0xffff0000, v63
	v_mul_f32_e32 v138, v120, v120
	v_mul_f32_e32 v149, v121, v121
	v_mul_f32_e32 v150, v122, v122
	v_mul_f32_e32 v154, v123, v123
	v_fma_f32 v138, v124, v124, v138
	v_fma_f32 v149, v125, v125, v149
	v_fma_f32 v150, v126, v126, v150
	v_fma_f32 v154, v127, v127, v154
	v_fma_f32 v138, v128, v128, v138
	v_fma_f32 v149, v129, v129, v149
	v_fma_f32 v150, v130, v130, v150
	v_fma_f32 v154, v131, v131, v154
	v_fma_f32 v138, v132, v132, v138
	v_fma_f32 v149, v133, v133, v149
	v_fma_f32 v150, v134, v134, v150
	v_fma_f32 v154, v135, v135, v154
	v_add_f32_e32 v138, v138, v149
	v_add_f32_e32 v150, v150, v154
	v_add_f32_e32 v138, v138, v150
	s_nop 1
	v_add_f32_dpp v138, v138, v138 quad_perm:[1,0,3,2] row_mask:0xf bank_mask:0xf
	s_nop 1
	v_add_f32_dpp v138, v138, v138 quad_perm:[2,3,0,1] row_mask:0xf bank_mask:0xf
	s_nop 1
	v_add_f32_dpp v138, v138, v138 row_half_mirror row_mask:0xf bank_mask:0xf
	s_nop 1
	v_add_f32_dpp v138, v138, v138 row_mirror row_mask:0xf bank_mask:0xf
	v_mov_b32_e32 v139, v138
	s_nop 1
	v_permlane16_swap_b32_e32 v138, v139
	v_add_f32_e32 v138, v138, v139
	v_mov_b32_e32 v139, v138
	s_nop 1
	v_permlane32_swap_b32_e32 v138, v139
	v_add_f32_e32 v138, v138, v139
	v_mul_f32_e32 v138, 0x3a800000, v138
	v_add_f32_e32 v138, 0x358637bd, v138
	v_rsq_f32_e32 v140, v138
	v_lshlrev_b32_e32 v16, 16, v24
	v_and_b32_e32 v17, 0xffff0000, v24
	v_lshlrev_b32_e32 v18, 16, v25
	v_and_b32_e32 v19, 0xffff0000, v25
	v_lshlrev_b32_e32 v20, 16, v26
	v_and_b32_e32 v21, 0xffff0000, v26
	v_lshlrev_b32_e32 v22, 16, v27
	v_and_b32_e32 v23, 0xffff0000, v27
	v_lshlrev_b32_e32 v24, 16, v28
	v_and_b32_e32 v25, 0xffff0000, v28
	v_lshlrev_b32_e32 v26, 16, v29
	v_and_b32_e32 v27, 0xffff0000, v29
	v_lshlrev_b32_e32 v28, 16, v30
	v_and_b32_e32 v29, 0xffff0000, v30
	v_lshlrev_b32_e32 v30, 16, v31
	v_and_b32_e32 v31, 0xffff0000, v31
	s_nop 0
	v_mul_f32_e32 v120, v120, v140
	v_mul_f32_e32 v121, v121, v140
	v_mul_f32_e32 v122, v122, v140
	v_mul_f32_e32 v123, v123, v140
	v_mul_f32_e32 v124, v124, v140
	v_mul_f32_e32 v125, v125, v140
	v_mul_f32_e32 v126, v126, v140
	v_mul_f32_e32 v127, v127, v140
	v_mul_f32_e32 v128, v128, v140
	v_mul_f32_e32 v129, v129, v140
	v_mul_f32_e32 v130, v130, v140
	v_mul_f32_e32 v131, v131, v140
	v_mul_f32_e32 v132, v132, v140
	v_mul_f32_e32 v133, v133, v140
	v_mul_f32_e32 v134, v134, v140
	v_mul_f32_e32 v135, v135, v140
	v_fma_f32 v16, v120, v72, v16
	v_fma_f32 v17, v121, v73, v17
	v_fma_f32 v18, v122, v74, v18
	v_fma_f32 v19, v123, v75, v19
	v_fma_f32 v20, v124, v76, v20
	v_fma_f32 v21, v125, v77, v21
	v_fma_f32 v22, v126, v78, v22
	v_fma_f32 v23, v127, v79, v23
	v_fma_f32 v24, v128, v80, v24
	v_fma_f32 v25, v129, v81, v25
	v_fma_f32 v26, v130, v82, v26
	v_fma_f32 v27, v131, v83, v27
	v_fma_f32 v28, v132, v84, v28
	v_fma_f32 v29, v133, v85, v29
	v_fma_f32 v30, v134, v86, v30
	v_fma_f32 v31, v135, v87, v31
	v_cvt_pk_bf16_f32 v156, v16, v17
	v_cvt_pk_bf16_f32 v157, v18, v19
	v_cvt_pk_bf16_f32 v158, v20, v21
	v_cvt_pk_bf16_f32 v159, v22, v23
	v_cvt_pk_bf16_f32 v160, v24, v25
	v_cvt_pk_bf16_f32 v161, v26, v27
	v_cvt_pk_bf16_f32 v162, v28, v29
	v_cvt_pk_bf16_f32 v163, v30, v31
	s_lshl_b32 vcc_lo, s19, 11
	s_add_u32 vcc_lo, vcc_lo, 0x400000
	s_add_u32 s100, s16, vcc_lo
	s_addc_u32 s101, s17, 0
	global_store_dwordx2 v137, v[156:157], s[100:101] offset:0
	global_store_dwordx2 v137, v[158:159], s[100:101] offset:512
	global_store_dwordx2 v137, v[160:161], s[100:101] offset:1024
; __device__ __forceinline__ void row_phase(const Params& P, int glayer, int layer, int xsrc, bool hasY, int gate_idx, const float* gpost,
;                           int xdst, bool doH, const float* gpre, int sh_idx, int nrows) {
;     ...
;         if (xdst == 3 || (xdst == 1 && row >= N_X)) {
;           float* xout = (xdst == 3) ? P.out + (long)row * 1024 : P.xc + (long)(row - N_X) * 1024;
; #pragma unroll
;           for (int i = 0; i < 4; ++i) *reinterpret_cast<float4*>(xout + (i * 64 + lane) * 4) = xv[i];
;         } else if (xdst != 0) {
;           u16* xo = ((xdst == 1) ? resA : P.zf) + (long)row * 1024;
; #pragma unroll
;           for (int i = 0; i < 4; ++i) {
;             const unsigned b0 = f2bf(xv[i].x), b1 = f2bf(xv[i].y), b2 = f2bf(xv[i].z), b3 = f2bf(xv[i].w);
;             *reinterpret_cast<uint2*>(xo + (i * 64 + lane) * 4) = make_uint2(b0 | (b1 << 16), b2 | (b3 << 16));
;           }
;         }
;         if (doH) {
;           float ss = 0.f;
; #pragma unroll
;           for (int i = 0; i < 4; ++i) ss += xv[i].x * xv[i].x + xv[i].y * xv[i].y + xv[i].z * xv[i].z + xv[i].w * xv[i].w;
;           ss = wave_sum(ss);
;           const float rstd = __builtin_amdgcn_rsqf(ss * (1.f / 1024.f) + EPSF);
;           u16* h = P.hy + (long)row * 1024;
; #pragma unroll
;           for (int i = 0; i < 4; ++i) {
;             const int col = (i * 64 + lane) * 4;
;             const float4 g = *reinterpret_cast<const float4*>(gpre + col);
;             const float4 sh = *reinterpret_cast<const float4*>(modp + sh_idx * 1024 + col);
;             const float4 sc = *reinterpret_cast<const float4*>(modp + (sh_idx + 1) * 1024 + col);
;             const unsigned h0 = f2bf(xv[i].x * rstd * g.x * (1.f + sc.x) + sh.x);
;             const unsigned h1 = f2bf(xv[i].y * rstd * g.y * (1.f + sc.y) + sh.y);
;             const unsigned h2 = f2bf(xv[i].z * rstd * g.z * (1.f + sc.z) + sh.z);
;             const unsigned h3 = f2bf(xv[i].w * rstd * g.w * (1.f + sc.w) + sh.w);
;             *reinterpret_cast<uint2*>(h + col) = make_uint2(h0 | (h1 << 16), h2 | (h3 << 16));
	global_store_dwordx2 v137, v[162:163], s[100:101] offset:1536
	v_mul_f32_e32 v138, v16, v16
	v_mul_f32_e32 v149, v17, v17
	v_mul_f32_e32 v150, v18, v18
	v_mul_f32_e32 v154, v19, v19
	v_fma_f32 v138, v20, v20, v138
	v_fma_f32 v149, v21, v21, v149
	v_fma_f32 v150, v22, v22, v150
	v_fma_f32 v154, v23, v23, v154
	v_fma_f32 v138, v24, v24, v138
	v_fma_f32 v149, v25, v25, v149
	v_fma_f32 v150, v26, v26, v150
	v_fma_f32 v154, v27, v27, v154
	v_fma_f32 v138, v28, v28, v138
	v_fma_f32 v149, v29, v29, v149
	v_fma_f32 v150, v30, v30, v150
	v_fma_f32 v154, v31, v31, v154
	v_add_f32_e32 v138, v138, v149
	v_add_f32_e32 v150, v150, v154
	v_add_f32_e32 v138, v138, v150
	s_nop 1
	v_add_f32_dpp v138, v138, v138 quad_perm:[1,0,3,2] row_mask:0xf bank_mask:0xf
	s_nop 1
	v_add_f32_dpp v138, v138, v138 quad_perm:[2,3,0,1] row_mask:0xf bank_mask:0xf
	s_nop 1
	v_add_f32_dpp v138, v138, v138 row_half_mirror row_mask:0xf bank_mask:0xf
	s_nop 1
	v_add_f32_dpp v138, v138, v138 row_mirror row_mask:0xf bank_mask:0xf
	v_mov_b32_e32 v139, v138
	s_nop 1
	v_permlane16_swap_b32_e32 v138, v139
	v_add_f32_e32 v138, v138, v139
	v_mov_b32_e32 v139, v138
	s_nop 1
	v_permlane32_swap_b32_e32 v138, v139
	v_add_f32_e32 v138, v138, v139
	v_mul_f32_e32 v138, 0x3a800000, v138
	v_add_f32_e32 v138, 0x358637bd, v138
	v_rsq_f32_e32 v140, v138
	s_nop 0
	v_mul_f32_e32 v120, v16, v140
	v_mul_f32_e32 v121, v17, v140
	v_mul_f32_e32 v122, v18, v140
	v_mul_f32_e32 v123, v19, v140
	v_mul_f32_e32 v124, v20, v140
	v_mul_f32_e32 v125, v21, v140
	v_mul_f32_e32 v126, v22, v140
	v_mul_f32_e32 v127, v23, v140
	v_mul_f32_e32 v128, v24, v140
	v_mul_f32_e32 v129, v25, v140
	v_mul_f32_e32 v130, v26, v140
	v_mul_f32_e32 v131, v27, v140
	v_mul_f32_e32 v132, v28, v140
	v_mul_f32_e32 v133, v29, v140
	v_mul_f32_e32 v134, v30, v140
	v_mul_f32_e32 v135, v31, v140
	v_fma_f32 v120, v120, v88, v104
	v_fma_f32 v121, v121, v89, v105
	v_fma_f32 v122, v122, v90, v106
	v_fma_f32 v123, v123, v91, v107
	v_fma_f32 v124, v124, v92, v108
	v_fma_f32 v125, v125, v93, v109
	v_fma_f32 v126, v126, v94, v110
	v_fma_f32 v127, v127, v95, v111
	v_fma_f32 v128, v128, v96, v112
	v_fma_f32 v129, v129, v97, v113
	v_fma_f32 v130, v130, v98, v114
	v_fma_f32 v131, v131, v99, v115
	v_fma_f32 v132, v132, v100, v116
	v_fma_f32 v133, v133, v101, v117
	v_fma_f32 v134, v134, v102, v118
	v_fma_f32 v135, v135, v103, v119
	v_cvt_pk_bf16_f32 v156, v120, v121
	v_cvt_pk_bf16_f32 v157, v122, v123
	v_cvt_pk_bf16_f32 v158, v124, v125
	v_cvt_pk_bf16_f32 v159, v126, v127
	v_cvt_pk_bf16_f32 v160, v128, v129
	v_cvt_pk_bf16_f32 v161, v130, v131
	v_cvt_pk_bf16_f32 v162, v132, v133
	v_cvt_pk_bf16_f32 v163, v134, v135
	s_lshl_b32 vcc_lo, s19, 11
	s_add_u32 vcc_lo, vcc_lo, 0x400000
	s_add_u32 s100, s14, vcc_lo
	s_addc_u32 s101, s15, 0
	global_store_dwordx2 v137, v[156:157], s[100:101] offset:0
	global_store_dwordx2 v137, v[158:159], s[100:101] offset:512
	global_store_dwordx2 v137, v[160:161], s[100:101] offset:1024
	global_store_dwordx2 v137, v[162:163], s[100:101] offset:1536
	s_lshl_b32 vcc_lo, s19, 11
	s_add_u32 vcc_lo, vcc_lo, 0x1000000
	s_add_u32 s100, s12, vcc_lo
	s_addc_u32 s101, s13, 0
	global_load_dwordx2 v[24:25], v137, s[100:101] offset:0
	global_load_dwordx2 v[26:27], v137, s[100:101] offset:512
	global_load_dwordx2 v[28:29], v137, s[100:101] offset:1024
	global_load_dwordx2 v[30:31], v137, s[100:101] offset:1536
	s_lshl_b32 vcc_lo, s19, 11
	s_add_u32 vcc_lo, vcc_lo, 0x1000000
	s_add_u32 s100, s14, vcc_lo
	s_addc_u32 s101, s15, 0
	global_load_dwordx2 v[56:57], v137, s[100:101] offset:0
	global_load_dwordx2 v[58:59], v137, s[100:101] offset:512
	global_load_dwordx2 v[60:61], v137, s[100:101] offset:1024
	global_load_dwordx2 v[62:63], v137, s[100:101] offset:1536
	s_waitcnt vmcnt(32)
	v_lshlrev_b32_e32 v120, 16, v64
	v_and_b32_e32 v121, 0xffff0000, v64
	v_lshlrev_b32_e32 v122, 16, v65
	v_and_b32_e32 v123, 0xffff0000, v65
	v_lshlrev_b32_e32 v124, 16, v66
	v_and_b32_e32 v125, 0xffff0000, v66
	v_lshlrev_b32_e32 v126, 16, v67
	v_and_b32_e32 v127, 0xffff0000, v67
	v_lshlrev_b32_e32 v128, 16, v68
	v_and_b32_e32 v129, 0xffff0000, v68
	v_lshlrev_b32_e32 v130, 16, v69
	v_and_b32_e32 v131, 0xffff0000, v69
	v_lshlrev_b32_e32 v132, 16, v70
	v_and_b32_e32 v133, 0xffff0000, v70
	v_lshlrev_b32_e32 v134, 16, v71
	v_and_b32_e32 v135, 0xffff0000, v71
	v_mul_f32_e32 v138, v120, v120
	v_mul_f32_e32 v149, v121, v121
	v_mul_f32_e32 v150, v122, v122
	v_mul_f32_e32 v154, v123, v123
	v_fma_f32 v138, v124, v124, v138
	v_fma_f32 v149, v125, v125, v149
	v_fma_f32 v150, v126, v126, v150
	v_fma_f32 v154, v127, v127, v154
	v_fma_f32 v138, v128, v128, v138
	v_fma_f32 v149, v129, v129, v149
	v_fma_f32 v150, v130, v130, v150
	v_fma_f32 v154, v131, v131, v154
	v_fma_f32 v138, v132, v132, v138
	v_fma_f32 v149, v133, v133, v149
	v_fma_f32 v150, v134, v134, v150
	v_fma_f32 v154, v135, v135, v154
	v_add_f32_e32 v138, v138, v149
	v_add_f32_e32 v150, v150, v154
	v_add_f32_e32 v138, v138, v150
	s_nop 1
	v_add_f32_dpp v138, v138, v138 quad_perm:[1,0,3,2] row_mask:0xf bank_mask:0xf
	s_nop 1
	v_add_f32_dpp v138, v138, v138 quad_perm:[2,3,0,1] row_mask:0xf bank_mask:0xf
	s_nop 1
	v_add_f32_dpp v138, v138, v138 row_half_mirror row_mask:0xf bank_mask:0xf
	s_nop 1
	v_add_f32_dpp v138, v138, v138 row_mirror row_mask:0xf bank_mask:0xf
	v_mov_b32_e32 v139, v138
	s_nop 1
	v_permlane16_swap_b32_e32 v138, v139
	v_add_f32_e32 v138, v138, v139
	v_mov_b32_e32 v139, v138
	s_nop 1
	v_permlane32_swap_b32_e32 v138, v139
	v_add_f32_e32 v138, v138, v139
	v_mul_f32_e32 v138, 0x3a800000, v138
	v_add_f32_e32 v138, 0x358637bd, v138
	v_rsq_f32_e32 v140, v138
	v_lshlrev_b32_e32 v32, 16, v40
	v_and_b32_e32 v33, 0xffff0000, v40
; __device__ __forceinline__ void row_phase(const Params& P, int glayer, int layer, int xsrc, bool hasY, int gate_idx, const float* gpost,
;                           int xdst, bool doH, const float* gpre, int sh_idx, int nrows) {
;     ...
;         if (xsrc != 0 && row < N_X) {
; #pragma unroll
;           for (int i = 0; i < 4; ++i) {
;             const uint4 raw = xr[u][i];
;             xv[i].x = bf2f((u16)(raw.x & 0xffff)); xv[i].y = bf2f((u16)(raw.x >> 16));
;             xv[i].z = bf2f((u16)(raw.y & 0xffff)); xv[i].w = bf2f((u16)(raw.y >> 16));
;           }
;         } else {
; #pragma unroll
;           for (int i = 0; i < 4; ++i) {
;             xv[i].x = __uint_as_float(xr[u][i].x); xv[i].y = __uint_as_float(xr[u][i].y);
;             xv[i].z = __uint_as_float(xr[u][i].z); xv[i].w = __uint_as_float(xr[u][i].w);
;           }
;         }
;         if (hasY) {
;           float4 yv[4];
;           float ss = 0.f;
; #pragma unroll
;           for (int i = 0; i < 4; ++i) {
;             const uint2 raw = yy[u][i];
;             yv[i].x = bf2f((u16)(raw.x & 0xffff)); yv[i].y = bf2f((u16)(raw.x >> 16));
;             yv[i].z = bf2f((u16)(raw.y & 0xffff)); yv[i].w = bf2f((u16)(raw.y >> 16));
;             ss += yv[i].x * yv[i].x + yv[i].y * yv[i].y + yv[i].z * yv[i].z + yv[i].w * yv[i].w;
;           }
;           ss = wave_sum(ss);
;           const float rstd = __builtin_amdgcn_rsqf(ss * (1.f / 1024.f) + EPSF);
; #pragma unroll
;           for (int i = 0; i < 4; ++i) {
;             const int col = (i * 64 + lane) * 4;
;             const float4 gt = *reinterpret_cast<const float4*>(modg + gate_idx * 1024 + col);
;             const float4 gp = *reinterpret_cast<const float4*>(gpost + col);
;             xv[i].x += gt.x * (yv[i].x * rstd * gp.x); xv[i].y += gt.y * (yv[i].y * rstd * gp.y);
;             xv[i].z += gt.z * (yv[i].z * rstd * gp.z); xv[i].w += gt.w * (yv[i].w * rstd * gp.w);
;           }
;         }
;         if (xdst == 3 || (xdst == 1 && row >= N_X)) {
;           float* xout = (xdst == 3) ? P.out + (long)row * 1024 : P.xc + (long)(row - N_X) * 1024;
; #pragma unroll
;           for (int i = 0; i < 4; ++i) *reinterpret_cast<float4*>(xout + (i * 64 + lane) * 4) = xv[i];
;         } else if (xdst != 0) {
;           u16* xo = ((xdst == 1) ? resA : P.zf) + (long)row * 1024;
; #pragma unroll
;           for (int i = 0; i < 4; ++i) {
	v_lshlrev_b32_e32 v34, 16, v41
	v_and_b32_e32 v35, 0xffff0000, v41
	v_lshlrev_b32_e32 v36, 16, v42
	v_and_b32_e32 v37, 0xffff0000, v42
	v_lshlrev_b32_e32 v38, 16, v43
	v_and_b32_e32 v39, 0xffff0000, v43
	v_lshlrev_b32_e32 v40, 16, v44
	v_and_b32_e32 v41, 0xffff0000, v44
	v_lshlrev_b32_e32 v42, 16, v45
	v_and_b32_e32 v43, 0xffff0000, v45
	v_lshlrev_b32_e32 v44, 16, v46
	v_and_b32_e32 v45, 0xffff0000, v46
	v_lshlrev_b32_e32 v46, 16, v47
	v_and_b32_e32 v47, 0xffff0000, v47
	s_nop 0
	v_mul_f32_e32 v120, v120, v140
	v_mul_f32_e32 v121, v121, v140
	v_mul_f32_e32 v122, v122, v140
	v_mul_f32_e32 v123, v123, v140
	v_mul_f32_e32 v124, v124, v140
	v_mul_f32_e32 v125, v125, v140
	v_mul_f32_e32 v126, v126, v140
	v_mul_f32_e32 v127, v127, v140
	v_mul_f32_e32 v128, v128, v140
	v_mul_f32_e32 v129, v129, v140
	v_mul_f32_e32 v130, v130, v140
	v_mul_f32_e32 v131, v131, v140
	v_mul_f32_e32 v132, v132, v140
	v_mul_f32_e32 v133, v133, v140
	v_mul_f32_e32 v134, v134, v140
	v_mul_f32_e32 v135, v135, v140
	v_fma_f32 v32, v120, v72, v32
	v_fma_f32 v33, v121, v73, v33
	v_fma_f32 v34, v122, v74, v34
	v_fma_f32 v35, v123, v75, v35
	v_fma_f32 v36, v124, v76, v36
	v_fma_f32 v37, v125, v77, v37
	v_fma_f32 v38, v126, v78, v38
	v_fma_f32 v39, v127, v79, v39
	v_fma_f32 v40, v128, v80, v40
	v_fma_f32 v41, v129, v81, v41
	v_fma_f32 v42, v130, v82, v42
	v_fma_f32 v43, v131, v83, v43
	v_fma_f32 v44, v132, v84, v44
	v_fma_f32 v45, v133, v85, v45
	v_fma_f32 v46, v134, v86, v46
	v_fma_f32 v47, v135, v87, v47
	v_cvt_pk_bf16_f32 v156, v32, v33
	v_cvt_pk_bf16_f32 v157, v34, v35
	v_cvt_pk_bf16_f32 v158, v36, v37
	v_cvt_pk_bf16_f32 v159, v38, v39
	v_cvt_pk_bf16_f32 v160, v40, v41
	v_cvt_pk_bf16_f32 v161, v42, v43
	v_cvt_pk_bf16_f32 v162, v44, v45
	v_cvt_pk_bf16_f32 v163, v46, v47
	s_lshl_b32 vcc_lo, s19, 11
	s_add_u32 vcc_lo, vcc_lo, 0x800000
	s_add_u32 s100, s16, vcc_lo
	s_addc_u32 s101, s17, 0
	global_store_dwordx2 v137, v[156:157], s[100:101] offset:0
	global_store_dwordx2 v137, v[158:159], s[100:101] offset:512
	global_store_dwordx2 v137, v[160:161], s[100:101] offset:1024
	global_store_dwordx2 v137, v[162:163], s[100:101] offset:1536
	v_mul_f32_e32 v138, v32, v32
	v_mul_f32_e32 v149, v33, v33
	v_mul_f32_e32 v150, v34, v34
	v_mul_f32_e32 v154, v35, v35
	v_fma_f32 v138, v36, v36, v138
	v_fma_f32 v149, v37, v37, v149
	v_fma_f32 v150, v38, v38, v150
	v_fma_f32 v154, v39, v39, v154
	v_fma_f32 v138, v40, v40, v138
	v_fma_f32 v149, v41, v41, v149
	v_fma_f32 v150, v42, v42, v150
	v_fma_f32 v154, v43, v43, v154
	v_fma_f32 v138, v44, v44, v138
	v_fma_f32 v149, v45, v45, v149
	v_fma_f32 v150, v46, v46, v150
	v_fma_f32 v154, v47, v47, v154
	v_add_f32_e32 v138, v138, v149
	v_add_f32_e32 v150, v150, v154
	v_add_f32_e32 v138, v138, v150
	s_nop 1
	v_add_f32_dpp v138, v138, v138 quad_perm:[1,0,3,2] row_mask:0xf bank_mask:0xf
	s_nop 1
	v_add_f32_dpp v138, v138, v138 quad_perm:[2,3,0,1] row_mask:0xf bank_mask:0xf
	s_nop 1
	v_add_f32_dpp v138, v138, v138 row_half_mirror row_mask:0xf bank_mask:0xf
	s_nop 1
	v_add_f32_dpp v138, v138, v138 row_mirror row_mask:0xf bank_mask:0xf
	v_mov_b32_e32 v139, v138
	s_nop 1
	v_permlane16_swap_b32_e32 v138, v139
	v_add_f32_e32 v138, v138, v139
	v_mov_b32_e32 v139, v138
	s_nop 1
	v_permlane32_swap_b32_e32 v138, v139
	v_add_f32_e32 v138, v138, v139
	v_mul_f32_e32 v138, 0x3a800000, v138
	v_add_f32_e32 v138, 0x358637bd, v138
	v_rsq_f32_e32 v140, v138
	s_nop 0
	v_mul_f32_e32 v120, v32, v140
	v_mul_f32_e32 v121, v33, v140
	v_mul_f32_e32 v122, v34, v140
	v_mul_f32_e32 v123, v35, v140
	v_mul_f32_e32 v124, v36, v140
	v_mul_f32_e32 v125, v37, v140
	v_mul_f32_e32 v126, v38, v140
	v_mul_f32_e32 v127, v39, v140
	v_mul_f32_e32 v128, v40, v140
	v_mul_f32_e32 v129, v41, v140
	v_mul_f32_e32 v130, v42, v140
	v_mul_f32_e32 v131, v43, v140
	v_mul_f32_e32 v132, v44, v140
	v_mul_f32_e32 v133, v45, v140
	v_mul_f32_e32 v134, v46, v140
	v_mul_f32_e32 v135, v47, v140
	v_fma_f32 v120, v120, v88, v104
	v_fma_f32 v121, v121, v89, v105
	v_fma_f32 v122, v122, v90, v106
	v_fma_f32 v123, v123, v91, v107
	v_fma_f32 v124, v124, v92, v108
	v_fma_f32 v125, v125, v93, v109
	v_fma_f32 v126, v126, v94, v110
	v_fma_f32 v127, v127, v95, v111
	v_fma_f32 v128, v128, v96, v112
	v_fma_f32 v129, v129, v97, v113
	v_fma_f32 v130, v130, v98, v114
	v_fma_f32 v131, v131, v99, v115
	v_fma_f32 v132, v132, v100, v116
	v_fma_f32 v133, v133, v101, v117
	v_fma_f32 v134, v134, v102, v118
	v_fma_f32 v135, v135, v103, v119
	v_cvt_pk_bf16_f32 v156, v120, v121
	v_cvt_pk_bf16_f32 v157, v122, v123
	v_cvt_pk_bf16_f32 v158, v124, v125
	v_cvt_pk_bf16_f32 v159, v126, v127
	v_cvt_pk_bf16_f32 v160, v128, v129
	v_cvt_pk_bf16_f32 v161, v130, v131
	v_cvt_pk_bf16_f32 v162, v132, v133
	v_cvt_pk_bf16_f32 v163, v134, v135
	s_lshl_b32 vcc_lo, s19, 11
	s_add_u32 vcc_lo, vcc_lo, 0x800000
	s_add_u32 s100, s14, vcc_lo
	s_addc_u32 s101, s15, 0
	global_store_dwordx2 v137, v[156:157], s[100:101] offset:0
	global_store_dwordx2 v137, v[158:159], s[100:101] offset:512
	global_store_dwordx2 v137, v[160:161], s[100:101] offset:1024
	global_store_dwordx2 v137, v[162:163], s[100:101] offset:1536
	s_lshl_b32 vcc_lo, s19, 11
	s_add_u32 vcc_lo, vcc_lo, 0x1400000
	s_add_u32 s100, s12, vcc_lo
	s_addc_u32 s101, s13, 0
	global_load_dwordx2 v[40:41], v137, s[100:101] offset:0
	global_load_dwordx2 v[42:43], v137, s[100:101] offset:512
	global_load_dwordx2 v[44:45], v137, s[100:101] offset:1024
	global_load_dwordx2 v[46:47], v137, s[100:101] offset:1536
	s_lshl_b32 vcc_lo, s19, 11
	s_add_u32 vcc_lo, vcc_lo, 0x1400000
	s_add_u32 s100, s14, vcc_lo
	s_addc_u32 s101, s15, 0
	global_load_dwordx2 v[64:65], v137, s[100:101] offset:0
	global_load_dwordx2 v[66:67], v137, s[100:101] offset:512
	global_load_dwordx2 v[68:69], v137, s[100:101] offset:1024
	global_load_dwordx2 v[70:71], v137, s[100:101] offset:1536
	s_waitcnt vmcnt(32)
; __device__ __forceinline__ void row_phase(const Params& P, int glayer, int layer, int xsrc, bool hasY, int gate_idx, const float* gpost,
;                           int xdst, bool doH, const float* gpre, int sh_idx, int nrows) {
;     ...
;         if (hasY) {
;           float4 yv[4];
;           float ss = 0.f;
; #pragma unroll
;           for (int i = 0; i < 4; ++i) {
;             const uint2 raw = yy[u][i];
;             yv[i].x = bf2f((u16)(raw.x & 0xffff)); yv[i].y = bf2f((u16)(raw.x >> 16));
;             yv[i].z = bf2f((u16)(raw.y & 0xffff)); yv[i].w = bf2f((u16)(raw.y >> 16));
;             ss += yv[i].x * yv[i].x + yv[i].y * yv[i].y + yv[i].z * yv[i].z + yv[i].w * yv[i].w;
;           }
;           ss = wave_sum(ss);
;           const float rstd = __builtin_amdgcn_rsqf(ss * (1.f / 1024.f) + EPSF);
; #pragma unroll
;           for (int i = 0; i < 4; ++i) {
;             const int col = (i * 64 + lane) * 4;
;             const float4 gt = *reinterpret_cast<const float4*>(modg + gate_idx * 1024 + col);
;             const float4 gp = *reinterpret_cast<const float4*>(gpost + col);
;             xv[i].x += gt.x * (yv[i].x * rstd * gp.x); xv[i].y += gt.y * (yv[i].y * rstd * gp.y);
;             xv[i].z += gt.z * (yv[i].z * rstd * gp.z); xv[i].w += gt.w * (yv[i].w * rstd * gp.w);
;           }
;         }
;         if (xdst == 3 || (xdst == 1 && row >= N_X)) {
;           float* xout = (xdst == 3) ? P.out + (long)row * 1024 : P.xc + (long)(row - N_X) * 1024;
; #pragma unroll
;           for (int i = 0; i < 4; ++i) *reinterpret_cast<float4*>(xout + (i * 64 + lane) * 4) = xv[i];
;         } else if (xdst != 0) {
;           u16* xo = ((xdst == 1) ? resA : P.zf) + (long)row * 1024;
; #pragma unroll
;           for (int i = 0; i < 4; ++i) {
;             const unsigned b0 = f2bf(xv[i].x), b1 = f2bf(xv[i].y), b2 = f2bf(xv[i].z), b3 = f2bf(xv[i].w);
;             *reinterpret_cast<uint2*>(xo + (i * 64 + lane) * 4) = make_uint2(b0 | (b1 << 16), b2 | (b3 << 16));
;           }
;         }
;         if (doH) {
;           float ss = 0.f;
; #pragma unroll
;           for (int i = 0; i < 4; ++i) ss += xv[i].x * xv[i].x + xv[i].y * xv[i].y + xv[i].z * xv[i].z + xv[i].w * xv[i].w;
;           ss = wave_sum(ss);
;           const float rstd = __builtin_amdgcn_rsqf(ss * (1.f / 1024.f) + EPSF);
;           u16* h = P.hy + (long)row * 1024;
; #pragma unroll
	v_lshlrev_b32_e32 v120, 16, v48
	v_and_b32_e32 v121, 0xffff0000, v48
	v_lshlrev_b32_e32 v122, 16, v49
	v_and_b32_e32 v123, 0xffff0000, v49
	v_lshlrev_b32_e32 v124, 16, v50
	v_and_b32_e32 v125, 0xffff0000, v50
	v_lshlrev_b32_e32 v126, 16, v51
	v_and_b32_e32 v127, 0xffff0000, v51
	v_lshlrev_b32_e32 v128, 16, v52
	v_and_b32_e32 v129, 0xffff0000, v52
	v_lshlrev_b32_e32 v130, 16, v53
	v_and_b32_e32 v131, 0xffff0000, v53
	v_lshlrev_b32_e32 v132, 16, v54
	v_and_b32_e32 v133, 0xffff0000, v54
	v_lshlrev_b32_e32 v134, 16, v55
	v_and_b32_e32 v135, 0xffff0000, v55
	v_mul_f32_e32 v138, v120, v120
	v_mul_f32_e32 v149, v121, v121
	v_mul_f32_e32 v150, v122, v122
	v_mul_f32_e32 v154, v123, v123
	v_fma_f32 v138, v124, v124, v138
	v_fma_f32 v149, v125, v125, v149
	v_fma_f32 v150, v126, v126, v150
	v_fma_f32 v154, v127, v127, v154
	v_fma_f32 v138, v128, v128, v138
	v_fma_f32 v149, v129, v129, v149
	v_fma_f32 v150, v130, v130, v150
	v_fma_f32 v154, v131, v131, v154
	v_fma_f32 v138, v132, v132, v138
	v_fma_f32 v149, v133, v133, v149
	v_fma_f32 v150, v134, v134, v150
	v_fma_f32 v154, v135, v135, v154
	v_add_f32_e32 v138, v138, v149
	v_add_f32_e32 v150, v150, v154
	v_add_f32_e32 v138, v138, v150
	s_nop 1
	v_add_f32_dpp v138, v138, v138 quad_perm:[1,0,3,2] row_mask:0xf bank_mask:0xf
	s_nop 1
	v_add_f32_dpp v138, v138, v138 quad_perm:[2,3,0,1] row_mask:0xf bank_mask:0xf
	s_nop 1
	v_add_f32_dpp v138, v138, v138 row_half_mirror row_mask:0xf bank_mask:0xf
	s_nop 1
	v_add_f32_dpp v138, v138, v138 row_mirror row_mask:0xf bank_mask:0xf
	v_mov_b32_e32 v139, v138
	s_nop 1
	v_permlane16_swap_b32_e32 v138, v139
	v_add_f32_e32 v138, v138, v139
	v_mov_b32_e32 v139, v138
	s_nop 1
	v_permlane32_swap_b32_e32 v138, v139
	v_add_f32_e32 v138, v138, v139
	v_mul_f32_e32 v138, 0x3a800000, v138
	v_add_f32_e32 v138, 0x358637bd, v138
	v_rsq_f32_e32 v140, v138
	v_lshlrev_b32_e32 v0, 16, v8
	v_and_b32_e32 v1, 0xffff0000, v8
	v_lshlrev_b32_e32 v2, 16, v9
	v_and_b32_e32 v3, 0xffff0000, v9
	v_lshlrev_b32_e32 v4, 16, v10
	v_and_b32_e32 v5, 0xffff0000, v10
	v_lshlrev_b32_e32 v6, 16, v11
	v_and_b32_e32 v7, 0xffff0000, v11
	v_lshlrev_b32_e32 v8, 16, v12
	v_and_b32_e32 v9, 0xffff0000, v12
	v_lshlrev_b32_e32 v10, 16, v13
	v_and_b32_e32 v11, 0xffff0000, v13
	v_lshlrev_b32_e32 v12, 16, v14
	v_and_b32_e32 v13, 0xffff0000, v14
	v_lshlrev_b32_e32 v14, 16, v15
	v_and_b32_e32 v15, 0xffff0000, v15
	s_nop 0
	v_mul_f32_e32 v120, v120, v140
	v_mul_f32_e32 v121, v121, v140
	v_mul_f32_e32 v122, v122, v140
	v_mul_f32_e32 v123, v123, v140
	v_mul_f32_e32 v124, v124, v140
	v_mul_f32_e32 v125, v125, v140
	v_mul_f32_e32 v126, v126, v140
	v_mul_f32_e32 v127, v127, v140
	v_mul_f32_e32 v128, v128, v140
	v_mul_f32_e32 v129, v129, v140
	v_mul_f32_e32 v130, v130, v140
	v_mul_f32_e32 v131, v131, v140
	v_mul_f32_e32 v132, v132, v140
	v_mul_f32_e32 v133, v133, v140
	v_mul_f32_e32 v134, v134, v140
	v_mul_f32_e32 v135, v135, v140
	v_fma_f32 v0, v120, v72, v0
	v_fma_f32 v1, v121, v73, v1
	v_fma_f32 v2, v122, v74, v2
	v_fma_f32 v3, v123, v75, v3
	v_fma_f32 v4, v124, v76, v4
	v_fma_f32 v5, v125, v77, v5
	v_fma_f32 v6, v126, v78, v6
	v_fma_f32 v7, v127, v79, v7
	v_fma_f32 v8, v128, v80, v8
	v_fma_f32 v9, v129, v81, v9
	v_fma_f32 v10, v130, v82, v10
	v_fma_f32 v11, v131, v83, v11
	v_fma_f32 v12, v132, v84, v12
	v_fma_f32 v13, v133, v85, v13
	v_fma_f32 v14, v134, v86, v14
	v_fma_f32 v15, v135, v87, v15
	v_cvt_pk_bf16_f32 v156, v0, v1
	v_cvt_pk_bf16_f32 v157, v2, v3
	v_cvt_pk_bf16_f32 v158, v4, v5
	v_cvt_pk_bf16_f32 v159, v6, v7
	v_cvt_pk_bf16_f32 v160, v8, v9
	v_cvt_pk_bf16_f32 v161, v10, v11
	v_cvt_pk_bf16_f32 v162, v12, v13
	v_cvt_pk_bf16_f32 v163, v14, v15
	s_lshl_b32 vcc_lo, s19, 11
	s_add_u32 vcc_lo, vcc_lo, 0xc00000
	s_add_u32 s100, s16, vcc_lo
	s_addc_u32 s101, s17, 0
	global_store_dwordx2 v137, v[156:157], s[100:101] offset:0
	global_store_dwordx2 v137, v[158:159], s[100:101] offset:512
	global_store_dwordx2 v137, v[160:161], s[100:101] offset:1024
	global_store_dwordx2 v137, v[162:163], s[100:101] offset:1536
	v_mul_f32_e32 v138, v0, v0
	v_mul_f32_e32 v149, v1, v1
	v_mul_f32_e32 v150, v2, v2
	v_mul_f32_e32 v154, v3, v3
	v_fma_f32 v138, v4, v4, v138
	v_fma_f32 v149, v5, v5, v149
	v_fma_f32 v150, v6, v6, v150
	v_fma_f32 v154, v7, v7, v154
	v_fma_f32 v138, v8, v8, v138
	v_fma_f32 v149, v9, v9, v149
	v_fma_f32 v150, v10, v10, v150
	v_fma_f32 v154, v11, v11, v154
	v_fma_f32 v138, v12, v12, v138
	v_fma_f32 v149, v13, v13, v149
	v_fma_f32 v150, v14, v14, v150
	v_fma_f32 v154, v15, v15, v154
	v_add_f32_e32 v138, v138, v149
	v_add_f32_e32 v150, v150, v154
	v_add_f32_e32 v138, v138, v150
	s_nop 1
	v_add_f32_dpp v138, v138, v138 quad_perm:[1,0,3,2] row_mask:0xf bank_mask:0xf
	s_nop 1
	v_add_f32_dpp v138, v138, v138 quad_perm:[2,3,0,1] row_mask:0xf bank_mask:0xf
	s_nop 1
	v_add_f32_dpp v138, v138, v138 row_half_mirror row_mask:0xf bank_mask:0xf
	s_nop 1
	v_add_f32_dpp v138, v138, v138 row_mirror row_mask:0xf bank_mask:0xf
	v_mov_b32_e32 v139, v138
	s_nop 1
	v_permlane16_swap_b32_e32 v138, v139
	v_add_f32_e32 v138, v138, v139
	v_mov_b32_e32 v139, v138
	s_nop 1
	v_permlane32_swap_b32_e32 v138, v139
	v_add_f32_e32 v138, v138, v139
	v_mul_f32_e32 v138, 0x3a800000, v138
	v_add_f32_e32 v138, 0x358637bd, v138
	v_rsq_f32_e32 v140, v138
	s_nop 0
	v_mul_f32_e32 v120, v0, v140
	v_mul_f32_e32 v121, v1, v140
	v_mul_f32_e32 v122, v2, v140
	v_mul_f32_e32 v123, v3, v140
	v_mul_f32_e32 v124, v4, v140
	v_mul_f32_e32 v125, v5, v140
	v_mul_f32_e32 v126, v6, v140
	v_mul_f32_e32 v127, v7, v140
	v_mul_f32_e32 v128, v8, v140
	v_mul_f32_e32 v129, v9, v140
	v_mul_f32_e32 v130, v10, v140
	v_mul_f32_e32 v131, v11, v140
	v_mul_f32_e32 v132, v12, v140
; __device__ __forceinline__ float bf2f(u16 h) { return __uint_as_float(((unsigned)h) << 16); }
; __device__ __forceinline__ void row_phase(const Params& P, int glayer, int layer, int xsrc, bool hasY, int gate_idx, const float* gpost,
;                           int xdst, bool doH, const float* gpre, int sh_idx, int nrows) {
;     ...
;         const int mi = row < N_X ? (row >> 13) : 4;
;         const float* modp = P.mod + (long)(layer * 5 + mi) * 6144;
;         const float* modg = P.mod + (long)(glayer * 5 + mi) * 6144;
;         float4 xv[4];
;         if (xsrc != 0 && row < N_X) {
; #pragma unroll
;           for (int i = 0; i < 4; ++i) {
;             const uint4 raw = xr[u][i];
;             xv[i].x = bf2f((u16)(raw.x & 0xffff)); xv[i].y = bf2f((u16)(raw.x >> 16));
;             xv[i].z = bf2f((u16)(raw.y & 0xffff)); xv[i].w = bf2f((u16)(raw.y >> 16));
;           }
;         } else {
; #pragma unroll
;           for (int i = 0; i < 4; ++i) {
;             xv[i].x = __uint_as_float(xr[u][i].x); xv[i].y = __uint_as_float(xr[u][i].y);
;             xv[i].z = __uint_as_float(xr[u][i].z); xv[i].w = __uint_as_float(xr[u][i].w);
;           }
;         }
;         if (hasY) {
;           float4 yv[4];
;           float ss = 0.f;
; #pragma unroll
;           for (int i = 0; i < 4; ++i) {
;             const uint2 raw = yy[u][i];
;             yv[i].x = bf2f((u16)(raw.x & 0xffff)); yv[i].y = bf2f((u16)(raw.x >> 16));
;             yv[i].z = bf2f((u16)(raw.y & 0xffff)); yv[i].w = bf2f((u16)(raw.y >> 16));
;             ss += yv[i].x * yv[i].x + yv[i].y * yv[i].y + yv[i].z * yv[i].z + yv[i].w * yv[i].w;
;           }
;           ss = wave_sum(ss);
;           const float rstd = __builtin_amdgcn_rsqf(ss * (1.f / 1024.f) + EPSF);
; #pragma unroll
;           for (int i = 0; i < 4; ++i) {
;             const int col = (i * 64 + lane) * 4;
;             const float4 gt = *reinterpret_cast<const float4*>(modg + gate_idx * 1024 + col);
;             const float4 gp = *reinterpret_cast<const float4*>(gpost + col);
;             xv[i].x += gt.x * (yv[i].x * rstd * gp.x); xv[i].y += gt.y * (yv[i].y * rstd * gp.y);
;             xv[i].z += gt.z * (yv[i].z * rstd * gp.z); xv[i].w += gt.w * (yv[i].w * rstd * gp.w);
;           }
;         }
	v_mul_f32_e32 v133, v13, v140
	v_mul_f32_e32 v134, v14, v140
	v_mul_f32_e32 v135, v15, v140
	v_fma_f32 v120, v120, v88, v104
	v_fma_f32 v121, v121, v89, v105
	v_fma_f32 v122, v122, v90, v106
	v_fma_f32 v123, v123, v91, v107
	v_fma_f32 v124, v124, v92, v108
	v_fma_f32 v125, v125, v93, v109
	v_fma_f32 v126, v126, v94, v110
	v_fma_f32 v127, v127, v95, v111
	v_fma_f32 v128, v128, v96, v112
	v_fma_f32 v129, v129, v97, v113
	v_fma_f32 v130, v130, v98, v114
	v_fma_f32 v131, v131, v99, v115
	v_fma_f32 v132, v132, v100, v116
	v_fma_f32 v133, v133, v101, v117
	v_fma_f32 v134, v134, v102, v118
	v_fma_f32 v135, v135, v103, v119
	v_cvt_pk_bf16_f32 v156, v120, v121
	v_cvt_pk_bf16_f32 v157, v122, v123
	v_cvt_pk_bf16_f32 v158, v124, v125
	v_cvt_pk_bf16_f32 v159, v126, v127
	v_cvt_pk_bf16_f32 v160, v128, v129
	v_cvt_pk_bf16_f32 v161, v130, v131
	v_cvt_pk_bf16_f32 v162, v132, v133
	v_cvt_pk_bf16_f32 v163, v134, v135
	s_lshl_b32 vcc_lo, s19, 11
	s_add_u32 vcc_lo, vcc_lo, 0xc00000
	s_add_u32 s100, s14, vcc_lo
	s_addc_u32 s101, s15, 0
	global_store_dwordx2 v137, v[156:157], s[100:101] offset:0
	global_store_dwordx2 v137, v[158:159], s[100:101] offset:512
	global_store_dwordx2 v137, v[160:161], s[100:101] offset:1024
	global_store_dwordx2 v137, v[162:163], s[100:101] offset:1536
	s_add_u32 s100, s20, 0xb000
	s_addc_u32 s101, s21, 0
	global_load_dwordx4 v[72:75], v136, s[100:101] offset:0
	global_load_dwordx4 v[76:79], v136, s[100:101] offset:1024
	global_load_dwordx4 v[80:83], v136, s[100:101] offset:2048
	global_load_dwordx4 v[84:87], v136, s[100:101] offset:3072
	s_load_dwordx2 s[98:99], s[4:5], 0x48
	s_waitcnt lgkmcnt(0)
	global_load_dwordx4 v[120:123], v136, s[98:99] offset:0
	global_load_dwordx4 v[124:127], v136, s[98:99] offset:1024
	global_load_dwordx4 v[128:131], v136, s[98:99] offset:2048
	global_load_dwordx4 v[132:135], v136, s[98:99] offset:3072
	s_add_u32 s100, s20, 0x24000
	s_addc_u32 s101, s21, 0
	global_load_dwordx4 v[104:107], v136, s[100:101] offset:0
	global_load_dwordx4 v[108:111], v136, s[100:101] offset:1024
	global_load_dwordx4 v[112:115], v136, s[100:101] offset:2048
	global_load_dwordx4 v[116:119], v136, s[100:101] offset:3072
	s_add_u32 s100, s100, 0x1000
	s_addc_u32 s101, s101, 0
	global_load_dwordx4 v[0:3], v136, s[100:101] offset:0
	global_load_dwordx4 v[4:7], v136, s[100:101] offset:1024
	global_load_dwordx4 v[8:11], v136, s[100:101] offset:2048
	global_load_dwordx4 v[12:15], v136, s[100:101] offset:3072
	s_load_dwordx2 s[98:99], s[4:5], 0x30
	s_waitcnt lgkmcnt(0)
	s_add_u32 s98, s98, 0x1000
	s_addc_u32 s99, s99, 0
	global_load_dwordx4 v[88:91], v136, s[98:99] offset:0
	global_load_dwordx4 v[92:95], v136, s[98:99] offset:1024
	global_load_dwordx4 v[96:99], v136, s[98:99] offset:2048
	global_load_dwordx4 v[100:103], v136, s[98:99] offset:3072
	s_waitcnt vmcnt(0)
	v_mul_f32_e32 v72, v72, v120
	v_mul_f32_e32 v73, v73, v121
	v_mul_f32_e32 v74, v74, v122
	v_mul_f32_e32 v75, v75, v123
	v_mul_f32_e32 v76, v76, v124
	v_mul_f32_e32 v77, v77, v125
	v_mul_f32_e32 v78, v78, v126
	v_mul_f32_e32 v79, v79, v127
	v_mul_f32_e32 v80, v80, v128
	v_mul_f32_e32 v81, v81, v129
	v_mul_f32_e32 v82, v82, v130
	v_mul_f32_e32 v83, v83, v131
	v_mul_f32_e32 v84, v84, v132
	v_mul_f32_e32 v85, v85, v133
	v_mul_f32_e32 v86, v86, v134
	v_mul_f32_e32 v87, v87, v135
	v_fma_f32 v88, v88, v0, v88
	v_fma_f32 v89, v89, v1, v89
	v_fma_f32 v90, v90, v2, v90
	v_fma_f32 v91, v91, v3, v91
	v_fma_f32 v92, v92, v4, v92
	v_fma_f32 v93, v93, v5, v93
	v_fma_f32 v94, v94, v6, v94
	v_fma_f32 v95, v95, v7, v95
	v_fma_f32 v96, v96, v8, v96
	v_fma_f32 v97, v97, v9, v97
	v_fma_f32 v98, v98, v10, v98
	v_fma_f32 v99, v99, v11, v99
	v_fma_f32 v100, v100, v12, v100
	v_fma_f32 v101, v101, v13, v101
	v_fma_f32 v102, v102, v14, v102
	v_fma_f32 v103, v103, v15, v103
	s_lshl_b32 vcc_lo, s19, 11
	s_add_u32 vcc_lo, vcc_lo, 0x1800000
	s_add_u32 s100, s12, vcc_lo
	s_addc_u32 s101, s13, 0
	global_load_dwordx2 v[8:9], v137, s[100:101] offset:0
	global_load_dwordx2 v[10:11], v137, s[100:101] offset:512
	global_load_dwordx2 v[12:13], v137, s[100:101] offset:1024
	global_load_dwordx2 v[14:15], v137, s[100:101] offset:1536
	s_lshl_b32 vcc_lo, s19, 11
	s_add_u32 vcc_lo, vcc_lo, 0x1800000
	s_add_u32 s100, s14, vcc_lo
	s_addc_u32 s101, s15, 0
	global_load_dwordx2 v[48:49], v137, s[100:101] offset:0
	global_load_dwordx2 v[50:51], v137, s[100:101] offset:512
	global_load_dwordx2 v[52:53], v137, s[100:101] offset:1024
	global_load_dwordx2 v[54:55], v137, s[100:101] offset:1536
	v_lshlrev_b32_e32 v120, 16, v56
	v_and_b32_e32 v121, 0xffff0000, v56
	v_lshlrev_b32_e32 v122, 16, v57
	v_and_b32_e32 v123, 0xffff0000, v57
	v_lshlrev_b32_e32 v124, 16, v58
	v_and_b32_e32 v125, 0xffff0000, v58
	v_lshlrev_b32_e32 v126, 16, v59
	v_and_b32_e32 v127, 0xffff0000, v59
	v_lshlrev_b32_e32 v128, 16, v60
	v_and_b32_e32 v129, 0xffff0000, v60
	v_lshlrev_b32_e32 v130, 16, v61
	v_and_b32_e32 v131, 0xffff0000, v61
	v_lshlrev_b32_e32 v132, 16, v62
	v_and_b32_e32 v133, 0xffff0000, v62
	v_lshlrev_b32_e32 v134, 16, v63
	v_and_b32_e32 v135, 0xffff0000, v63
	v_mul_f32_e32 v138, v120, v120
	v_mul_f32_e32 v149, v121, v121
	v_mul_f32_e32 v150, v122, v122
	v_mul_f32_e32 v154, v123, v123
	v_fma_f32 v138, v124, v124, v138
	v_fma_f32 v149, v125, v125, v149
	v_fma_f32 v150, v126, v126, v150
	v_fma_f32 v154, v127, v127, v154
	v_fma_f32 v138, v128, v128, v138
	v_fma_f32 v149, v129, v129, v149
	v_fma_f32 v150, v130, v130, v150
	v_fma_f32 v154, v131, v131, v154
	v_fma_f32 v138, v132, v132, v138
	v_fma_f32 v149, v133, v133, v149
	v_fma_f32 v150, v134, v134, v150
	v_fma_f32 v154, v135, v135, v154
	v_add_f32_e32 v138, v138, v149
	v_add_f32_e32 v150, v150, v154
; __device__ __forceinline__ void row_phase(const Params& P, int glayer, int layer, int xsrc, bool hasY, int gate_idx, const float* gpost,
;                           int xdst, bool doH, const float* gpre, int sh_idx, int nrows) {
;     ...
;         if (xsrc != 0 && row < N_X) {
; #pragma unroll
;           for (int i = 0; i < 4; ++i) {
;             const uint4 raw = xr[u][i];
;             xv[i].x = bf2f((u16)(raw.x & 0xffff)); xv[i].y = bf2f((u16)(raw.x >> 16));
;             xv[i].z = bf2f((u16)(raw.y & 0xffff)); xv[i].w = bf2f((u16)(raw.y >> 16));
;           }
;         } else {
; #pragma unroll
;           for (int i = 0; i < 4; ++i) {
;             xv[i].x = __uint_as_float(xr[u][i].x); xv[i].y = __uint_as_float(xr[u][i].y);
;             xv[i].z = __uint_as_float(xr[u][i].z); xv[i].w = __uint_as_float(xr[u][i].w);
;           }
;         }
;         if (hasY) {
;           float4 yv[4];
;           float ss = 0.f;
; #pragma unroll
;           for (int i = 0; i < 4; ++i) {
;             const uint2 raw = yy[u][i];
;             yv[i].x = bf2f((u16)(raw.x & 0xffff)); yv[i].y = bf2f((u16)(raw.x >> 16));
;             yv[i].z = bf2f((u16)(raw.y & 0xffff)); yv[i].w = bf2f((u16)(raw.y >> 16));
;             ss += yv[i].x * yv[i].x + yv[i].y * yv[i].y + yv[i].z * yv[i].z + yv[i].w * yv[i].w;
;           }
;           ss = wave_sum(ss);
;           const float rstd = __builtin_amdgcn_rsqf(ss * (1.f / 1024.f) + EPSF);
; #pragma unroll
;           for (int i = 0; i < 4; ++i) {
;             const int col = (i * 64 + lane) * 4;
;             const float4 gt = *reinterpret_cast<const float4*>(modg + gate_idx * 1024 + col);
;             const float4 gp = *reinterpret_cast<const float4*>(gpost + col);
;             xv[i].x += gt.x * (yv[i].x * rstd * gp.x); xv[i].y += gt.y * (yv[i].y * rstd * gp.y);
;             xv[i].z += gt.z * (yv[i].z * rstd * gp.z); xv[i].w += gt.w * (yv[i].w * rstd * gp.w);
;           }
;         }
;         if (xdst == 3 || (xdst == 1 && row >= N_X)) {
;           float* xout = (xdst == 3) ? P.out + (long)row * 1024 : P.xc + (long)(row - N_X) * 1024;
; #pragma unroll
;           for (int i = 0; i < 4; ++i) *reinterpret_cast<float4*>(xout + (i * 64 + lane) * 4) = xv[i];
;         } else if (xdst != 0) {
;           u16* xo = ((xdst == 1) ? resA : P.zf) + (long)row * 1024;
; #pragma unroll
;           for (int i = 0; i < 4; ++i) {
	v_add_f32_e32 v138, v138, v150
	s_nop 1
	v_add_f32_dpp v138, v138, v138 quad_perm:[1,0,3,2] row_mask:0xf bank_mask:0xf
	s_nop 1
	v_add_f32_dpp v138, v138, v138 quad_perm:[2,3,0,1] row_mask:0xf bank_mask:0xf
	s_nop 1
	v_add_f32_dpp v138, v138, v138 row_half_mirror row_mask:0xf bank_mask:0xf
	s_nop 1
	v_add_f32_dpp v138, v138, v138 row_mirror row_mask:0xf bank_mask:0xf
	v_mov_b32_e32 v139, v138
	s_nop 1
	v_permlane16_swap_b32_e32 v138, v139
	v_add_f32_e32 v138, v138, v139
	v_mov_b32_e32 v139, v138
	s_nop 1
	v_permlane32_swap_b32_e32 v138, v139
	v_add_f32_e32 v138, v138, v139
	v_mul_f32_e32 v138, 0x3a800000, v138
	v_add_f32_e32 v138, 0x358637bd, v138
	v_rsq_f32_e32 v140, v138
	v_lshlrev_b32_e32 v16, 16, v24
	v_and_b32_e32 v17, 0xffff0000, v24
	v_lshlrev_b32_e32 v18, 16, v25
	v_and_b32_e32 v19, 0xffff0000, v25
	v_lshlrev_b32_e32 v20, 16, v26
	v_and_b32_e32 v21, 0xffff0000, v26
	v_lshlrev_b32_e32 v22, 16, v27
	v_and_b32_e32 v23, 0xffff0000, v27
	v_lshlrev_b32_e32 v24, 16, v28
	v_and_b32_e32 v25, 0xffff0000, v28
	v_lshlrev_b32_e32 v26, 16, v29
	v_and_b32_e32 v27, 0xffff0000, v29
	v_lshlrev_b32_e32 v28, 16, v30
	v_and_b32_e32 v29, 0xffff0000, v30
	v_lshlrev_b32_e32 v30, 16, v31
	v_and_b32_e32 v31, 0xffff0000, v31
	s_nop 0
	v_mul_f32_e32 v120, v120, v140
	v_mul_f32_e32 v121, v121, v140
	v_mul_f32_e32 v122, v122, v140
	v_mul_f32_e32 v123, v123, v140
	v_mul_f32_e32 v124, v124, v140
	v_mul_f32_e32 v125, v125, v140
	v_mul_f32_e32 v126, v126, v140
	v_mul_f32_e32 v127, v127, v140
	v_mul_f32_e32 v128, v128, v140
	v_mul_f32_e32 v129, v129, v140
	v_mul_f32_e32 v130, v130, v140
	v_mul_f32_e32 v131, v131, v140
	v_mul_f32_e32 v132, v132, v140
	v_mul_f32_e32 v133, v133, v140
	v_mul_f32_e32 v134, v134, v140
	v_mul_f32_e32 v135, v135, v140
	v_fma_f32 v16, v120, v72, v16
	v_fma_f32 v17, v121, v73, v17
	v_fma_f32 v18, v122, v74, v18
	v_fma_f32 v19, v123, v75, v19
	v_fma_f32 v20, v124, v76, v20
	v_fma_f32 v21, v125, v77, v21
	v_fma_f32 v22, v126, v78, v22
	v_fma_f32 v23, v127, v79, v23
	v_fma_f32 v24, v128, v80, v24
	v_fma_f32 v25, v129, v81, v25
	v_fma_f32 v26, v130, v82, v26
	v_fma_f32 v27, v131, v83, v27
	v_fma_f32 v28, v132, v84, v28
	v_fma_f32 v29, v133, v85, v29
	v_fma_f32 v30, v134, v86, v30
	v_fma_f32 v31, v135, v87, v31
	v_cvt_pk_bf16_f32 v156, v16, v17
	v_cvt_pk_bf16_f32 v157, v18, v19
	v_cvt_pk_bf16_f32 v158, v20, v21
	v_cvt_pk_bf16_f32 v159, v22, v23
	v_cvt_pk_bf16_f32 v160, v24, v25
	v_cvt_pk_bf16_f32 v161, v26, v27
	v_cvt_pk_bf16_f32 v162, v28, v29
	v_cvt_pk_bf16_f32 v163, v30, v31
	s_lshl_b32 vcc_lo, s19, 11
	s_add_u32 vcc_lo, vcc_lo, 0x1000000
	s_add_u32 s100, s16, vcc_lo
	s_addc_u32 s101, s17, 0
	global_store_dwordx2 v137, v[156:157], s[100:101] offset:0
	global_store_dwordx2 v137, v[158:159], s[100:101] offset:512
	global_store_dwordx2 v137, v[160:161], s[100:101] offset:1024
	global_store_dwordx2 v137, v[162:163], s[100:101] offset:1536
	v_mul_f32_e32 v138, v16, v16
	v_mul_f32_e32 v149, v17, v17
	v_mul_f32_e32 v150, v18, v18
	v_mul_f32_e32 v154, v19, v19
	v_fma_f32 v138, v20, v20, v138
	v_fma_f32 v149, v21, v21, v149
	v_fma_f32 v150, v22, v22, v150
	v_fma_f32 v154, v23, v23, v154
	v_fma_f32 v138, v24, v24, v138
	v_fma_f32 v149, v25, v25, v149
	v_fma_f32 v150, v26, v26, v150
	v_fma_f32 v154, v27, v27, v154
	v_fma_f32 v138, v28, v28, v138
	v_fma_f32 v149, v29, v29, v149
	v_fma_f32 v150, v30, v30, v150
	v_fma_f32 v154, v31, v31, v154
	v_add_f32_e32 v138, v138, v149
	v_add_f32_e32 v150, v150, v154
	v_add_f32_e32 v138, v138, v150
	s_nop 1
	v_add_f32_dpp v138, v138, v138 quad_perm:[1,0,3,2] row_mask:0xf bank_mask:0xf
	s_nop 1
	v_add_f32_dpp v138, v138, v138 quad_perm:[2,3,0,1] row_mask:0xf bank_mask:0xf
	s_nop 1
	v_add_f32_dpp v138, v138, v138 row_half_mirror row_mask:0xf bank_mask:0xf
	s_nop 1
	v_add_f32_dpp v138, v138, v138 row_mirror row_mask:0xf bank_mask:0xf
	v_mov_b32_e32 v139, v138
	s_nop 1
	v_permlane16_swap_b32_e32 v138, v139
	v_add_f32_e32 v138, v138, v139
	v_mov_b32_e32 v139, v138
	s_nop 1
	v_permlane32_swap_b32_e32 v138, v139
	v_add_f32_e32 v138, v138, v139
	v_mul_f32_e32 v138, 0x3a800000, v138
	v_add_f32_e32 v138, 0x358637bd, v138
	v_rsq_f32_e32 v140, v138
	s_nop 0
	v_mul_f32_e32 v120, v16, v140
	v_mul_f32_e32 v121, v17, v140
	v_mul_f32_e32 v122, v18, v140
	v_mul_f32_e32 v123, v19, v140
	v_mul_f32_e32 v124, v20, v140
	v_mul_f32_e32 v125, v21, v140
	v_mul_f32_e32 v126, v22, v140
	v_mul_f32_e32 v127, v23, v140
	v_mul_f32_e32 v128, v24, v140
	v_mul_f32_e32 v129, v25, v140
	v_mul_f32_e32 v130, v26, v140
	v_mul_f32_e32 v131, v27, v140
	v_mul_f32_e32 v132, v28, v140
	v_mul_f32_e32 v133, v29, v140
	v_mul_f32_e32 v134, v30, v140
	v_mul_f32_e32 v135, v31, v140
	v_fma_f32 v120, v120, v88, v104
	v_fma_f32 v121, v121, v89, v105
	v_fma_f32 v122, v122, v90, v106
	v_fma_f32 v123, v123, v91, v107
	v_fma_f32 v124, v124, v92, v108
	v_fma_f32 v125, v125, v93, v109
	v_fma_f32 v126, v126, v94, v110
	v_fma_f32 v127, v127, v95, v111
	v_fma_f32 v128, v128, v96, v112
	v_fma_f32 v129, v129, v97, v113
	v_fma_f32 v130, v130, v98, v114
	v_fma_f32 v131, v131, v99, v115
	v_fma_f32 v132, v132, v100, v116
	v_fma_f32 v133, v133, v101, v117
	v_fma_f32 v134, v134, v102, v118
	v_fma_f32 v135, v135, v103, v119
	v_cvt_pk_bf16_f32 v156, v120, v121
	v_cvt_pk_bf16_f32 v157, v122, v123
	v_cvt_pk_bf16_f32 v158, v124, v125
	v_cvt_pk_bf16_f32 v159, v126, v127
	v_cvt_pk_bf16_f32 v160, v128, v129
	v_cvt_pk_bf16_f32 v161, v130, v131
	v_cvt_pk_bf16_f32 v162, v132, v133
	v_cvt_pk_bf16_f32 v163, v134, v135
	s_lshl_b32 vcc_lo, s19, 11
	s_add_u32 vcc_lo, vcc_lo, 0x1000000
	s_add_u32 s100, s14, vcc_lo
	s_addc_u32 s101, s15, 0
	global_store_dwordx2 v137, v[156:157], s[100:101] offset:0
; __device__ __forceinline__ void row_phase(const Params& P, int glayer, int layer, int xsrc, bool hasY, int gate_idx, const float* gpost,
;                           int xdst, bool doH, const float* gpre, int sh_idx, int nrows) {
;     ...
;         if (hasY) {
;           float4 yv[4];
;           float ss = 0.f;
; #pragma unroll
;           for (int i = 0; i < 4; ++i) {
;             const uint2 raw = yy[u][i];
;             yv[i].x = bf2f((u16)(raw.x & 0xffff)); yv[i].y = bf2f((u16)(raw.x >> 16));
;             yv[i].z = bf2f((u16)(raw.y & 0xffff)); yv[i].w = bf2f((u16)(raw.y >> 16));
;             ss += yv[i].x * yv[i].x + yv[i].y * yv[i].y + yv[i].z * yv[i].z + yv[i].w * yv[i].w;
;           }
;           ss = wave_sum(ss);
;           const float rstd = __builtin_amdgcn_rsqf(ss * (1.f / 1024.f) + EPSF);
; #pragma unroll
;           for (int i = 0; i < 4; ++i) {
;             const int col = (i * 64 + lane) * 4;
;             const float4 gt = *reinterpret_cast<const float4*>(modg + gate_idx * 1024 + col);
;             const float4 gp = *reinterpret_cast<const float4*>(gpost + col);
;             xv[i].x += gt.x * (yv[i].x * rstd * gp.x); xv[i].y += gt.y * (yv[i].y * rstd * gp.y);
;             xv[i].z += gt.z * (yv[i].z * rstd * gp.z); xv[i].w += gt.w * (yv[i].w * rstd * gp.w);
;           }
;         }
;         if (xdst == 3 || (xdst == 1 && row >= N_X)) {
;           float* xout = (xdst == 3) ? P.out + (long)row * 1024 : P.xc + (long)(row - N_X) * 1024;
; #pragma unroll
;           for (int i = 0; i < 4; ++i) *reinterpret_cast<float4*>(xout + (i * 64 + lane) * 4) = xv[i];
;         } else if (xdst != 0) {
;           u16* xo = ((xdst == 1) ? resA : P.zf) + (long)row * 1024;
; #pragma unroll
;           for (int i = 0; i < 4; ++i) {
;             const unsigned b0 = f2bf(xv[i].x), b1 = f2bf(xv[i].y), b2 = f2bf(xv[i].z), b3 = f2bf(xv[i].w);
;             *reinterpret_cast<uint2*>(xo + (i * 64 + lane) * 4) = make_uint2(b0 | (b1 << 16), b2 | (b3 << 16));
;           }
;         }
;         if (doH) {
;           float ss = 0.f;
; #pragma unroll
;           for (int i = 0; i < 4; ++i) ss += xv[i].x * xv[i].x + xv[i].y * xv[i].y + xv[i].z * xv[i].z + xv[i].w * xv[i].w;
;           ss = wave_sum(ss);
;           const float rstd = __builtin_amdgcn_rsqf(ss * (1.f / 1024.f) + EPSF);
;           u16* h = P.hy + (long)row * 1024;
; #pragma unroll
	global_store_dwordx2 v137, v[158:159], s[100:101] offset:512
	global_store_dwordx2 v137, v[160:161], s[100:101] offset:1024
	global_store_dwordx2 v137, v[162:163], s[100:101] offset:1536
	s_lshl_b32 vcc_lo, s19, 11
	s_add_u32 vcc_lo, vcc_lo, 0x1c00000
	s_add_u32 s100, s12, vcc_lo
	s_addc_u32 s101, s13, 0
	global_load_dwordx2 v[24:25], v137, s[100:101] offset:0
	global_load_dwordx2 v[26:27], v137, s[100:101] offset:512
	global_load_dwordx2 v[28:29], v137, s[100:101] offset:1024
	global_load_dwordx2 v[30:31], v137, s[100:101] offset:1536
	s_lshl_b32 vcc_lo, s19, 11
	s_add_u32 vcc_lo, vcc_lo, 0x1c00000
	s_add_u32 s100, s14, vcc_lo
	s_addc_u32 s101, s15, 0
	global_load_dwordx2 v[56:57], v137, s[100:101] offset:0
	global_load_dwordx2 v[58:59], v137, s[100:101] offset:512
	global_load_dwordx2 v[60:61], v137, s[100:101] offset:1024
	global_load_dwordx2 v[62:63], v137, s[100:101] offset:1536
	v_lshlrev_b32_e32 v120, 16, v64
	v_and_b32_e32 v121, 0xffff0000, v64
	v_lshlrev_b32_e32 v122, 16, v65
	v_and_b32_e32 v123, 0xffff0000, v65
	v_lshlrev_b32_e32 v124, 16, v66
	v_and_b32_e32 v125, 0xffff0000, v66
	v_lshlrev_b32_e32 v126, 16, v67
	v_and_b32_e32 v127, 0xffff0000, v67
	v_lshlrev_b32_e32 v128, 16, v68
	v_and_b32_e32 v129, 0xffff0000, v68
	v_lshlrev_b32_e32 v130, 16, v69
	v_and_b32_e32 v131, 0xffff0000, v69
	v_lshlrev_b32_e32 v132, 16, v70
	v_and_b32_e32 v133, 0xffff0000, v70
	v_lshlrev_b32_e32 v134, 16, v71
	v_and_b32_e32 v135, 0xffff0000, v71
	v_mul_f32_e32 v138, v120, v120
	v_mul_f32_e32 v149, v121, v121
	v_mul_f32_e32 v150, v122, v122
	v_mul_f32_e32 v154, v123, v123
	v_fma_f32 v138, v124, v124, v138
	v_fma_f32 v149, v125, v125, v149
	v_fma_f32 v150, v126, v126, v150
	v_fma_f32 v154, v127, v127, v154
	v_fma_f32 v138, v128, v128, v138
	v_fma_f32 v149, v129, v129, v149
	v_fma_f32 v150, v130, v130, v150
	v_fma_f32 v154, v131, v131, v154
	v_fma_f32 v138, v132, v132, v138
	v_fma_f32 v149, v133, v133, v149
	v_fma_f32 v150, v134, v134, v150
	v_fma_f32 v154, v135, v135, v154
	v_add_f32_e32 v138, v138, v149
	v_add_f32_e32 v150, v150, v154
	v_add_f32_e32 v138, v138, v150
	s_nop 1
	v_add_f32_dpp v138, v138, v138 quad_perm:[1,0,3,2] row_mask:0xf bank_mask:0xf
	s_nop 1
	v_add_f32_dpp v138, v138, v138 quad_perm:[2,3,0,1] row_mask:0xf bank_mask:0xf
	s_nop 1
	v_add_f32_dpp v138, v138, v138 row_half_mirror row_mask:0xf bank_mask:0xf
	s_nop 1
	v_add_f32_dpp v138, v138, v138 row_mirror row_mask:0xf bank_mask:0xf
	v_mov_b32_e32 v139, v138
	s_nop 1
	v_permlane16_swap_b32_e32 v138, v139
	v_add_f32_e32 v138, v138, v139
	v_mov_b32_e32 v139, v138
	s_nop 1
	v_permlane32_swap_b32_e32 v138, v139
	v_add_f32_e32 v138, v138, v139
	v_mul_f32_e32 v138, 0x3a800000, v138
	v_add_f32_e32 v138, 0x358637bd, v138
	v_rsq_f32_e32 v140, v138
	v_lshlrev_b32_e32 v32, 16, v40
	v_and_b32_e32 v33, 0xffff0000, v40
	v_lshlrev_b32_e32 v34, 16, v41
	v_and_b32_e32 v35, 0xffff0000, v41
	v_lshlrev_b32_e32 v36, 16, v42
	v_and_b32_e32 v37, 0xffff0000, v42
	v_lshlrev_b32_e32 v38, 16, v43
	v_and_b32_e32 v39, 0xffff0000, v43
	v_lshlrev_b32_e32 v40, 16, v44
	v_and_b32_e32 v41, 0xffff0000, v44
	v_lshlrev_b32_e32 v42, 16, v45
	v_and_b32_e32 v43, 0xffff0000, v45
	v_lshlrev_b32_e32 v44, 16, v46
	v_and_b32_e32 v45, 0xffff0000, v46
	v_lshlrev_b32_e32 v46, 16, v47
	v_and_b32_e32 v47, 0xffff0000, v47
	s_nop 0
	v_mul_f32_e32 v120, v120, v140
	v_mul_f32_e32 v121, v121, v140
	v_mul_f32_e32 v122, v122, v140
	v_mul_f32_e32 v123, v123, v140
	v_mul_f32_e32 v124, v124, v140
	v_mul_f32_e32 v125, v125, v140
	v_mul_f32_e32 v126, v126, v140
	v_mul_f32_e32 v127, v127, v140
	v_mul_f32_e32 v128, v128, v140
	v_mul_f32_e32 v129, v129, v140
	v_mul_f32_e32 v130, v130, v140
	v_mul_f32_e32 v131, v131, v140
	v_mul_f32_e32 v132, v132, v140
	v_mul_f32_e32 v133, v133, v140
	v_mul_f32_e32 v134, v134, v140
	v_mul_f32_e32 v135, v135, v140
	v_fma_f32 v32, v120, v72, v32
	v_fma_f32 v33, v121, v73, v33
	v_fma_f32 v34, v122, v74, v34
	v_fma_f32 v35, v123, v75, v35
	v_fma_f32 v36, v124, v76, v36
	v_fma_f32 v37, v125, v77, v37
	v_fma_f32 v38, v126, v78, v38
	v_fma_f32 v39, v127, v79, v39
	v_fma_f32 v40, v128, v80, v40
	v_fma_f32 v41, v129, v81, v41
	v_fma_f32 v42, v130, v82, v42
	v_fma_f32 v43, v131, v83, v43
	v_fma_f32 v44, v132, v84, v44
	v_fma_f32 v45, v133, v85, v45
	v_fma_f32 v46, v134, v86, v46
	v_fma_f32 v47, v135, v87, v47
	v_cvt_pk_bf16_f32 v156, v32, v33
	v_cvt_pk_bf16_f32 v157, v34, v35
	v_cvt_pk_bf16_f32 v158, v36, v37
	v_cvt_pk_bf16_f32 v159, v38, v39
	v_cvt_pk_bf16_f32 v160, v40, v41
	v_cvt_pk_bf16_f32 v161, v42, v43
	v_cvt_pk_bf16_f32 v162, v44, v45
	v_cvt_pk_bf16_f32 v163, v46, v47
	s_lshl_b32 vcc_lo, s19, 11
	s_add_u32 vcc_lo, vcc_lo, 0x1400000
	s_add_u32 s100, s16, vcc_lo
	s_addc_u32 s101, s17, 0
	global_store_dwordx2 v137, v[156:157], s[100:101] offset:0
	global_store_dwordx2 v137, v[158:159], s[100:101] offset:512
	global_store_dwordx2 v137, v[160:161], s[100:101] offset:1024
	global_store_dwordx2 v137, v[162:163], s[100:101] offset:1536
	v_mul_f32_e32 v138, v32, v32
	v_mul_f32_e32 v149, v33, v33
	v_mul_f32_e32 v150, v34, v34
	v_mul_f32_e32 v154, v35, v35
	v_fma_f32 v138, v36, v36, v138
	v_fma_f32 v149, v37, v37, v149
	v_fma_f32 v150, v38, v38, v150
	v_fma_f32 v154, v39, v39, v154
	v_fma_f32 v138, v40, v40, v138
	v_fma_f32 v149, v41, v41, v149
	v_fma_f32 v150, v42, v42, v150
	v_fma_f32 v154, v43, v43, v154
	v_fma_f32 v138, v44, v44, v138
	v_fma_f32 v149, v45, v45, v149
	v_fma_f32 v150, v46, v46, v150
	v_fma_f32 v154, v47, v47, v154
	v_add_f32_e32 v138, v138, v149
	v_add_f32_e32 v150, v150, v154
	v_add_f32_e32 v138, v138, v150
	s_nop 1
	v_add_f32_dpp v138, v138, v138 quad_perm:[1,0,3,2] row_mask:0xf bank_mask:0xf
	s_nop 1
; __device__ __forceinline__ void row_phase(const Params& P, int glayer, int layer, int xsrc, bool hasY, int gate_idx, const float* gpost,
;                           int xdst, bool doH, const float* gpre, int sh_idx, int nrows) {
;     ...
;         if (hasY) {
;           float4 yv[4];
;           float ss = 0.f;
; #pragma unroll
;           for (int i = 0; i < 4; ++i) {
;             const uint2 raw = yy[u][i];
;             yv[i].x = bf2f((u16)(raw.x & 0xffff)); yv[i].y = bf2f((u16)(raw.x >> 16));
;             yv[i].z = bf2f((u16)(raw.y & 0xffff)); yv[i].w = bf2f((u16)(raw.y >> 16));
;             ss += yv[i].x * yv[i].x + yv[i].y * yv[i].y + yv[i].z * yv[i].z + yv[i].w * yv[i].w;
;           }
;           ss = wave_sum(ss);
;           const float rstd = __builtin_amdgcn_rsqf(ss * (1.f / 1024.f) + EPSF);
; #pragma unroll
;           for (int i = 0; i < 4; ++i) {
;             const int col = (i * 64 + lane) * 4;
;             const float4 gt = *reinterpret_cast<const float4*>(modg + gate_idx * 1024 + col);
;             const float4 gp = *reinterpret_cast<const float4*>(gpost + col);
;             xv[i].x += gt.x * (yv[i].x * rstd * gp.x); xv[i].y += gt.y * (yv[i].y * rstd * gp.y);
;             xv[i].z += gt.z * (yv[i].z * rstd * gp.z); xv[i].w += gt.w * (yv[i].w * rstd * gp.w);
;           }
;         }
;         if (xdst == 3 || (xdst == 1 && row >= N_X)) {
;           float* xout = (xdst == 3) ? P.out + (long)row * 1024 : P.xc + (long)(row - N_X) * 1024;
; #pragma unroll
;           for (int i = 0; i < 4; ++i) *reinterpret_cast<float4*>(xout + (i * 64 + lane) * 4) = xv[i];
;         } else if (xdst != 0) {
;           u16* xo = ((xdst == 1) ? resA : P.zf) + (long)row * 1024;
; #pragma unroll
;           for (int i = 0; i < 4; ++i) {
;             const unsigned b0 = f2bf(xv[i].x), b1 = f2bf(xv[i].y), b2 = f2bf(xv[i].z), b3 = f2bf(xv[i].w);
;             *reinterpret_cast<uint2*>(xo + (i * 64 + lane) * 4) = make_uint2(b0 | (b1 << 16), b2 | (b3 << 16));
;           }
;         }
;         if (doH) {
;           float ss = 0.f;
; #pragma unroll
;           for (int i = 0; i < 4; ++i) ss += xv[i].x * xv[i].x + xv[i].y * xv[i].y + xv[i].z * xv[i].z + xv[i].w * xv[i].w;
;           ss = wave_sum(ss);
;           const float rstd = __builtin_amdgcn_rsqf(ss * (1.f / 1024.f) + EPSF);
;           u16* h = P.hy + (long)row * 1024;
; #pragma unroll
	v_add_f32_dpp v138, v138, v138 quad_perm:[2,3,0,1] row_mask:0xf bank_mask:0xf
	s_nop 1
	v_add_f32_dpp v138, v138, v138 row_half_mirror row_mask:0xf bank_mask:0xf
	s_nop 1
	v_add_f32_dpp v138, v138, v138 row_mirror row_mask:0xf bank_mask:0xf
	v_mov_b32_e32 v139, v138
	s_nop 1
	v_permlane16_swap_b32_e32 v138, v139
	v_add_f32_e32 v138, v138, v139
	v_mov_b32_e32 v139, v138
	s_nop 1
	v_permlane32_swap_b32_e32 v138, v139
	v_add_f32_e32 v138, v138, v139
	v_mul_f32_e32 v138, 0x3a800000, v138
	v_add_f32_e32 v138, 0x358637bd, v138
	v_rsq_f32_e32 v140, v138
	s_nop 0
	v_mul_f32_e32 v120, v32, v140
	v_mul_f32_e32 v121, v33, v140
	v_mul_f32_e32 v122, v34, v140
	v_mul_f32_e32 v123, v35, v140
	v_mul_f32_e32 v124, v36, v140
	v_mul_f32_e32 v125, v37, v140
	v_mul_f32_e32 v126, v38, v140
	v_mul_f32_e32 v127, v39, v140
	v_mul_f32_e32 v128, v40, v140
	v_mul_f32_e32 v129, v41, v140
	v_mul_f32_e32 v130, v42, v140
	v_mul_f32_e32 v131, v43, v140
	v_mul_f32_e32 v132, v44, v140
	v_mul_f32_e32 v133, v45, v140
	v_mul_f32_e32 v134, v46, v140
	v_mul_f32_e32 v135, v47, v140
	v_fma_f32 v120, v120, v88, v104
	v_fma_f32 v121, v121, v89, v105
	v_fma_f32 v122, v122, v90, v106
	v_fma_f32 v123, v123, v91, v107
	v_fma_f32 v124, v124, v92, v108
	v_fma_f32 v125, v125, v93, v109
	v_fma_f32 v126, v126, v94, v110
	v_fma_f32 v127, v127, v95, v111
	v_fma_f32 v128, v128, v96, v112
	v_fma_f32 v129, v129, v97, v113
	v_fma_f32 v130, v130, v98, v114
	v_fma_f32 v131, v131, v99, v115
	v_fma_f32 v132, v132, v100, v116
	v_fma_f32 v133, v133, v101, v117
	v_fma_f32 v134, v134, v102, v118
	v_fma_f32 v135, v135, v103, v119
	v_cvt_pk_bf16_f32 v156, v120, v121
	v_cvt_pk_bf16_f32 v157, v122, v123
	v_cvt_pk_bf16_f32 v158, v124, v125
	v_cvt_pk_bf16_f32 v159, v126, v127
	v_cvt_pk_bf16_f32 v160, v128, v129
	v_cvt_pk_bf16_f32 v161, v130, v131
	v_cvt_pk_bf16_f32 v162, v132, v133
	v_cvt_pk_bf16_f32 v163, v134, v135
	s_lshl_b32 vcc_lo, s19, 11
	s_add_u32 vcc_lo, vcc_lo, 0x1400000
	s_add_u32 s100, s14, vcc_lo
	s_addc_u32 s101, s15, 0
	global_store_dwordx2 v137, v[156:157], s[100:101] offset:0
	global_store_dwordx2 v137, v[158:159], s[100:101] offset:512
	global_store_dwordx2 v137, v[160:161], s[100:101] offset:1024
	global_store_dwordx2 v137, v[162:163], s[100:101] offset:1536
	s_lshl_b32 vcc_lo, s19, 11
	s_add_u32 vcc_lo, vcc_lo, 0x2000000
	s_add_u32 s100, s12, vcc_lo
	s_addc_u32 s101, s13, 0
	global_load_dwordx2 v[40:41], v137, s[100:101] offset:0
	global_load_dwordx2 v[42:43], v137, s[100:101] offset:512
	global_load_dwordx2 v[44:45], v137, s[100:101] offset:1024
	global_load_dwordx2 v[46:47], v137, s[100:101] offset:1536
	s_lshl_b32 vcc_lo, s19, 11
	s_add_u32 vcc_lo, vcc_lo, 0x2000000
	s_add_u32 s100, s14, vcc_lo
	s_addc_u32 s101, s15, 0
	global_load_dwordx2 v[64:65], v137, s[100:101] offset:0
	global_load_dwordx2 v[66:67], v137, s[100:101] offset:512
	global_load_dwordx2 v[68:69], v137, s[100:101] offset:1024
	global_load_dwordx2 v[70:71], v137, s[100:101] offset:1536
	s_waitcnt vmcnt(32)
	v_lshlrev_b32_e32 v120, 16, v48
	v_and_b32_e32 v121, 0xffff0000, v48
	v_lshlrev_b32_e32 v122, 16, v49
	v_and_b32_e32 v123, 0xffff0000, v49
	v_lshlrev_b32_e32 v124, 16, v50
	v_and_b32_e32 v125, 0xffff0000, v50
	v_lshlrev_b32_e32 v126, 16, v51
	v_and_b32_e32 v127, 0xffff0000, v51
	v_lshlrev_b32_e32 v128, 16, v52
	v_and_b32_e32 v129, 0xffff0000, v52
	v_lshlrev_b32_e32 v130, 16, v53
	v_and_b32_e32 v131, 0xffff0000, v53
	v_lshlrev_b32_e32 v132, 16, v54
	v_and_b32_e32 v133, 0xffff0000, v54
	v_lshlrev_b32_e32 v134, 16, v55
	v_and_b32_e32 v135, 0xffff0000, v55
	v_mul_f32_e32 v138, v120, v120
	v_mul_f32_e32 v149, v121, v121
	v_mul_f32_e32 v150, v122, v122
	v_mul_f32_e32 v154, v123, v123
	v_fma_f32 v138, v124, v124, v138
	v_fma_f32 v149, v125, v125, v149
	v_fma_f32 v150, v126, v126, v150
	v_fma_f32 v154, v127, v127, v154
	v_fma_f32 v138, v128, v128, v138
	v_fma_f32 v149, v129, v129, v149
	v_fma_f32 v150, v130, v130, v150
	v_fma_f32 v154, v131, v131, v154
	v_fma_f32 v138, v132, v132, v138
	v_fma_f32 v149, v133, v133, v149
	v_fma_f32 v150, v134, v134, v150
	v_fma_f32 v154, v135, v135, v154
	v_add_f32_e32 v138, v138, v149
	v_add_f32_e32 v150, v150, v154
	v_add_f32_e32 v138, v138, v150
	s_nop 1
	v_add_f32_dpp v138, v138, v138 quad_perm:[1,0,3,2] row_mask:0xf bank_mask:0xf
	s_nop 1
	v_add_f32_dpp v138, v138, v138 quad_perm:[2,3,0,1] row_mask:0xf bank_mask:0xf
	s_nop 1
	v_add_f32_dpp v138, v138, v138 row_half_mirror row_mask:0xf bank_mask:0xf
	s_nop 1
	v_add_f32_dpp v138, v138, v138 row_mirror row_mask:0xf bank_mask:0xf
	v_mov_b32_e32 v139, v138
	s_nop 1
	v_permlane16_swap_b32_e32 v138, v139
	v_add_f32_e32 v138, v138, v139
	v_mov_b32_e32 v139, v138
	s_nop 1
	v_permlane32_swap_b32_e32 v138, v139
	v_add_f32_e32 v138, v138, v139
	v_mul_f32_e32 v138, 0x3a800000, v138
	v_add_f32_e32 v138, 0x358637bd, v138
	v_rsq_f32_e32 v140, v138
	v_lshlrev_b32_e32 v0, 16, v8
	v_and_b32_e32 v1, 0xffff0000, v8
	v_lshlrev_b32_e32 v2, 16, v9
	v_and_b32_e32 v3, 0xffff0000, v9
	v_lshlrev_b32_e32 v4, 16, v10
	v_and_b32_e32 v5, 0xffff0000, v10
	v_lshlrev_b32_e32 v6, 16, v11
	v_and_b32_e32 v7, 0xffff0000, v11
	v_lshlrev_b32_e32 v8, 16, v12
	v_and_b32_e32 v9, 0xffff0000, v12
	v_lshlrev_b32_e32 v10, 16, v13
	v_and_b32_e32 v11, 0xffff0000, v13
	v_lshlrev_b32_e32 v12, 16, v14
	v_and_b32_e32 v13, 0xffff0000, v14
	v_lshlrev_b32_e32 v14, 16, v15
	v_and_b32_e32 v15, 0xffff0000, v15
	s_nop 0
	v_mul_f32_e32 v120, v120, v140
	v_mul_f32_e32 v121, v121, v140
	v_mul_f32_e32 v122, v122, v140
	v_mul_f32_e32 v123, v123, v140
	v_mul_f32_e32 v124, v124, v140
	v_mul_f32_e32 v125, v125, v140
	v_mul_f32_e32 v126, v126, v140
	v_mul_f32_e32 v127, v127, v140
	v_mul_f32_e32 v128, v128, v140
; __device__ __forceinline__ void row_phase(const Params& P, int glayer, int layer, int xsrc, bool hasY, int gate_idx, const float* gpost,
;                           int xdst, bool doH, const float* gpre, int sh_idx, int nrows) {
;     ...
;             xv[i].x += gt.x * (yv[i].x * rstd * gp.x); xv[i].y += gt.y * (yv[i].y * rstd * gp.y);
;             xv[i].z += gt.z * (yv[i].z * rstd * gp.z); xv[i].w += gt.w * (yv[i].w * rstd * gp.w);
;           }
;         }
;         if (xdst == 3 || (xdst == 1 && row >= N_X)) {
;           float* xout = (xdst == 3) ? P.out + (long)row * 1024 : P.xc + (long)(row - N_X) * 1024;
; #pragma unroll
;           for (int i = 0; i < 4; ++i) *reinterpret_cast<float4*>(xout + (i * 64 + lane) * 4) = xv[i];
;         } else if (xdst != 0) {
;           u16* xo = ((xdst == 1) ? resA : P.zf) + (long)row * 1024;
; #pragma unroll
;           for (int i = 0; i < 4; ++i) {
;             const unsigned b0 = f2bf(xv[i].x), b1 = f2bf(xv[i].y), b2 = f2bf(xv[i].z), b3 = f2bf(xv[i].w);
;             *reinterpret_cast<uint2*>(xo + (i * 64 + lane) * 4) = make_uint2(b0 | (b1 << 16), b2 | (b3 << 16));
;           }
;         }
;         if (doH) {
;           float ss = 0.f;
; #pragma unroll
;           for (int i = 0; i < 4; ++i) ss += xv[i].x * xv[i].x + xv[i].y * xv[i].y + xv[i].z * xv[i].z + xv[i].w * xv[i].w;
;           ss = wave_sum(ss);
;           const float rstd = __builtin_amdgcn_rsqf(ss * (1.f / 1024.f) + EPSF);
;           u16* h = P.hy + (long)row * 1024;
; #pragma unroll
;           for (int i = 0; i < 4; ++i) {
;             const int col = (i * 64 + lane) * 4;
;             const float4 g = *reinterpret_cast<const float4*>(gpre + col);
;             const float4 sh = *reinterpret_cast<const float4*>(modp + sh_idx * 1024 + col);
;             const float4 sc = *reinterpret_cast<const float4*>(modp + (sh_idx + 1) * 1024 + col);
;             const unsigned h0 = f2bf(xv[i].x * rstd * g.x * (1.f + sc.x) + sh.x);
;             const unsigned h1 = f2bf(xv[i].y * rstd * g.y * (1.f + sc.y) + sh.y);
;             const unsigned h2 = f2bf(xv[i].z * rstd * g.z * (1.f + sc.z) + sh.z);
;             const unsigned h3 = f2bf(xv[i].w * rstd * g.w * (1.f + sc.w) + sh.w);
;             *reinterpret_cast<uint2*>(h + col) = make_uint2(h0 | (h1 << 16), h2 | (h3 << 16));
	v_mul_f32_e32 v129, v129, v140
	v_mul_f32_e32 v130, v130, v140
	v_mul_f32_e32 v131, v131, v140
	v_mul_f32_e32 v132, v132, v140
	v_mul_f32_e32 v133, v133, v140
	v_mul_f32_e32 v134, v134, v140
	v_mul_f32_e32 v135, v135, v140
	v_fma_f32 v0, v120, v72, v0
	v_fma_f32 v1, v121, v73, v1
	v_fma_f32 v2, v122, v74, v2
	v_fma_f32 v3, v123, v75, v3
	v_fma_f32 v4, v124, v76, v4
	v_fma_f32 v5, v125, v77, v5
	v_fma_f32 v6, v126, v78, v6
	v_fma_f32 v7, v127, v79, v7
	v_fma_f32 v8, v128, v80, v8
	v_fma_f32 v9, v129, v81, v9
	v_fma_f32 v10, v130, v82, v10
	v_fma_f32 v11, v131, v83, v11
	v_fma_f32 v12, v132, v84, v12
	v_fma_f32 v13, v133, v85, v13
	v_fma_f32 v14, v134, v86, v14
	v_fma_f32 v15, v135, v87, v15
	v_cvt_pk_bf16_f32 v156, v0, v1
	v_cvt_pk_bf16_f32 v157, v2, v3
	v_cvt_pk_bf16_f32 v158, v4, v5
	v_cvt_pk_bf16_f32 v159, v6, v7
	v_cvt_pk_bf16_f32 v160, v8, v9
	v_cvt_pk_bf16_f32 v161, v10, v11
	v_cvt_pk_bf16_f32 v162, v12, v13
	v_cvt_pk_bf16_f32 v163, v14, v15
	s_lshl_b32 vcc_lo, s19, 11
	s_add_u32 vcc_lo, vcc_lo, 0x1800000
	s_add_u32 s100, s16, vcc_lo
	s_addc_u32 s101, s17, 0
	global_store_dwordx2 v137, v[156:157], s[100:101] offset:0
	global_store_dwordx2 v137, v[158:159], s[100:101] offset:512
	global_store_dwordx2 v137, v[160:161], s[100:101] offset:1024
	global_store_dwordx2 v137, v[162:163], s[100:101] offset:1536
	v_mul_f32_e32 v138, v0, v0
	v_mul_f32_e32 v149, v1, v1
	v_mul_f32_e32 v150, v2, v2
	v_mul_f32_e32 v154, v3, v3
	v_fma_f32 v138, v4, v4, v138
	v_fma_f32 v149, v5, v5, v149
	v_fma_f32 v150, v6, v6, v150
	v_fma_f32 v154, v7, v7, v154
	v_fma_f32 v138, v8, v8, v138
	v_fma_f32 v149, v9, v9, v149
	v_fma_f32 v150, v10, v10, v150
	v_fma_f32 v154, v11, v11, v154
	v_fma_f32 v138, v12, v12, v138
	v_fma_f32 v149, v13, v13, v149
	v_fma_f32 v150, v14, v14, v150
	v_fma_f32 v154, v15, v15, v154
	v_add_f32_e32 v138, v138, v149
	v_add_f32_e32 v150, v150, v154
	v_add_f32_e32 v138, v138, v150
	s_nop 1
	v_add_f32_dpp v138, v138, v138 quad_perm:[1,0,3,2] row_mask:0xf bank_mask:0xf
	s_nop 1
	v_add_f32_dpp v138, v138, v138 quad_perm:[2,3,0,1] row_mask:0xf bank_mask:0xf
	s_nop 1
	v_add_f32_dpp v138, v138, v138 row_half_mirror row_mask:0xf bank_mask:0xf
	s_nop 1
	v_add_f32_dpp v138, v138, v138 row_mirror row_mask:0xf bank_mask:0xf
	v_mov_b32_e32 v139, v138
	s_nop 1
	v_permlane16_swap_b32_e32 v138, v139
	v_add_f32_e32 v138, v138, v139
	v_mov_b32_e32 v139, v138
	s_nop 1
	v_permlane32_swap_b32_e32 v138, v139
	v_add_f32_e32 v138, v138, v139
	v_mul_f32_e32 v138, 0x3a800000, v138
	v_add_f32_e32 v138, 0x358637bd, v138
	v_rsq_f32_e32 v140, v138
	s_nop 0
	v_mul_f32_e32 v120, v0, v140
	v_mul_f32_e32 v121, v1, v140
	v_mul_f32_e32 v122, v2, v140
	v_mul_f32_e32 v123, v3, v140
	v_mul_f32_e32 v124, v4, v140
	v_mul_f32_e32 v125, v5, v140
	v_mul_f32_e32 v126, v6, v140
	v_mul_f32_e32 v127, v7, v140
	v_mul_f32_e32 v128, v8, v140
	v_mul_f32_e32 v129, v9, v140
	v_mul_f32_e32 v130, v10, v140
	v_mul_f32_e32 v131, v11, v140
	v_mul_f32_e32 v132, v12, v140
	v_mul_f32_e32 v133, v13, v140
	v_mul_f32_e32 v134, v14, v140
	v_mul_f32_e32 v135, v15, v140
	v_fma_f32 v120, v120, v88, v104
	v_fma_f32 v121, v121, v89, v105
	v_fma_f32 v122, v122, v90, v106
	v_fma_f32 v123, v123, v91, v107
	v_fma_f32 v124, v124, v92, v108
	v_fma_f32 v125, v125, v93, v109
	v_fma_f32 v126, v126, v94, v110
	v_fma_f32 v127, v127, v95, v111
	v_fma_f32 v128, v128, v96, v112
	v_fma_f32 v129, v129, v97, v113
	v_fma_f32 v130, v130, v98, v114
	v_fma_f32 v131, v131, v99, v115
	v_fma_f32 v132, v132, v100, v116
	v_fma_f32 v133, v133, v101, v117
	v_fma_f32 v134, v134, v102, v118
	v_fma_f32 v135, v135, v103, v119
	v_cvt_pk_bf16_f32 v156, v120, v121
	v_cvt_pk_bf16_f32 v157, v122, v123
	v_cvt_pk_bf16_f32 v158, v124, v125
	v_cvt_pk_bf16_f32 v159, v126, v127
	v_cvt_pk_bf16_f32 v160, v128, v129
	v_cvt_pk_bf16_f32 v161, v130, v131
	v_cvt_pk_bf16_f32 v162, v132, v133
	v_cvt_pk_bf16_f32 v163, v134, v135
	s_lshl_b32 vcc_lo, s19, 11
	s_add_u32 vcc_lo, vcc_lo, 0x1800000
	s_add_u32 s100, s14, vcc_lo
	s_addc_u32 s101, s15, 0
	global_store_dwordx2 v137, v[156:157], s[100:101] offset:0
	global_store_dwordx2 v137, v[158:159], s[100:101] offset:512
	global_store_dwordx2 v137, v[160:161], s[100:101] offset:1024
	global_store_dwordx2 v137, v[162:163], s[100:101] offset:1536
	s_lshl_b32 vcc_lo, s19, 11
	s_add_u32 vcc_lo, vcc_lo, 0x2400000
	s_add_u32 s100, s12, vcc_lo
	s_addc_u32 s101, s13, 0
	global_load_dwordx2 v[8:9], v137, s[100:101] offset:0
	global_load_dwordx2 v[10:11], v137, s[100:101] offset:512
	global_load_dwordx2 v[12:13], v137, s[100:101] offset:1024
	global_load_dwordx2 v[14:15], v137, s[100:101] offset:1536
	s_lshl_b32 vcc_lo, s19, 11
	s_add_u32 vcc_lo, vcc_lo, 0x2400000
	s_add_u32 s100, s14, vcc_lo
	s_addc_u32 s101, s15, 0
	global_load_dwordx2 v[48:49], v137, s[100:101] offset:0
	global_load_dwordx2 v[50:51], v137, s[100:101] offset:512
	global_load_dwordx2 v[52:53], v137, s[100:101] offset:1024
	global_load_dwordx2 v[54:55], v137, s[100:101] offset:1536
	s_waitcnt vmcnt(32)
; __device__ __forceinline__ void row_phase(const Params& P, int glayer, int layer, int xsrc, bool hasY, int gate_idx, const float* gpost,
;                           int xdst, bool doH, const float* gpre, int sh_idx, int nrows) {
;     ...
;         if (hasY) {
;           float4 yv[4];
;           float ss = 0.f;
; #pragma unroll
;           for (int i = 0; i < 4; ++i) {
;             const uint2 raw = yy[u][i];
;             yv[i].x = bf2f((u16)(raw.x & 0xffff)); yv[i].y = bf2f((u16)(raw.x >> 16));
;             yv[i].z = bf2f((u16)(raw.y & 0xffff)); yv[i].w = bf2f((u16)(raw.y >> 16));
;             ss += yv[i].x * yv[i].x + yv[i].y * yv[i].y + yv[i].z * yv[i].z + yv[i].w * yv[i].w;
;           }
;           ss = wave_sum(ss);
;           const float rstd = __builtin_amdgcn_rsqf(ss * (1.f / 1024.f) + EPSF);
; #pragma unroll
;           for (int i = 0; i < 4; ++i) {
;             const int col = (i * 64 + lane) * 4;
;             const float4 gt = *reinterpret_cast<const float4*>(modg + gate_idx * 1024 + col);
;             const float4 gp = *reinterpret_cast<const float4*>(gpost + col);
;             xv[i].x += gt.x * (yv[i].x * rstd * gp.x); xv[i].y += gt.y * (yv[i].y * rstd * gp.y);
;             xv[i].z += gt.z * (yv[i].z * rstd * gp.z); xv[i].w += gt.w * (yv[i].w * rstd * gp.w);
;           }
;         }
;         if (xdst == 3 || (xdst == 1 && row >= N_X)) {
;           float* xout = (xdst == 3) ? P.out + (long)row * 1024 : P.xc + (long)(row - N_X) * 1024;
; #pragma unroll
;           for (int i = 0; i < 4; ++i) *reinterpret_cast<float4*>(xout + (i * 64 + lane) * 4) = xv[i];
;         } else if (xdst != 0) {
;           u16* xo = ((xdst == 1) ? resA : P.zf) + (long)row * 1024;
; #pragma unroll
;           for (int i = 0; i < 4; ++i) {
;             const unsigned b0 = f2bf(xv[i].x), b1 = f2bf(xv[i].y), b2 = f2bf(xv[i].z), b3 = f2bf(xv[i].w);
;             *reinterpret_cast<uint2*>(xo + (i * 64 + lane) * 4) = make_uint2(b0 | (b1 << 16), b2 | (b3 << 16));
;           }
;         }
;         if (doH) {
;           float ss = 0.f;
; #pragma unroll
;           for (int i = 0; i < 4; ++i) ss += xv[i].x * xv[i].x + xv[i].y * xv[i].y + xv[i].z * xv[i].z + xv[i].w * xv[i].w;
;           ss = wave_sum(ss);
;           const float rstd = __builtin_amdgcn_rsqf(ss * (1.f / 1024.f) + EPSF);
;           u16* h = P.hy + (long)row * 1024;
; #pragma unroll
	v_lshlrev_b32_e32 v120, 16, v56
	v_and_b32_e32 v121, 0xffff0000, v56
	v_lshlrev_b32_e32 v122, 16, v57
	v_and_b32_e32 v123, 0xffff0000, v57
	v_lshlrev_b32_e32 v124, 16, v58
	v_and_b32_e32 v125, 0xffff0000, v58
	v_lshlrev_b32_e32 v126, 16, v59
	v_and_b32_e32 v127, 0xffff0000, v59
	v_lshlrev_b32_e32 v128, 16, v60
	v_and_b32_e32 v129, 0xffff0000, v60
	v_lshlrev_b32_e32 v130, 16, v61
	v_and_b32_e32 v131, 0xffff0000, v61
	v_lshlrev_b32_e32 v132, 16, v62
	v_and_b32_e32 v133, 0xffff0000, v62
	v_lshlrev_b32_e32 v134, 16, v63
	v_and_b32_e32 v135, 0xffff0000, v63
	v_mul_f32_e32 v138, v120, v120
	v_mul_f32_e32 v149, v121, v121
	v_mul_f32_e32 v150, v122, v122
	v_mul_f32_e32 v154, v123, v123
	v_fma_f32 v138, v124, v124, v138
	v_fma_f32 v149, v125, v125, v149
	v_fma_f32 v150, v126, v126, v150
	v_fma_f32 v154, v127, v127, v154
	v_fma_f32 v138, v128, v128, v138
	v_fma_f32 v149, v129, v129, v149
	v_fma_f32 v150, v130, v130, v150
	v_fma_f32 v154, v131, v131, v154
	v_fma_f32 v138, v132, v132, v138
	v_fma_f32 v149, v133, v133, v149
	v_fma_f32 v150, v134, v134, v150
	v_fma_f32 v154, v135, v135, v154
	v_add_f32_e32 v138, v138, v149
	v_add_f32_e32 v150, v150, v154
	v_add_f32_e32 v138, v138, v150
	s_nop 1
	v_add_f32_dpp v138, v138, v138 quad_perm:[1,0,3,2] row_mask:0xf bank_mask:0xf
	s_nop 1
	v_add_f32_dpp v138, v138, v138 quad_perm:[2,3,0,1] row_mask:0xf bank_mask:0xf
	s_nop 1
	v_add_f32_dpp v138, v138, v138 row_half_mirror row_mask:0xf bank_mask:0xf
	s_nop 1
	v_add_f32_dpp v138, v138, v138 row_mirror row_mask:0xf bank_mask:0xf
	v_mov_b32_e32 v139, v138
	s_nop 1
	v_permlane16_swap_b32_e32 v138, v139
	v_add_f32_e32 v138, v138, v139
	v_mov_b32_e32 v139, v138
	s_nop 1
	v_permlane32_swap_b32_e32 v138, v139
	v_add_f32_e32 v138, v138, v139
	v_mul_f32_e32 v138, 0x3a800000, v138
	v_add_f32_e32 v138, 0x358637bd, v138
	v_rsq_f32_e32 v140, v138
	v_lshlrev_b32_e32 v16, 16, v24
	v_and_b32_e32 v17, 0xffff0000, v24
	v_lshlrev_b32_e32 v18, 16, v25
	v_and_b32_e32 v19, 0xffff0000, v25
	v_lshlrev_b32_e32 v20, 16, v26
	v_and_b32_e32 v21, 0xffff0000, v26
	v_lshlrev_b32_e32 v22, 16, v27
	v_and_b32_e32 v23, 0xffff0000, v27
	v_lshlrev_b32_e32 v24, 16, v28
	v_and_b32_e32 v25, 0xffff0000, v28
	v_lshlrev_b32_e32 v26, 16, v29
	v_and_b32_e32 v27, 0xffff0000, v29
	v_lshlrev_b32_e32 v28, 16, v30
	v_and_b32_e32 v29, 0xffff0000, v30
	v_lshlrev_b32_e32 v30, 16, v31
	v_and_b32_e32 v31, 0xffff0000, v31
	s_nop 0
	v_mul_f32_e32 v120, v120, v140
	v_mul_f32_e32 v121, v121, v140
	v_mul_f32_e32 v122, v122, v140
	v_mul_f32_e32 v123, v123, v140
	v_mul_f32_e32 v124, v124, v140
	v_mul_f32_e32 v125, v125, v140
	v_mul_f32_e32 v126, v126, v140
	v_mul_f32_e32 v127, v127, v140
	v_mul_f32_e32 v128, v128, v140
	v_mul_f32_e32 v129, v129, v140
	v_mul_f32_e32 v130, v130, v140
	v_mul_f32_e32 v131, v131, v140
	v_mul_f32_e32 v132, v132, v140
	v_mul_f32_e32 v133, v133, v140
	v_mul_f32_e32 v134, v134, v140
	v_mul_f32_e32 v135, v135, v140
	v_fma_f32 v16, v120, v72, v16
	v_fma_f32 v17, v121, v73, v17
	v_fma_f32 v18, v122, v74, v18
	v_fma_f32 v19, v123, v75, v19
	v_fma_f32 v20, v124, v76, v20
	v_fma_f32 v21, v125, v77, v21
	v_fma_f32 v22, v126, v78, v22
	v_fma_f32 v23, v127, v79, v23
	v_fma_f32 v24, v128, v80, v24
	v_fma_f32 v25, v129, v81, v25
	v_fma_f32 v26, v130, v82, v26
	v_fma_f32 v27, v131, v83, v27
	v_fma_f32 v28, v132, v84, v28
	v_fma_f32 v29, v133, v85, v29
	v_fma_f32 v30, v134, v86, v30
	v_fma_f32 v31, v135, v87, v31
	v_cvt_pk_bf16_f32 v156, v16, v17
	v_cvt_pk_bf16_f32 v157, v18, v19
	v_cvt_pk_bf16_f32 v158, v20, v21
	v_cvt_pk_bf16_f32 v159, v22, v23
	v_cvt_pk_bf16_f32 v160, v24, v25
	v_cvt_pk_bf16_f32 v161, v26, v27
	v_cvt_pk_bf16_f32 v162, v28, v29
	v_cvt_pk_bf16_f32 v163, v30, v31
	s_lshl_b32 vcc_lo, s19, 11
	s_add_u32 vcc_lo, vcc_lo, 0x1c00000
	s_add_u32 s100, s16, vcc_lo
	s_addc_u32 s101, s17, 0
	global_store_dwordx2 v137, v[156:157], s[100:101] offset:0
	global_store_dwordx2 v137, v[158:159], s[100:101] offset:512
	global_store_dwordx2 v137, v[160:161], s[100:101] offset:1024
	global_store_dwordx2 v137, v[162:163], s[100:101] offset:1536
	v_mul_f32_e32 v138, v16, v16
	v_mul_f32_e32 v149, v17, v17
	v_mul_f32_e32 v150, v18, v18
	v_mul_f32_e32 v154, v19, v19
	v_fma_f32 v138, v20, v20, v138
	v_fma_f32 v149, v21, v21, v149
	v_fma_f32 v150, v22, v22, v150
	v_fma_f32 v154, v23, v23, v154
	v_fma_f32 v138, v24, v24, v138
	v_fma_f32 v149, v25, v25, v149
	v_fma_f32 v150, v26, v26, v150
	v_fma_f32 v154, v27, v27, v154
	v_fma_f32 v138, v28, v28, v138
	v_fma_f32 v149, v29, v29, v149
	v_fma_f32 v150, v30, v30, v150
	v_fma_f32 v154, v31, v31, v154
	v_add_f32_e32 v138, v138, v149
	v_add_f32_e32 v150, v150, v154
	v_add_f32_e32 v138, v138, v150
	s_nop 1
	v_add_f32_dpp v138, v138, v138 quad_perm:[1,0,3,2] row_mask:0xf bank_mask:0xf
	s_nop 1
	v_add_f32_dpp v138, v138, v138 quad_perm:[2,3,0,1] row_mask:0xf bank_mask:0xf
	s_nop 1
	v_add_f32_dpp v138, v138, v138 row_half_mirror row_mask:0xf bank_mask:0xf
	s_nop 1
	v_add_f32_dpp v138, v138, v138 row_mirror row_mask:0xf bank_mask:0xf
	v_mov_b32_e32 v139, v138
	s_nop 1
	v_permlane16_swap_b32_e32 v138, v139
	v_add_f32_e32 v138, v138, v139
	v_mov_b32_e32 v139, v138
	s_nop 1
	v_permlane32_swap_b32_e32 v138, v139
	v_add_f32_e32 v138, v138, v139
	v_mul_f32_e32 v138, 0x3a800000, v138
	v_add_f32_e32 v138, 0x358637bd, v138
	v_rsq_f32_e32 v140, v138
	s_nop 0
	v_mul_f32_e32 v120, v16, v140
	v_mul_f32_e32 v121, v17, v140
	v_mul_f32_e32 v122, v18, v140
	v_mul_f32_e32 v123, v19, v140
	v_mul_f32_e32 v124, v20, v140
	v_mul_f32_e32 v125, v21, v140
	v_mul_f32_e32 v126, v22, v140
	v_mul_f32_e32 v127, v23, v140
	v_mul_f32_e32 v128, v24, v140
	v_mul_f32_e32 v129, v25, v140
	v_mul_f32_e32 v130, v26, v140
; __device__ __forceinline__ float bf2f(u16 h) { return __uint_as_float(((unsigned)h) << 16); }
; __device__ __forceinline__ void row_phase(const Params& P, int glayer, int layer, int xsrc, bool hasY, int gate_idx, const float* gpost,
;                           int xdst, bool doH, const float* gpre, int sh_idx, int nrows) {
;     ...
;         const int mi = row < N_X ? (row >> 13) : 4;
;         const float* modp = P.mod + (long)(layer * 5 + mi) * 6144;
;         const float* modg = P.mod + (long)(glayer * 5 + mi) * 6144;
;         float4 xv[4];
;         if (xsrc != 0 && row < N_X) {
; #pragma unroll
;           for (int i = 0; i < 4; ++i) {
;             const uint4 raw = xr[u][i];
;             xv[i].x = bf2f((u16)(raw.x & 0xffff)); xv[i].y = bf2f((u16)(raw.x >> 16));
;             xv[i].z = bf2f((u16)(raw.y & 0xffff)); xv[i].w = bf2f((u16)(raw.y >> 16));
;           }
;         } else {
; #pragma unroll
;           for (int i = 0; i < 4; ++i) {
;             xv[i].x = __uint_as_float(xr[u][i].x); xv[i].y = __uint_as_float(xr[u][i].y);
;             xv[i].z = __uint_as_float(xr[u][i].z); xv[i].w = __uint_as_float(xr[u][i].w);
;           }
;         }
;         if (hasY) {
;           float4 yv[4];
;           float ss = 0.f;
; #pragma unroll
;           for (int i = 0; i < 4; ++i) {
;             const uint2 raw = yy[u][i];
;             yv[i].x = bf2f((u16)(raw.x & 0xffff)); yv[i].y = bf2f((u16)(raw.x >> 16));
;             yv[i].z = bf2f((u16)(raw.y & 0xffff)); yv[i].w = bf2f((u16)(raw.y >> 16));
;             ss += yv[i].x * yv[i].x + yv[i].y * yv[i].y + yv[i].z * yv[i].z + yv[i].w * yv[i].w;
;           }
;           ss = wave_sum(ss);
;           const float rstd = __builtin_amdgcn_rsqf(ss * (1.f / 1024.f) + EPSF);
; #pragma unroll
;           for (int i = 0; i < 4; ++i) {
;             const int col = (i * 64 + lane) * 4;
;             const float4 gt = *reinterpret_cast<const float4*>(modg + gate_idx * 1024 + col);
;             const float4 gp = *reinterpret_cast<const float4*>(gpost + col);
;             xv[i].x += gt.x * (yv[i].x * rstd * gp.x); xv[i].y += gt.y * (yv[i].y * rstd * gp.y);
;             xv[i].z += gt.z * (yv[i].z * rstd * gp.z); xv[i].w += gt.w * (yv[i].w * rstd * gp.w);
;           }
;         }
	v_mul_f32_e32 v131, v27, v140
	v_mul_f32_e32 v132, v28, v140
	v_mul_f32_e32 v133, v29, v140
	v_mul_f32_e32 v134, v30, v140
	v_mul_f32_e32 v135, v31, v140
	v_fma_f32 v120, v120, v88, v104
	v_fma_f32 v121, v121, v89, v105
	v_fma_f32 v122, v122, v90, v106
	v_fma_f32 v123, v123, v91, v107
	v_fma_f32 v124, v124, v92, v108
	v_fma_f32 v125, v125, v93, v109
	v_fma_f32 v126, v126, v94, v110
	v_fma_f32 v127, v127, v95, v111
	v_fma_f32 v128, v128, v96, v112
	v_fma_f32 v129, v129, v97, v113
	v_fma_f32 v130, v130, v98, v114
	v_fma_f32 v131, v131, v99, v115
	v_fma_f32 v132, v132, v100, v116
	v_fma_f32 v133, v133, v101, v117
	v_fma_f32 v134, v134, v102, v118
	v_fma_f32 v135, v135, v103, v119
	v_cvt_pk_bf16_f32 v156, v120, v121
	v_cvt_pk_bf16_f32 v157, v122, v123
	v_cvt_pk_bf16_f32 v158, v124, v125
	v_cvt_pk_bf16_f32 v159, v126, v127
	v_cvt_pk_bf16_f32 v160, v128, v129
	v_cvt_pk_bf16_f32 v161, v130, v131
	v_cvt_pk_bf16_f32 v162, v132, v133
	v_cvt_pk_bf16_f32 v163, v134, v135
	s_lshl_b32 vcc_lo, s19, 11
	s_add_u32 vcc_lo, vcc_lo, 0x1c00000
	s_add_u32 s100, s14, vcc_lo
	s_addc_u32 s101, s15, 0
	global_store_dwordx2 v137, v[156:157], s[100:101] offset:0
	global_store_dwordx2 v137, v[158:159], s[100:101] offset:512
	global_store_dwordx2 v137, v[160:161], s[100:101] offset:1024
	global_store_dwordx2 v137, v[162:163], s[100:101] offset:1536
	s_add_u32 s100, s20, 0x11000
	s_addc_u32 s101, s21, 0
	global_load_dwordx4 v[72:75], v136, s[100:101] offset:0
	global_load_dwordx4 v[76:79], v136, s[100:101] offset:1024
	global_load_dwordx4 v[80:83], v136, s[100:101] offset:2048
	global_load_dwordx4 v[84:87], v136, s[100:101] offset:3072
	s_load_dwordx2 s[98:99], s[4:5], 0x48
	s_waitcnt lgkmcnt(0)
	global_load_dwordx4 v[120:123], v136, s[98:99] offset:0
	global_load_dwordx4 v[124:127], v136, s[98:99] offset:1024
	global_load_dwordx4 v[128:131], v136, s[98:99] offset:2048
	global_load_dwordx4 v[132:135], v136, s[98:99] offset:3072
	s_add_u32 s100, s20, 0x2a000
	s_addc_u32 s101, s21, 0
	global_load_dwordx4 v[104:107], v136, s[100:101] offset:0
	global_load_dwordx4 v[108:111], v136, s[100:101] offset:1024
	global_load_dwordx4 v[112:115], v136, s[100:101] offset:2048
	global_load_dwordx4 v[116:119], v136, s[100:101] offset:3072
	s_add_u32 s100, s100, 0x1000
	s_addc_u32 s101, s101, 0
	global_load_dwordx4 v[16:19], v136, s[100:101] offset:0
	global_load_dwordx4 v[20:23], v136, s[100:101] offset:1024
	global_load_dwordx4 v[24:27], v136, s[100:101] offset:2048
	global_load_dwordx4 v[28:31], v136, s[100:101] offset:3072
	s_load_dwordx2 s[98:99], s[4:5], 0x30
	s_waitcnt lgkmcnt(0)
	s_add_u32 s98, s98, 0x1000
	s_addc_u32 s99, s99, 0
	global_load_dwordx4 v[88:91], v136, s[98:99] offset:0
	global_load_dwordx4 v[92:95], v136, s[98:99] offset:1024
	global_load_dwordx4 v[96:99], v136, s[98:99] offset:2048
	global_load_dwordx4 v[100:103], v136, s[98:99] offset:3072
	s_waitcnt vmcnt(0)
	v_mul_f32_e32 v72, v72, v120
	v_mul_f32_e32 v73, v73, v121
	v_mul_f32_e32 v74, v74, v122
	v_mul_f32_e32 v75, v75, v123
	v_mul_f32_e32 v76, v76, v124
	v_mul_f32_e32 v77, v77, v125
	v_mul_f32_e32 v78, v78, v126
	v_mul_f32_e32 v79, v79, v127
	v_mul_f32_e32 v80, v80, v128
	v_mul_f32_e32 v81, v81, v129
	v_mul_f32_e32 v82, v82, v130
	v_mul_f32_e32 v83, v83, v131
	v_mul_f32_e32 v84, v84, v132
	v_mul_f32_e32 v85, v85, v133
	v_mul_f32_e32 v86, v86, v134
	v_mul_f32_e32 v87, v87, v135
	v_fma_f32 v88, v88, v16, v88
	v_fma_f32 v89, v89, v17, v89
	v_fma_f32 v90, v90, v18, v90
	v_fma_f32 v91, v91, v19, v91
	v_fma_f32 v92, v92, v20, v92
	v_fma_f32 v93, v93, v21, v93
	v_fma_f32 v94, v94, v22, v94
	v_fma_f32 v95, v95, v23, v95
	v_fma_f32 v96, v96, v24, v96
	v_fma_f32 v97, v97, v25, v97
	v_fma_f32 v98, v98, v26, v98
	v_fma_f32 v99, v99, v27, v99
	v_fma_f32 v100, v100, v28, v100
	v_fma_f32 v101, v101, v29, v101
	v_fma_f32 v102, v102, v30, v102
	v_fma_f32 v103, v103, v31, v103
	s_lshl_b32 vcc_lo, s19, 11
	s_add_u32 vcc_lo, vcc_lo, 0x2800000
	s_add_u32 s100, s12, vcc_lo
	s_addc_u32 s101, s13, 0
	global_load_dwordx2 v[24:25], v137, s[100:101] offset:0
	global_load_dwordx2 v[26:27], v137, s[100:101] offset:512
	global_load_dwordx2 v[28:29], v137, s[100:101] offset:1024
	global_load_dwordx2 v[30:31], v137, s[100:101] offset:1536
	s_lshl_b32 vcc_lo, s19, 11
	s_add_u32 vcc_lo, vcc_lo, 0x2800000
	s_add_u32 s100, s14, vcc_lo
	s_addc_u32 s101, s15, 0
	global_load_dwordx2 v[56:57], v137, s[100:101] offset:0
	global_load_dwordx2 v[58:59], v137, s[100:101] offset:512
	global_load_dwordx2 v[60:61], v137, s[100:101] offset:1024
	global_load_dwordx2 v[62:63], v137, s[100:101] offset:1536
	v_lshlrev_b32_e32 v120, 16, v64
	v_and_b32_e32 v121, 0xffff0000, v64
	v_lshlrev_b32_e32 v122, 16, v65
	v_and_b32_e32 v123, 0xffff0000, v65
	v_lshlrev_b32_e32 v124, 16, v66
	v_and_b32_e32 v125, 0xffff0000, v66
	v_lshlrev_b32_e32 v126, 16, v67
	v_and_b32_e32 v127, 0xffff0000, v67
	v_lshlrev_b32_e32 v128, 16, v68
	v_and_b32_e32 v129, 0xffff0000, v68
	v_lshlrev_b32_e32 v130, 16, v69
	v_and_b32_e32 v131, 0xffff0000, v69
	v_lshlrev_b32_e32 v132, 16, v70
	v_and_b32_e32 v133, 0xffff0000, v70
	v_lshlrev_b32_e32 v134, 16, v71
	v_and_b32_e32 v135, 0xffff0000, v71
	v_mul_f32_e32 v138, v120, v120
	v_mul_f32_e32 v149, v121, v121
	v_mul_f32_e32 v150, v122, v122
	v_mul_f32_e32 v154, v123, v123
	v_fma_f32 v138, v124, v124, v138
	v_fma_f32 v149, v125, v125, v149
	v_fma_f32 v150, v126, v126, v150
	v_fma_f32 v154, v127, v127, v154
	v_fma_f32 v138, v128, v128, v138
	v_fma_f32 v149, v129, v129, v149
	v_fma_f32 v150, v130, v130, v150
	v_fma_f32 v154, v131, v131, v154
	v_fma_f32 v138, v132, v132, v138
	v_fma_f32 v149, v133, v133, v149
	v_fma_f32 v150, v134, v134, v150
; __device__ __forceinline__ void row_phase(const Params& P, int glayer, int layer, int xsrc, bool hasY, int gate_idx, const float* gpost,
;                           int xdst, bool doH, const float* gpre, int sh_idx, int nrows) {
;     ...
;         if (hasY) {
;           float4 yv[4];
;           float ss = 0.f;
; #pragma unroll
;           for (int i = 0; i < 4; ++i) {
;             const uint2 raw = yy[u][i];
;             yv[i].x = bf2f((u16)(raw.x & 0xffff)); yv[i].y = bf2f((u16)(raw.x >> 16));
;             yv[i].z = bf2f((u16)(raw.y & 0xffff)); yv[i].w = bf2f((u16)(raw.y >> 16));
;             ss += yv[i].x * yv[i].x + yv[i].y * yv[i].y + yv[i].z * yv[i].z + yv[i].w * yv[i].w;
;           }
;           ss = wave_sum(ss);
;           const float rstd = __builtin_amdgcn_rsqf(ss * (1.f / 1024.f) + EPSF);
; #pragma unroll
;           for (int i = 0; i < 4; ++i) {
;             const int col = (i * 64 + lane) * 4;
;             const float4 gt = *reinterpret_cast<const float4*>(modg + gate_idx * 1024 + col);
;             const float4 gp = *reinterpret_cast<const float4*>(gpost + col);
;             xv[i].x += gt.x * (yv[i].x * rstd * gp.x); xv[i].y += gt.y * (yv[i].y * rstd * gp.y);
;             xv[i].z += gt.z * (yv[i].z * rstd * gp.z); xv[i].w += gt.w * (yv[i].w * rstd * gp.w);
;           }
;         }
;         if (xdst == 3 || (xdst == 1 && row >= N_X)) {
;           float* xout = (xdst == 3) ? P.out + (long)row * 1024 : P.xc + (long)(row - N_X) * 1024;
; #pragma unroll
;           for (int i = 0; i < 4; ++i) *reinterpret_cast<float4*>(xout + (i * 64 + lane) * 4) = xv[i];
;         } else if (xdst != 0) {
;           u16* xo = ((xdst == 1) ? resA : P.zf) + (long)row * 1024;
; #pragma unroll
;           for (int i = 0; i < 4; ++i) {
;             const unsigned b0 = f2bf(xv[i].x), b1 = f2bf(xv[i].y), b2 = f2bf(xv[i].z), b3 = f2bf(xv[i].w);
;             *reinterpret_cast<uint2*>(xo + (i * 64 + lane) * 4) = make_uint2(b0 | (b1 << 16), b2 | (b3 << 16));
;           }
;         }
;         if (doH) {
;           float ss = 0.f;
; #pragma unroll
;           for (int i = 0; i < 4; ++i) ss += xv[i].x * xv[i].x + xv[i].y * xv[i].y + xv[i].z * xv[i].z + xv[i].w * xv[i].w;
;           ss = wave_sum(ss);
;           const float rstd = __builtin_amdgcn_rsqf(ss * (1.f / 1024.f) + EPSF);
;           u16* h = P.hy + (long)row * 1024;
; #pragma unroll
	v_fma_f32 v154, v135, v135, v154
	v_add_f32_e32 v138, v138, v149
	v_add_f32_e32 v150, v150, v154
	v_add_f32_e32 v138, v138, v150
	s_nop 1
	v_add_f32_dpp v138, v138, v138 quad_perm:[1,0,3,2] row_mask:0xf bank_mask:0xf
	s_nop 1
	v_add_f32_dpp v138, v138, v138 quad_perm:[2,3,0,1] row_mask:0xf bank_mask:0xf
	s_nop 1
	v_add_f32_dpp v138, v138, v138 row_half_mirror row_mask:0xf bank_mask:0xf
	s_nop 1
	v_add_f32_dpp v138, v138, v138 row_mirror row_mask:0xf bank_mask:0xf
	v_mov_b32_e32 v139, v138
	s_nop 1
	v_permlane16_swap_b32_e32 v138, v139
	v_add_f32_e32 v138, v138, v139
	v_mov_b32_e32 v139, v138
	s_nop 1
	v_permlane32_swap_b32_e32 v138, v139
	v_add_f32_e32 v138, v138, v139
	v_mul_f32_e32 v138, 0x3a800000, v138
	v_add_f32_e32 v138, 0x358637bd, v138
	v_rsq_f32_e32 v140, v138
	v_lshlrev_b32_e32 v32, 16, v40
	v_and_b32_e32 v33, 0xffff0000, v40
	v_lshlrev_b32_e32 v34, 16, v41
	v_and_b32_e32 v35, 0xffff0000, v41
	v_lshlrev_b32_e32 v36, 16, v42
	v_and_b32_e32 v37, 0xffff0000, v42
	v_lshlrev_b32_e32 v38, 16, v43
	v_and_b32_e32 v39, 0xffff0000, v43
	v_lshlrev_b32_e32 v40, 16, v44
	v_and_b32_e32 v41, 0xffff0000, v44
	v_lshlrev_b32_e32 v42, 16, v45
	v_and_b32_e32 v43, 0xffff0000, v45
	v_lshlrev_b32_e32 v44, 16, v46
	v_and_b32_e32 v45, 0xffff0000, v46
	v_lshlrev_b32_e32 v46, 16, v47
	v_and_b32_e32 v47, 0xffff0000, v47
	s_nop 0
	v_mul_f32_e32 v120, v120, v140
	v_mul_f32_e32 v121, v121, v140
	v_mul_f32_e32 v122, v122, v140
	v_mul_f32_e32 v123, v123, v140
	v_mul_f32_e32 v124, v124, v140
	v_mul_f32_e32 v125, v125, v140
	v_mul_f32_e32 v126, v126, v140
	v_mul_f32_e32 v127, v127, v140
	v_mul_f32_e32 v128, v128, v140
	v_mul_f32_e32 v129, v129, v140
	v_mul_f32_e32 v130, v130, v140
	v_mul_f32_e32 v131, v131, v140
	v_mul_f32_e32 v132, v132, v140
	v_mul_f32_e32 v133, v133, v140
	v_mul_f32_e32 v134, v134, v140
	v_mul_f32_e32 v135, v135, v140
	v_fma_f32 v32, v120, v72, v32
	v_fma_f32 v33, v121, v73, v33
	v_fma_f32 v34, v122, v74, v34
	v_fma_f32 v35, v123, v75, v35
	v_fma_f32 v36, v124, v76, v36
	v_fma_f32 v37, v125, v77, v37
	v_fma_f32 v38, v126, v78, v38
	v_fma_f32 v39, v127, v79, v39
	v_fma_f32 v40, v128, v80, v40
	v_fma_f32 v41, v129, v81, v41
	v_fma_f32 v42, v130, v82, v42
	v_fma_f32 v43, v131, v83, v43
	v_fma_f32 v44, v132, v84, v44
	v_fma_f32 v45, v133, v85, v45
	v_fma_f32 v46, v134, v86, v46
	v_fma_f32 v47, v135, v87, v47
	v_cvt_pk_bf16_f32 v156, v32, v33
	v_cvt_pk_bf16_f32 v157, v34, v35
	v_cvt_pk_bf16_f32 v158, v36, v37
	v_cvt_pk_bf16_f32 v159, v38, v39
	v_cvt_pk_bf16_f32 v160, v40, v41
	v_cvt_pk_bf16_f32 v161, v42, v43
	v_cvt_pk_bf16_f32 v162, v44, v45
	v_cvt_pk_bf16_f32 v163, v46, v47
	s_lshl_b32 vcc_lo, s19, 11
	s_add_u32 vcc_lo, vcc_lo, 0x2000000
	s_add_u32 s100, s16, vcc_lo
	s_addc_u32 s101, s17, 0
	global_store_dwordx2 v137, v[156:157], s[100:101] offset:0
	global_store_dwordx2 v137, v[158:159], s[100:101] offset:512
	global_store_dwordx2 v137, v[160:161], s[100:101] offset:1024
	global_store_dwordx2 v137, v[162:163], s[100:101] offset:1536
	v_mul_f32_e32 v138, v32, v32
	v_mul_f32_e32 v149, v33, v33
	v_mul_f32_e32 v150, v34, v34
	v_mul_f32_e32 v154, v35, v35
	v_fma_f32 v138, v36, v36, v138
	v_fma_f32 v149, v37, v37, v149
	v_fma_f32 v150, v38, v38, v150
	v_fma_f32 v154, v39, v39, v154
	v_fma_f32 v138, v40, v40, v138
	v_fma_f32 v149, v41, v41, v149
	v_fma_f32 v150, v42, v42, v150
	v_fma_f32 v154, v43, v43, v154
	v_fma_f32 v138, v44, v44, v138
	v_fma_f32 v149, v45, v45, v149
	v_fma_f32 v150, v46, v46, v150
	v_fma_f32 v154, v47, v47, v154
	v_add_f32_e32 v138, v138, v149
	v_add_f32_e32 v150, v150, v154
	v_add_f32_e32 v138, v138, v150
	s_nop 1
	v_add_f32_dpp v138, v138, v138 quad_perm:[1,0,3,2] row_mask:0xf bank_mask:0xf
	s_nop 1
	v_add_f32_dpp v138, v138, v138 quad_perm:[2,3,0,1] row_mask:0xf bank_mask:0xf
	s_nop 1
	v_add_f32_dpp v138, v138, v138 row_half_mirror row_mask:0xf bank_mask:0xf
	s_nop 1
	v_add_f32_dpp v138, v138, v138 row_mirror row_mask:0xf bank_mask:0xf
	v_mov_b32_e32 v139, v138
	s_nop 1
	v_permlane16_swap_b32_e32 v138, v139
	v_add_f32_e32 v138, v138, v139
	v_mov_b32_e32 v139, v138
	s_nop 1
	v_permlane32_swap_b32_e32 v138, v139
	v_add_f32_e32 v138, v138, v139
	v_mul_f32_e32 v138, 0x3a800000, v138
	v_add_f32_e32 v138, 0x358637bd, v138
	v_rsq_f32_e32 v140, v138
	s_nop 0
	v_mul_f32_e32 v120, v32, v140
	v_mul_f32_e32 v121, v33, v140
	v_mul_f32_e32 v122, v34, v140
	v_mul_f32_e32 v123, v35, v140
	v_mul_f32_e32 v124, v36, v140
	v_mul_f32_e32 v125, v37, v140
	v_mul_f32_e32 v126, v38, v140
	v_mul_f32_e32 v127, v39, v140
	v_mul_f32_e32 v128, v40, v140
	v_mul_f32_e32 v129, v41, v140
	v_mul_f32_e32 v130, v42, v140
	v_mul_f32_e32 v131, v43, v140
	v_mul_f32_e32 v132, v44, v140
	v_mul_f32_e32 v133, v45, v140
	v_mul_f32_e32 v134, v46, v140
	v_mul_f32_e32 v135, v47, v140
	v_fma_f32 v120, v120, v88, v104
	v_fma_f32 v121, v121, v89, v105
	v_fma_f32 v122, v122, v90, v106
	v_fma_f32 v123, v123, v91, v107
	v_fma_f32 v124, v124, v92, v108
	v_fma_f32 v125, v125, v93, v109
	v_fma_f32 v126, v126, v94, v110
	v_fma_f32 v127, v127, v95, v111
	v_fma_f32 v128, v128, v96, v112
	v_fma_f32 v129, v129, v97, v113
	v_fma_f32 v130, v130, v98, v114
	v_fma_f32 v131, v131, v99, v115
	v_fma_f32 v132, v132, v100, v116
	v_fma_f32 v133, v133, v101, v117
	v_fma_f32 v134, v134, v102, v118
	v_fma_f32 v135, v135, v103, v119
	v_cvt_pk_bf16_f32 v156, v120, v121
	v_cvt_pk_bf16_f32 v157, v122, v123
	v_cvt_pk_bf16_f32 v158, v124, v125
	v_cvt_pk_bf16_f32 v159, v126, v127
	v_cvt_pk_bf16_f32 v160, v128, v129
	v_cvt_pk_bf16_f32 v161, v130, v131
	v_cvt_pk_bf16_f32 v162, v132, v133
	v_cvt_pk_bf16_f32 v163, v134, v135
	s_lshl_b32 vcc_lo, s19, 11
	s_add_u32 vcc_lo, vcc_lo, 0x2000000
	s_add_u32 s100, s14, vcc_lo
; __device__ __forceinline__ void row_phase(const Params& P, int glayer, int layer, int xsrc, bool hasY, int gate_idx, const float* gpost,
;                           int xdst, bool doH, const float* gpre, int sh_idx, int nrows) {
;     ...
;         if (hasY) {
;           float4 yv[4];
;           float ss = 0.f;
; #pragma unroll
;           for (int i = 0; i < 4; ++i) {
;             const uint2 raw = yy[u][i];
;             yv[i].x = bf2f((u16)(raw.x & 0xffff)); yv[i].y = bf2f((u16)(raw.x >> 16));
;             yv[i].z = bf2f((u16)(raw.y & 0xffff)); yv[i].w = bf2f((u16)(raw.y >> 16));
;             ss += yv[i].x * yv[i].x + yv[i].y * yv[i].y + yv[i].z * yv[i].z + yv[i].w * yv[i].w;
;           }
;           ss = wave_sum(ss);
;           const float rstd = __builtin_amdgcn_rsqf(ss * (1.f / 1024.f) + EPSF);
; #pragma unroll
;           for (int i = 0; i < 4; ++i) {
;             const int col = (i * 64 + lane) * 4;
;             const float4 gt = *reinterpret_cast<const float4*>(modg + gate_idx * 1024 + col);
;             const float4 gp = *reinterpret_cast<const float4*>(gpost + col);
;             xv[i].x += gt.x * (yv[i].x * rstd * gp.x); xv[i].y += gt.y * (yv[i].y * rstd * gp.y);
;             xv[i].z += gt.z * (yv[i].z * rstd * gp.z); xv[i].w += gt.w * (yv[i].w * rstd * gp.w);
;           }
;         }
;         if (xdst == 3 || (xdst == 1 && row >= N_X)) {
;           float* xout = (xdst == 3) ? P.out + (long)row * 1024 : P.xc + (long)(row - N_X) * 1024;
; #pragma unroll
;           for (int i = 0; i < 4; ++i) *reinterpret_cast<float4*>(xout + (i * 64 + lane) * 4) = xv[i];
;         } else if (xdst != 0) {
;           u16* xo = ((xdst == 1) ? resA : P.zf) + (long)row * 1024;
; #pragma unroll
;           for (int i = 0; i < 4; ++i) {
;             const unsigned b0 = f2bf(xv[i].x), b1 = f2bf(xv[i].y), b2 = f2bf(xv[i].z), b3 = f2bf(xv[i].w);
;             *reinterpret_cast<uint2*>(xo + (i * 64 + lane) * 4) = make_uint2(b0 | (b1 << 16), b2 | (b3 << 16));
;           }
;         }
;         if (doH) {
;           float ss = 0.f;
; #pragma unroll
;           for (int i = 0; i < 4; ++i) ss += xv[i].x * xv[i].x + xv[i].y * xv[i].y + xv[i].z * xv[i].z + xv[i].w * xv[i].w;
;           ss = wave_sum(ss);
;           const float rstd = __builtin_amdgcn_rsqf(ss * (1.f / 1024.f) + EPSF);
;           u16* h = P.hy + (long)row * 1024;
; #pragma unroll
	s_addc_u32 s101, s15, 0
	global_store_dwordx2 v137, v[156:157], s[100:101] offset:0
	global_store_dwordx2 v137, v[158:159], s[100:101] offset:512
	global_store_dwordx2 v137, v[160:161], s[100:101] offset:1024
	global_store_dwordx2 v137, v[162:163], s[100:101] offset:1536
	s_lshl_b32 vcc_lo, s19, 11
	s_add_u32 vcc_lo, vcc_lo, 0x2c00000
	s_add_u32 s100, s12, vcc_lo
	s_addc_u32 s101, s13, 0
	global_load_dwordx2 v[40:41], v137, s[100:101] offset:0
	global_load_dwordx2 v[42:43], v137, s[100:101] offset:512
	global_load_dwordx2 v[44:45], v137, s[100:101] offset:1024
	global_load_dwordx2 v[46:47], v137, s[100:101] offset:1536
	s_lshl_b32 vcc_lo, s19, 11
	s_add_u32 vcc_lo, vcc_lo, 0x2c00000
	s_add_u32 s100, s14, vcc_lo
	s_addc_u32 s101, s15, 0
	global_load_dwordx2 v[64:65], v137, s[100:101] offset:0
	global_load_dwordx2 v[66:67], v137, s[100:101] offset:512
	global_load_dwordx2 v[68:69], v137, s[100:101] offset:1024
	global_load_dwordx2 v[70:71], v137, s[100:101] offset:1536
	v_lshlrev_b32_e32 v120, 16, v48
	v_and_b32_e32 v121, 0xffff0000, v48
	v_lshlrev_b32_e32 v122, 16, v49
	v_and_b32_e32 v123, 0xffff0000, v49
	v_lshlrev_b32_e32 v124, 16, v50
	v_and_b32_e32 v125, 0xffff0000, v50
	v_lshlrev_b32_e32 v126, 16, v51
	v_and_b32_e32 v127, 0xffff0000, v51
	v_lshlrev_b32_e32 v128, 16, v52
	v_and_b32_e32 v129, 0xffff0000, v52
	v_lshlrev_b32_e32 v130, 16, v53
	v_and_b32_e32 v131, 0xffff0000, v53
	v_lshlrev_b32_e32 v132, 16, v54
	v_and_b32_e32 v133, 0xffff0000, v54
	v_lshlrev_b32_e32 v134, 16, v55
	v_and_b32_e32 v135, 0xffff0000, v55
	v_mul_f32_e32 v138, v120, v120
	v_mul_f32_e32 v149, v121, v121
	v_mul_f32_e32 v150, v122, v122
	v_mul_f32_e32 v154, v123, v123
	v_fma_f32 v138, v124, v124, v138
	v_fma_f32 v149, v125, v125, v149
	v_fma_f32 v150, v126, v126, v150
	v_fma_f32 v154, v127, v127, v154
	v_fma_f32 v138, v128, v128, v138
	v_fma_f32 v149, v129, v129, v149
	v_fma_f32 v150, v130, v130, v150
	v_fma_f32 v154, v131, v131, v154
	v_fma_f32 v138, v132, v132, v138
	v_fma_f32 v149, v133, v133, v149
	v_fma_f32 v150, v134, v134, v150
	v_fma_f32 v154, v135, v135, v154
	v_add_f32_e32 v138, v138, v149
	v_add_f32_e32 v150, v150, v154
	v_add_f32_e32 v138, v138, v150
	s_nop 1
	v_add_f32_dpp v138, v138, v138 quad_perm:[1,0,3,2] row_mask:0xf bank_mask:0xf
	s_nop 1
	v_add_f32_dpp v138, v138, v138 quad_perm:[2,3,0,1] row_mask:0xf bank_mask:0xf
	s_nop 1
	v_add_f32_dpp v138, v138, v138 row_half_mirror row_mask:0xf bank_mask:0xf
	s_nop 1
	v_add_f32_dpp v138, v138, v138 row_mirror row_mask:0xf bank_mask:0xf
	v_mov_b32_e32 v139, v138
	s_nop 1
	v_permlane16_swap_b32_e32 v138, v139
	v_add_f32_e32 v138, v138, v139
	v_mov_b32_e32 v139, v138
	s_nop 1
	v_permlane32_swap_b32_e32 v138, v139
	v_add_f32_e32 v138, v138, v139
	v_mul_f32_e32 v138, 0x3a800000, v138
	v_add_f32_e32 v138, 0x358637bd, v138
	v_rsq_f32_e32 v140, v138
	v_lshlrev_b32_e32 v0, 16, v8
	v_and_b32_e32 v1, 0xffff0000, v8
	v_lshlrev_b32_e32 v2, 16, v9
	v_and_b32_e32 v3, 0xffff0000, v9
	v_lshlrev_b32_e32 v4, 16, v10
	v_and_b32_e32 v5, 0xffff0000, v10
	v_lshlrev_b32_e32 v6, 16, v11
	v_and_b32_e32 v7, 0xffff0000, v11
	v_lshlrev_b32_e32 v8, 16, v12
	v_and_b32_e32 v9, 0xffff0000, v12
	v_lshlrev_b32_e32 v10, 16, v13
	v_and_b32_e32 v11, 0xffff0000, v13
	v_lshlrev_b32_e32 v12, 16, v14
	v_and_b32_e32 v13, 0xffff0000, v14
	v_lshlrev_b32_e32 v14, 16, v15
	v_and_b32_e32 v15, 0xffff0000, v15
	s_nop 0
	v_mul_f32_e32 v120, v120, v140
	v_mul_f32_e32 v121, v121, v140
	v_mul_f32_e32 v122, v122, v140
	v_mul_f32_e32 v123, v123, v140
	v_mul_f32_e32 v124, v124, v140
	v_mul_f32_e32 v125, v125, v140
	v_mul_f32_e32 v126, v126, v140
	v_mul_f32_e32 v127, v127, v140
	v_mul_f32_e32 v128, v128, v140
	v_mul_f32_e32 v129, v129, v140
	v_mul_f32_e32 v130, v130, v140
	v_mul_f32_e32 v131, v131, v140
	v_mul_f32_e32 v132, v132, v140
	v_mul_f32_e32 v133, v133, v140
	v_mul_f32_e32 v134, v134, v140
	v_mul_f32_e32 v135, v135, v140
	v_fma_f32 v0, v120, v72, v0
	v_fma_f32 v1, v121, v73, v1
	v_fma_f32 v2, v122, v74, v2
	v_fma_f32 v3, v123, v75, v3
	v_fma_f32 v4, v124, v76, v4
	v_fma_f32 v5, v125, v77, v5
	v_fma_f32 v6, v126, v78, v6
	v_fma_f32 v7, v127, v79, v7
	v_fma_f32 v8, v128, v80, v8
	v_fma_f32 v9, v129, v81, v9
	v_fma_f32 v10, v130, v82, v10
	v_fma_f32 v11, v131, v83, v11
	v_fma_f32 v12, v132, v84, v12
	v_fma_f32 v13, v133, v85, v13
	v_fma_f32 v14, v134, v86, v14
	v_fma_f32 v15, v135, v87, v15
	v_cvt_pk_bf16_f32 v156, v0, v1
	v_cvt_pk_bf16_f32 v157, v2, v3
	v_cvt_pk_bf16_f32 v158, v4, v5
	v_cvt_pk_bf16_f32 v159, v6, v7
	v_cvt_pk_bf16_f32 v160, v8, v9
	v_cvt_pk_bf16_f32 v161, v10, v11
	v_cvt_pk_bf16_f32 v162, v12, v13
	v_cvt_pk_bf16_f32 v163, v14, v15
	s_lshl_b32 vcc_lo, s19, 11
	s_add_u32 vcc_lo, vcc_lo, 0x2400000
	s_add_u32 s100, s16, vcc_lo
	s_addc_u32 s101, s17, 0
	global_store_dwordx2 v137, v[156:157], s[100:101] offset:0
	global_store_dwordx2 v137, v[158:159], s[100:101] offset:512
	global_store_dwordx2 v137, v[160:161], s[100:101] offset:1024
	global_store_dwordx2 v137, v[162:163], s[100:101] offset:1536
	v_mul_f32_e32 v138, v0, v0
	v_mul_f32_e32 v149, v1, v1
	v_mul_f32_e32 v150, v2, v2
	v_mul_f32_e32 v154, v3, v3
	v_fma_f32 v138, v4, v4, v138
	v_fma_f32 v149, v5, v5, v149
	v_fma_f32 v150, v6, v6, v150
	v_fma_f32 v154, v7, v7, v154
	v_fma_f32 v138, v8, v8, v138
	v_fma_f32 v149, v9, v9, v149
	v_fma_f32 v150, v10, v10, v150
	v_fma_f32 v154, v11, v11, v154
	v_fma_f32 v138, v12, v12, v138
	v_fma_f32 v149, v13, v13, v149
	v_fma_f32 v150, v14, v14, v150
	v_fma_f32 v154, v15, v15, v154
	v_add_f32_e32 v138, v138, v149
	v_add_f32_e32 v150, v150, v154
	v_add_f32_e32 v138, v138, v150
	s_nop 1
	v_add_f32_dpp v138, v138, v138 quad_perm:[1,0,3,2] row_mask:0xf bank_mask:0xf
; __device__ __forceinline__ void row_phase(const Params& P, int glayer, int layer, int xsrc, bool hasY, int gate_idx, const float* gpost,
;                           int xdst, bool doH, const float* gpre, int sh_idx, int nrows) {
;     ...
;         if (hasY) {
;           float4 yv[4];
;           float ss = 0.f;
; #pragma unroll
;           for (int i = 0; i < 4; ++i) {
;             const uint2 raw = yy[u][i];
;             yv[i].x = bf2f((u16)(raw.x & 0xffff)); yv[i].y = bf2f((u16)(raw.x >> 16));
;             yv[i].z = bf2f((u16)(raw.y & 0xffff)); yv[i].w = bf2f((u16)(raw.y >> 16));
;             ss += yv[i].x * yv[i].x + yv[i].y * yv[i].y + yv[i].z * yv[i].z + yv[i].w * yv[i].w;
;           }
;           ss = wave_sum(ss);
;           const float rstd = __builtin_amdgcn_rsqf(ss * (1.f / 1024.f) + EPSF);
; #pragma unroll
;           for (int i = 0; i < 4; ++i) {
;             const int col = (i * 64 + lane) * 4;
;             const float4 gt = *reinterpret_cast<const float4*>(modg + gate_idx * 1024 + col);
;             const float4 gp = *reinterpret_cast<const float4*>(gpost + col);
;             xv[i].x += gt.x * (yv[i].x * rstd * gp.x); xv[i].y += gt.y * (yv[i].y * rstd * gp.y);
;             xv[i].z += gt.z * (yv[i].z * rstd * gp.z); xv[i].w += gt.w * (yv[i].w * rstd * gp.w);
;           }
;         }
;         if (xdst == 3 || (xdst == 1 && row >= N_X)) {
;           float* xout = (xdst == 3) ? P.out + (long)row * 1024 : P.xc + (long)(row - N_X) * 1024;
; #pragma unroll
;           for (int i = 0; i < 4; ++i) *reinterpret_cast<float4*>(xout + (i * 64 + lane) * 4) = xv[i];
;         } else if (xdst != 0) {
;           u16* xo = ((xdst == 1) ? resA : P.zf) + (long)row * 1024;
; #pragma unroll
;           for (int i = 0; i < 4; ++i) {
;             const unsigned b0 = f2bf(xv[i].x), b1 = f2bf(xv[i].y), b2 = f2bf(xv[i].z), b3 = f2bf(xv[i].w);
;             *reinterpret_cast<uint2*>(xo + (i * 64 + lane) * 4) = make_uint2(b0 | (b1 << 16), b2 | (b3 << 16));
;           }
;         }
;         if (doH) {
;           float ss = 0.f;
; #pragma unroll
;           for (int i = 0; i < 4; ++i) ss += xv[i].x * xv[i].x + xv[i].y * xv[i].y + xv[i].z * xv[i].z + xv[i].w * xv[i].w;
;           ss = wave_sum(ss);
;           const float rstd = __builtin_amdgcn_rsqf(ss * (1.f / 1024.f) + EPSF);
;           u16* h = P.hy + (long)row * 1024;
; #pragma unroll
	s_nop 1
	v_add_f32_dpp v138, v138, v138 quad_perm:[2,3,0,1] row_mask:0xf bank_mask:0xf
	s_nop 1
	v_add_f32_dpp v138, v138, v138 row_half_mirror row_mask:0xf bank_mask:0xf
	s_nop 1
	v_add_f32_dpp v138, v138, v138 row_mirror row_mask:0xf bank_mask:0xf
	v_mov_b32_e32 v139, v138
	s_nop 1
	v_permlane16_swap_b32_e32 v138, v139
	v_add_f32_e32 v138, v138, v139
	v_mov_b32_e32 v139, v138
	s_nop 1
	v_permlane32_swap_b32_e32 v138, v139
	v_add_f32_e32 v138, v138, v139
	v_mul_f32_e32 v138, 0x3a800000, v138
	v_add_f32_e32 v138, 0x358637bd, v138
	v_rsq_f32_e32 v140, v138
	s_nop 0
	v_mul_f32_e32 v120, v0, v140
	v_mul_f32_e32 v121, v1, v140
	v_mul_f32_e32 v122, v2, v140
	v_mul_f32_e32 v123, v3, v140
	v_mul_f32_e32 v124, v4, v140
	v_mul_f32_e32 v125, v5, v140
	v_mul_f32_e32 v126, v6, v140
	v_mul_f32_e32 v127, v7, v140
	v_mul_f32_e32 v128, v8, v140
	v_mul_f32_e32 v129, v9, v140
	v_mul_f32_e32 v130, v10, v140
	v_mul_f32_e32 v131, v11, v140
	v_mul_f32_e32 v132, v12, v140
	v_mul_f32_e32 v133, v13, v140
	v_mul_f32_e32 v134, v14, v140
	v_mul_f32_e32 v135, v15, v140
	v_fma_f32 v120, v120, v88, v104
	v_fma_f32 v121, v121, v89, v105
	v_fma_f32 v122, v122, v90, v106
	v_fma_f32 v123, v123, v91, v107
	v_fma_f32 v124, v124, v92, v108
	v_fma_f32 v125, v125, v93, v109
	v_fma_f32 v126, v126, v94, v110
	v_fma_f32 v127, v127, v95, v111
	v_fma_f32 v128, v128, v96, v112
	v_fma_f32 v129, v129, v97, v113
	v_fma_f32 v130, v130, v98, v114
	v_fma_f32 v131, v131, v99, v115
	v_fma_f32 v132, v132, v100, v116
	v_fma_f32 v133, v133, v101, v117
	v_fma_f32 v134, v134, v102, v118
	v_fma_f32 v135, v135, v103, v119
	v_cvt_pk_bf16_f32 v156, v120, v121
	v_cvt_pk_bf16_f32 v157, v122, v123
	v_cvt_pk_bf16_f32 v158, v124, v125
	v_cvt_pk_bf16_f32 v159, v126, v127
	v_cvt_pk_bf16_f32 v160, v128, v129
	v_cvt_pk_bf16_f32 v161, v130, v131
	v_cvt_pk_bf16_f32 v162, v132, v133
	v_cvt_pk_bf16_f32 v163, v134, v135
	s_lshl_b32 vcc_lo, s19, 11
	s_add_u32 vcc_lo, vcc_lo, 0x2400000
	s_add_u32 s100, s14, vcc_lo
	s_addc_u32 s101, s15, 0
	global_store_dwordx2 v137, v[156:157], s[100:101] offset:0
	global_store_dwordx2 v137, v[158:159], s[100:101] offset:512
	global_store_dwordx2 v137, v[160:161], s[100:101] offset:1024
	global_store_dwordx2 v137, v[162:163], s[100:101] offset:1536
	s_lshl_b32 vcc_lo, s19, 11
	s_add_u32 vcc_lo, vcc_lo, 0x3000000
	s_add_u32 s100, s12, vcc_lo
	s_addc_u32 s101, s13, 0
	global_load_dwordx2 v[8:9], v137, s[100:101] offset:0
	global_load_dwordx2 v[10:11], v137, s[100:101] offset:512
	global_load_dwordx2 v[12:13], v137, s[100:101] offset:1024
	global_load_dwordx2 v[14:15], v137, s[100:101] offset:1536
	s_lshl_b32 vcc_lo, s19, 11
	s_add_u32 vcc_lo, vcc_lo, 0x3000000
	s_add_u32 s100, s14, vcc_lo
	s_addc_u32 s101, s15, 0
	global_load_dwordx2 v[48:49], v137, s[100:101] offset:0
	global_load_dwordx2 v[50:51], v137, s[100:101] offset:512
	global_load_dwordx2 v[52:53], v137, s[100:101] offset:1024
	global_load_dwordx2 v[54:55], v137, s[100:101] offset:1536
	s_waitcnt vmcnt(32)
	v_lshlrev_b32_e32 v120, 16, v56
	v_and_b32_e32 v121, 0xffff0000, v56
	v_lshlrev_b32_e32 v122, 16, v57
	v_and_b32_e32 v123, 0xffff0000, v57
	v_lshlrev_b32_e32 v124, 16, v58
	v_and_b32_e32 v125, 0xffff0000, v58
	v_lshlrev_b32_e32 v126, 16, v59
	v_and_b32_e32 v127, 0xffff0000, v59
	v_lshlrev_b32_e32 v128, 16, v60
	v_and_b32_e32 v129, 0xffff0000, v60
	v_lshlrev_b32_e32 v130, 16, v61
	v_and_b32_e32 v131, 0xffff0000, v61
	v_lshlrev_b32_e32 v132, 16, v62
	v_and_b32_e32 v133, 0xffff0000, v62
	v_lshlrev_b32_e32 v134, 16, v63
	v_and_b32_e32 v135, 0xffff0000, v63
	v_mul_f32_e32 v138, v120, v120
	v_mul_f32_e32 v149, v121, v121
	v_mul_f32_e32 v150, v122, v122
	v_mul_f32_e32 v154, v123, v123
	v_fma_f32 v138, v124, v124, v138
	v_fma_f32 v149, v125, v125, v149
	v_fma_f32 v150, v126, v126, v150
	v_fma_f32 v154, v127, v127, v154
	v_fma_f32 v138, v128, v128, v138
	v_fma_f32 v149, v129, v129, v149
	v_fma_f32 v150, v130, v130, v150
	v_fma_f32 v154, v131, v131, v154
	v_fma_f32 v138, v132, v132, v138
	v_fma_f32 v149, v133, v133, v149
	v_fma_f32 v150, v134, v134, v150
	v_fma_f32 v154, v135, v135, v154
	v_add_f32_e32 v138, v138, v149
	v_add_f32_e32 v150, v150, v154
	v_add_f32_e32 v138, v138, v150
	s_nop 1
	v_add_f32_dpp v138, v138, v138 quad_perm:[1,0,3,2] row_mask:0xf bank_mask:0xf
	s_nop 1
	v_add_f32_dpp v138, v138, v138 quad_perm:[2,3,0,1] row_mask:0xf bank_mask:0xf
	s_nop 1
	v_add_f32_dpp v138, v138, v138 row_half_mirror row_mask:0xf bank_mask:0xf
	s_nop 1
	v_add_f32_dpp v138, v138, v138 row_mirror row_mask:0xf bank_mask:0xf
	v_mov_b32_e32 v139, v138
	s_nop 1
	v_permlane16_swap_b32_e32 v138, v139
	v_add_f32_e32 v138, v138, v139
	v_mov_b32_e32 v139, v138
	s_nop 1
	v_permlane32_swap_b32_e32 v138, v139
	v_add_f32_e32 v138, v138, v139
	v_mul_f32_e32 v138, 0x3a800000, v138
	v_add_f32_e32 v138, 0x358637bd, v138
	v_rsq_f32_e32 v140, v138
	v_lshlrev_b32_e32 v16, 16, v24
	v_and_b32_e32 v17, 0xffff0000, v24
	v_lshlrev_b32_e32 v18, 16, v25
	v_and_b32_e32 v19, 0xffff0000, v25
	v_lshlrev_b32_e32 v20, 16, v26
	v_and_b32_e32 v21, 0xffff0000, v26
	v_lshlrev_b32_e32 v22, 16, v27
	v_and_b32_e32 v23, 0xffff0000, v27
	v_lshlrev_b32_e32 v24, 16, v28
	v_and_b32_e32 v25, 0xffff0000, v28
	v_lshlrev_b32_e32 v26, 16, v29
	v_and_b32_e32 v27, 0xffff0000, v29
	v_lshlrev_b32_e32 v28, 16, v30
	v_and_b32_e32 v29, 0xffff0000, v30
	v_lshlrev_b32_e32 v30, 16, v31
	v_and_b32_e32 v31, 0xffff0000, v31
	s_nop 0
	v_mul_f32_e32 v120, v120, v140
	v_mul_f32_e32 v121, v121, v140
	v_mul_f32_e32 v122, v122, v140
	v_mul_f32_e32 v123, v123, v140
	v_mul_f32_e32 v124, v124, v140
	v_mul_f32_e32 v125, v125, v140
	v_mul_f32_e32 v126, v126, v140
	v_mul_f32_e32 v127, v127, v140
; __device__ __forceinline__ void row_phase(const Params& P, int glayer, int layer, int xsrc, bool hasY, int gate_idx, const float* gpost,
;                           int xdst, bool doH, const float* gpre, int sh_idx, int nrows) {
;     ...
;             xv[i].x += gt.x * (yv[i].x * rstd * gp.x); xv[i].y += gt.y * (yv[i].y * rstd * gp.y);
;             xv[i].z += gt.z * (yv[i].z * rstd * gp.z); xv[i].w += gt.w * (yv[i].w * rstd * gp.w);
;           }
;         }
;         if (xdst == 3 || (xdst == 1 && row >= N_X)) {
;           float* xout = (xdst == 3) ? P.out + (long)row * 1024 : P.xc + (long)(row - N_X) * 1024;
; #pragma unroll
;           for (int i = 0; i < 4; ++i) *reinterpret_cast<float4*>(xout + (i * 64 + lane) * 4) = xv[i];
;         } else if (xdst != 0) {
;           u16* xo = ((xdst == 1) ? resA : P.zf) + (long)row * 1024;
; #pragma unroll
;           for (int i = 0; i < 4; ++i) {
;             const unsigned b0 = f2bf(xv[i].x), b1 = f2bf(xv[i].y), b2 = f2bf(xv[i].z), b3 = f2bf(xv[i].w);
;             *reinterpret_cast<uint2*>(xo + (i * 64 + lane) * 4) = make_uint2(b0 | (b1 << 16), b2 | (b3 << 16));
;           }
;         }
;         if (doH) {
;           float ss = 0.f;
; #pragma unroll
;           for (int i = 0; i < 4; ++i) ss += xv[i].x * xv[i].x + xv[i].y * xv[i].y + xv[i].z * xv[i].z + xv[i].w * xv[i].w;
;           ss = wave_sum(ss);
;           const float rstd = __builtin_amdgcn_rsqf(ss * (1.f / 1024.f) + EPSF);
;           u16* h = P.hy + (long)row * 1024;
; #pragma unroll
;           for (int i = 0; i < 4; ++i) {
;             const int col = (i * 64 + lane) * 4;
;             const float4 g = *reinterpret_cast<const float4*>(gpre + col);
;             const float4 sh = *reinterpret_cast<const float4*>(modp + sh_idx * 1024 + col);
;             const float4 sc = *reinterpret_cast<const float4*>(modp + (sh_idx + 1) * 1024 + col);
;             const unsigned h0 = f2bf(xv[i].x * rstd * g.x * (1.f + sc.x) + sh.x);
;             const unsigned h1 = f2bf(xv[i].y * rstd * g.y * (1.f + sc.y) + sh.y);
;             const unsigned h2 = f2bf(xv[i].z * rstd * g.z * (1.f + sc.z) + sh.z);
;             const unsigned h3 = f2bf(xv[i].w * rstd * g.w * (1.f + sc.w) + sh.w);
;             *reinterpret_cast<uint2*>(h + col) = make_uint2(h0 | (h1 << 16), h2 | (h3 << 16));
	v_mul_f32_e32 v128, v128, v140
	v_mul_f32_e32 v129, v129, v140
	v_mul_f32_e32 v130, v130, v140
	v_mul_f32_e32 v131, v131, v140
	v_mul_f32_e32 v132, v132, v140
	v_mul_f32_e32 v133, v133, v140
	v_mul_f32_e32 v134, v134, v140
	v_mul_f32_e32 v135, v135, v140
	v_fma_f32 v16, v120, v72, v16
	v_fma_f32 v17, v121, v73, v17
	v_fma_f32 v18, v122, v74, v18
	v_fma_f32 v19, v123, v75, v19
	v_fma_f32 v20, v124, v76, v20
	v_fma_f32 v21, v125, v77, v21
	v_fma_f32 v22, v126, v78, v22
	v_fma_f32 v23, v127, v79, v23
	v_fma_f32 v24, v128, v80, v24
	v_fma_f32 v25, v129, v81, v25
	v_fma_f32 v26, v130, v82, v26
	v_fma_f32 v27, v131, v83, v27
	v_fma_f32 v28, v132, v84, v28
	v_fma_f32 v29, v133, v85, v29
	v_fma_f32 v30, v134, v86, v30
	v_fma_f32 v31, v135, v87, v31
	v_cvt_pk_bf16_f32 v156, v16, v17
	v_cvt_pk_bf16_f32 v157, v18, v19
	v_cvt_pk_bf16_f32 v158, v20, v21
	v_cvt_pk_bf16_f32 v159, v22, v23
	v_cvt_pk_bf16_f32 v160, v24, v25
	v_cvt_pk_bf16_f32 v161, v26, v27
	v_cvt_pk_bf16_f32 v162, v28, v29
	v_cvt_pk_bf16_f32 v163, v30, v31
	s_lshl_b32 vcc_lo, s19, 11
	s_add_u32 vcc_lo, vcc_lo, 0x2800000
	s_add_u32 s100, s16, vcc_lo
	s_addc_u32 s101, s17, 0
	global_store_dwordx2 v137, v[156:157], s[100:101] offset:0
	global_store_dwordx2 v137, v[158:159], s[100:101] offset:512
	global_store_dwordx2 v137, v[160:161], s[100:101] offset:1024
	global_store_dwordx2 v137, v[162:163], s[100:101] offset:1536
	v_mul_f32_e32 v138, v16, v16
	v_mul_f32_e32 v149, v17, v17
	v_mul_f32_e32 v150, v18, v18
	v_mul_f32_e32 v154, v19, v19
	v_fma_f32 v138, v20, v20, v138
	v_fma_f32 v149, v21, v21, v149
	v_fma_f32 v150, v22, v22, v150
	v_fma_f32 v154, v23, v23, v154
	v_fma_f32 v138, v24, v24, v138
	v_fma_f32 v149, v25, v25, v149
	v_fma_f32 v150, v26, v26, v150
	v_fma_f32 v154, v27, v27, v154
	v_fma_f32 v138, v28, v28, v138
	v_fma_f32 v149, v29, v29, v149
	v_fma_f32 v150, v30, v30, v150
	v_fma_f32 v154, v31, v31, v154
	v_add_f32_e32 v138, v138, v149
	v_add_f32_e32 v150, v150, v154
	v_add_f32_e32 v138, v138, v150
	s_nop 1
	v_add_f32_dpp v138, v138, v138 quad_perm:[1,0,3,2] row_mask:0xf bank_mask:0xf
	s_nop 1
	v_add_f32_dpp v138, v138, v138 quad_perm:[2,3,0,1] row_mask:0xf bank_mask:0xf
	s_nop 1
	v_add_f32_dpp v138, v138, v138 row_half_mirror row_mask:0xf bank_mask:0xf
	s_nop 1
	v_add_f32_dpp v138, v138, v138 row_mirror row_mask:0xf bank_mask:0xf
	v_mov_b32_e32 v139, v138
	s_nop 1
	v_permlane16_swap_b32_e32 v138, v139
	v_add_f32_e32 v138, v138, v139
	v_mov_b32_e32 v139, v138
	s_nop 1
	v_permlane32_swap_b32_e32 v138, v139
	v_add_f32_e32 v138, v138, v139
	v_mul_f32_e32 v138, 0x3a800000, v138
	v_add_f32_e32 v138, 0x358637bd, v138
	v_rsq_f32_e32 v140, v138
	s_nop 0
	v_mul_f32_e32 v120, v16, v140
	v_mul_f32_e32 v121, v17, v140
	v_mul_f32_e32 v122, v18, v140
	v_mul_f32_e32 v123, v19, v140
	v_mul_f32_e32 v124, v20, v140
	v_mul_f32_e32 v125, v21, v140
	v_mul_f32_e32 v126, v22, v140
	v_mul_f32_e32 v127, v23, v140
	v_mul_f32_e32 v128, v24, v140
	v_mul_f32_e32 v129, v25, v140
	v_mul_f32_e32 v130, v26, v140
	v_mul_f32_e32 v131, v27, v140
	v_mul_f32_e32 v132, v28, v140
	v_mul_f32_e32 v133, v29, v140
	v_mul_f32_e32 v134, v30, v140
	v_mul_f32_e32 v135, v31, v140
	v_fma_f32 v120, v120, v88, v104
	v_fma_f32 v121, v121, v89, v105
	v_fma_f32 v122, v122, v90, v106
	v_fma_f32 v123, v123, v91, v107
	v_fma_f32 v124, v124, v92, v108
	v_fma_f32 v125, v125, v93, v109
	v_fma_f32 v126, v126, v94, v110
	v_fma_f32 v127, v127, v95, v111
	v_fma_f32 v128, v128, v96, v112
	v_fma_f32 v129, v129, v97, v113
	v_fma_f32 v130, v130, v98, v114
	v_fma_f32 v131, v131, v99, v115
	v_fma_f32 v132, v132, v100, v116
	v_fma_f32 v133, v133, v101, v117
	v_fma_f32 v134, v134, v102, v118
	v_fma_f32 v135, v135, v103, v119
	v_cvt_pk_bf16_f32 v156, v120, v121
	v_cvt_pk_bf16_f32 v157, v122, v123
	v_cvt_pk_bf16_f32 v158, v124, v125
	v_cvt_pk_bf16_f32 v159, v126, v127
	v_cvt_pk_bf16_f32 v160, v128, v129
	v_cvt_pk_bf16_f32 v161, v130, v131
	v_cvt_pk_bf16_f32 v162, v132, v133
	v_cvt_pk_bf16_f32 v163, v134, v135
	s_lshl_b32 vcc_lo, s19, 11
	s_add_u32 vcc_lo, vcc_lo, 0x2800000
	s_add_u32 s100, s14, vcc_lo
	s_addc_u32 s101, s15, 0
	global_store_dwordx2 v137, v[156:157], s[100:101] offset:0
	global_store_dwordx2 v137, v[158:159], s[100:101] offset:512
	global_store_dwordx2 v137, v[160:161], s[100:101] offset:1024
	global_store_dwordx2 v137, v[162:163], s[100:101] offset:1536
	s_lshl_b32 vcc_lo, s19, 11
	s_add_u32 vcc_lo, vcc_lo, 0x3400000
	s_add_u32 s100, s12, vcc_lo
	s_addc_u32 s101, s13, 0
	global_load_dwordx2 v[24:25], v137, s[100:101] offset:0
	global_load_dwordx2 v[26:27], v137, s[100:101] offset:512
	global_load_dwordx2 v[28:29], v137, s[100:101] offset:1024
	global_load_dwordx2 v[30:31], v137, s[100:101] offset:1536
	s_lshl_b32 vcc_lo, s19, 11
	s_add_u32 vcc_lo, vcc_lo, 0x3400000
	s_add_u32 s100, s14, vcc_lo
	s_addc_u32 s101, s15, 0
	global_load_dwordx2 v[56:57], v137, s[100:101] offset:0
	global_load_dwordx2 v[58:59], v137, s[100:101] offset:512
	global_load_dwordx2 v[60:61], v137, s[100:101] offset:1024
	global_load_dwordx2 v[62:63], v137, s[100:101] offset:1536
	s_waitcnt vmcnt(32)
; __device__ __forceinline__ void row_phase(const Params& P, int glayer, int layer, int xsrc, bool hasY, int gate_idx, const float* gpost,
;                           int xdst, bool doH, const float* gpre, int sh_idx, int nrows) {
;     ...
;         if (hasY) {
;           float4 yv[4];
;           float ss = 0.f;
; #pragma unroll
;           for (int i = 0; i < 4; ++i) {
;             const uint2 raw = yy[u][i];
;             yv[i].x = bf2f((u16)(raw.x & 0xffff)); yv[i].y = bf2f((u16)(raw.x >> 16));
;             yv[i].z = bf2f((u16)(raw.y & 0xffff)); yv[i].w = bf2f((u16)(raw.y >> 16));
;             ss += yv[i].x * yv[i].x + yv[i].y * yv[i].y + yv[i].z * yv[i].z + yv[i].w * yv[i].w;
;           }
;           ss = wave_sum(ss);
;           const float rstd = __builtin_amdgcn_rsqf(ss * (1.f / 1024.f) + EPSF);
; #pragma unroll
;           for (int i = 0; i < 4; ++i) {
;             const int col = (i * 64 + lane) * 4;
;             const float4 gt = *reinterpret_cast<const float4*>(modg + gate_idx * 1024 + col);
;             const float4 gp = *reinterpret_cast<const float4*>(gpost + col);
;             xv[i].x += gt.x * (yv[i].x * rstd * gp.x); xv[i].y += gt.y * (yv[i].y * rstd * gp.y);
;             xv[i].z += gt.z * (yv[i].z * rstd * gp.z); xv[i].w += gt.w * (yv[i].w * rstd * gp.w);
;           }
;         }
;         if (xdst == 3 || (xdst == 1 && row >= N_X)) {
;           float* xout = (xdst == 3) ? P.out + (long)row * 1024 : P.xc + (long)(row - N_X) * 1024;
; #pragma unroll
;           for (int i = 0; i < 4; ++i) *reinterpret_cast<float4*>(xout + (i * 64 + lane) * 4) = xv[i];
;         } else if (xdst != 0) {
;           u16* xo = ((xdst == 1) ? resA : P.zf) + (long)row * 1024;
; #pragma unroll
;           for (int i = 0; i < 4; ++i) {
;             const unsigned b0 = f2bf(xv[i].x), b1 = f2bf(xv[i].y), b2 = f2bf(xv[i].z), b3 = f2bf(xv[i].w);
;             *reinterpret_cast<uint2*>(xo + (i * 64 + lane) * 4) = make_uint2(b0 | (b1 << 16), b2 | (b3 << 16));
;           }
;         }
;         if (doH) {
;           float ss = 0.f;
; #pragma unroll
;           for (int i = 0; i < 4; ++i) ss += xv[i].x * xv[i].x + xv[i].y * xv[i].y + xv[i].z * xv[i].z + xv[i].w * xv[i].w;
;           ss = wave_sum(ss);
;           const float rstd = __builtin_amdgcn_rsqf(ss * (1.f / 1024.f) + EPSF);
;           u16* h = P.hy + (long)row * 1024;
; #pragma unroll
	v_lshlrev_b32_e32 v120, 16, v64
	v_and_b32_e32 v121, 0xffff0000, v64
	v_lshlrev_b32_e32 v122, 16, v65
	v_and_b32_e32 v123, 0xffff0000, v65
	v_lshlrev_b32_e32 v124, 16, v66
	v_and_b32_e32 v125, 0xffff0000, v66
	v_lshlrev_b32_e32 v126, 16, v67
	v_and_b32_e32 v127, 0xffff0000, v67
	v_lshlrev_b32_e32 v128, 16, v68
	v_and_b32_e32 v129, 0xffff0000, v68
	v_lshlrev_b32_e32 v130, 16, v69
	v_and_b32_e32 v131, 0xffff0000, v69
	v_lshlrev_b32_e32 v132, 16, v70
	v_and_b32_e32 v133, 0xffff0000, v70
	v_lshlrev_b32_e32 v134, 16, v71
	v_and_b32_e32 v135, 0xffff0000, v71
	v_mul_f32_e32 v138, v120, v120
	v_mul_f32_e32 v149, v121, v121
	v_mul_f32_e32 v150, v122, v122
	v_mul_f32_e32 v154, v123, v123
	v_fma_f32 v138, v124, v124, v138
	v_fma_f32 v149, v125, v125, v149
	v_fma_f32 v150, v126, v126, v150
	v_fma_f32 v154, v127, v127, v154
	v_fma_f32 v138, v128, v128, v138
	v_fma_f32 v149, v129, v129, v149
	v_fma_f32 v150, v130, v130, v150
	v_fma_f32 v154, v131, v131, v154
	v_fma_f32 v138, v132, v132, v138
	v_fma_f32 v149, v133, v133, v149
	v_fma_f32 v150, v134, v134, v150
	v_fma_f32 v154, v135, v135, v154
	v_add_f32_e32 v138, v138, v149
	v_add_f32_e32 v150, v150, v154
	v_add_f32_e32 v138, v138, v150
	s_nop 1
	v_add_f32_dpp v138, v138, v138 quad_perm:[1,0,3,2] row_mask:0xf bank_mask:0xf
	s_nop 1
	v_add_f32_dpp v138, v138, v138 quad_perm:[2,3,0,1] row_mask:0xf bank_mask:0xf
	s_nop 1
	v_add_f32_dpp v138, v138, v138 row_half_mirror row_mask:0xf bank_mask:0xf
	s_nop 1
	v_add_f32_dpp v138, v138, v138 row_mirror row_mask:0xf bank_mask:0xf
	v_mov_b32_e32 v139, v138
	s_nop 1
	v_permlane16_swap_b32_e32 v138, v139
	v_add_f32_e32 v138, v138, v139
	v_mov_b32_e32 v139, v138
	s_nop 1
	v_permlane32_swap_b32_e32 v138, v139
	v_add_f32_e32 v138, v138, v139
	v_mul_f32_e32 v138, 0x3a800000, v138
	v_add_f32_e32 v138, 0x358637bd, v138
	v_rsq_f32_e32 v140, v138
	v_lshlrev_b32_e32 v32, 16, v40
	v_and_b32_e32 v33, 0xffff0000, v40
	v_lshlrev_b32_e32 v34, 16, v41
	v_and_b32_e32 v35, 0xffff0000, v41
	v_lshlrev_b32_e32 v36, 16, v42
	v_and_b32_e32 v37, 0xffff0000, v42
	v_lshlrev_b32_e32 v38, 16, v43
	v_and_b32_e32 v39, 0xffff0000, v43
	v_lshlrev_b32_e32 v40, 16, v44
	v_and_b32_e32 v41, 0xffff0000, v44
	v_lshlrev_b32_e32 v42, 16, v45
	v_and_b32_e32 v43, 0xffff0000, v45
	v_lshlrev_b32_e32 v44, 16, v46
	v_and_b32_e32 v45, 0xffff0000, v46
	v_lshlrev_b32_e32 v46, 16, v47
	v_and_b32_e32 v47, 0xffff0000, v47
	s_nop 0
	v_mul_f32_e32 v120, v120, v140
	v_mul_f32_e32 v121, v121, v140
	v_mul_f32_e32 v122, v122, v140
	v_mul_f32_e32 v123, v123, v140
	v_mul_f32_e32 v124, v124, v140
	v_mul_f32_e32 v125, v125, v140
	v_mul_f32_e32 v126, v126, v140
	v_mul_f32_e32 v127, v127, v140
	v_mul_f32_e32 v128, v128, v140
	v_mul_f32_e32 v129, v129, v140
	v_mul_f32_e32 v130, v130, v140
	v_mul_f32_e32 v131, v131, v140
	v_mul_f32_e32 v132, v132, v140
	v_mul_f32_e32 v133, v133, v140
	v_mul_f32_e32 v134, v134, v140
	v_mul_f32_e32 v135, v135, v140
	v_fma_f32 v32, v120, v72, v32
	v_fma_f32 v33, v121, v73, v33
	v_fma_f32 v34, v122, v74, v34
	v_fma_f32 v35, v123, v75, v35
	v_fma_f32 v36, v124, v76, v36
	v_fma_f32 v37, v125, v77, v37
	v_fma_f32 v38, v126, v78, v38
	v_fma_f32 v39, v127, v79, v39
	v_fma_f32 v40, v128, v80, v40
	v_fma_f32 v41, v129, v81, v41
	v_fma_f32 v42, v130, v82, v42
	v_fma_f32 v43, v131, v83, v43
	v_fma_f32 v44, v132, v84, v44
	v_fma_f32 v45, v133, v85, v45
	v_fma_f32 v46, v134, v86, v46
	v_fma_f32 v47, v135, v87, v47
	v_cvt_pk_bf16_f32 v156, v32, v33
	v_cvt_pk_bf16_f32 v157, v34, v35
	v_cvt_pk_bf16_f32 v158, v36, v37
	v_cvt_pk_bf16_f32 v159, v38, v39
	v_cvt_pk_bf16_f32 v160, v40, v41
	v_cvt_pk_bf16_f32 v161, v42, v43
	v_cvt_pk_bf16_f32 v162, v44, v45
	v_cvt_pk_bf16_f32 v163, v46, v47
	s_lshl_b32 vcc_lo, s19, 11
	s_add_u32 vcc_lo, vcc_lo, 0x2c00000
	s_add_u32 s100, s16, vcc_lo
	s_addc_u32 s101, s17, 0
	global_store_dwordx2 v137, v[156:157], s[100:101] offset:0
	global_store_dwordx2 v137, v[158:159], s[100:101] offset:512
	global_store_dwordx2 v137, v[160:161], s[100:101] offset:1024
	global_store_dwordx2 v137, v[162:163], s[100:101] offset:1536
	v_mul_f32_e32 v138, v32, v32
	v_mul_f32_e32 v149, v33, v33
	v_mul_f32_e32 v150, v34, v34
	v_mul_f32_e32 v154, v35, v35
	v_fma_f32 v138, v36, v36, v138
	v_fma_f32 v149, v37, v37, v149
	v_fma_f32 v150, v38, v38, v150
	v_fma_f32 v154, v39, v39, v154
	v_fma_f32 v138, v40, v40, v138
	v_fma_f32 v149, v41, v41, v149
	v_fma_f32 v150, v42, v42, v150
	v_fma_f32 v154, v43, v43, v154
	v_fma_f32 v138, v44, v44, v138
	v_fma_f32 v149, v45, v45, v149
	v_fma_f32 v150, v46, v46, v150
	v_fma_f32 v154, v47, v47, v154
	v_add_f32_e32 v138, v138, v149
	v_add_f32_e32 v150, v150, v154
	v_add_f32_e32 v138, v138, v150
	s_nop 1
	v_add_f32_dpp v138, v138, v138 quad_perm:[1,0,3,2] row_mask:0xf bank_mask:0xf
	s_nop 1
	v_add_f32_dpp v138, v138, v138 quad_perm:[2,3,0,1] row_mask:0xf bank_mask:0xf
	s_nop 1
	v_add_f32_dpp v138, v138, v138 row_half_mirror row_mask:0xf bank_mask:0xf
	s_nop 1
	v_add_f32_dpp v138, v138, v138 row_mirror row_mask:0xf bank_mask:0xf
	v_mov_b32_e32 v139, v138
	s_nop 1
	v_permlane16_swap_b32_e32 v138, v139
	v_add_f32_e32 v138, v138, v139
	v_mov_b32_e32 v139, v138
	s_nop 1
	v_permlane32_swap_b32_e32 v138, v139
	v_add_f32_e32 v138, v138, v139
	v_mul_f32_e32 v138, 0x3a800000, v138
	v_add_f32_e32 v138, 0x358637bd, v138
	v_rsq_f32_e32 v140, v138
	s_nop 0
	v_mul_f32_e32 v120, v32, v140
	v_mul_f32_e32 v121, v33, v140
	v_mul_f32_e32 v122, v34, v140
	v_mul_f32_e32 v123, v35, v140
	v_mul_f32_e32 v124, v36, v140
	v_mul_f32_e32 v125, v37, v140
	v_mul_f32_e32 v126, v38, v140
	v_mul_f32_e32 v127, v39, v140
	v_mul_f32_e32 v128, v40, v140
	v_mul_f32_e32 v129, v41, v140
	v_mul_f32_e32 v130, v42, v140
; __device__ __forceinline__ float bf2f(u16 h) { return __uint_as_float(((unsigned)h) << 16); }
; __device__ __forceinline__ void row_phase(const Params& P, int glayer, int layer, int xsrc, bool hasY, int gate_idx, const float* gpost,
;                           int xdst, bool doH, const float* gpre, int sh_idx, int nrows) {
;     ...
;         const int mi = row < N_X ? (row >> 13) : 4;
;         const float* modp = P.mod + (long)(layer * 5 + mi) * 6144;
;         const float* modg = P.mod + (long)(glayer * 5 + mi) * 6144;
;         float4 xv[4];
;         if (xsrc != 0 && row < N_X) {
; #pragma unroll
;           for (int i = 0; i < 4; ++i) {
;             const uint4 raw = xr[u][i];
;             xv[i].x = bf2f((u16)(raw.x & 0xffff)); xv[i].y = bf2f((u16)(raw.x >> 16));
;             xv[i].z = bf2f((u16)(raw.y & 0xffff)); xv[i].w = bf2f((u16)(raw.y >> 16));
;           }
;         } else {
; #pragma unroll
;           for (int i = 0; i < 4; ++i) {
;             xv[i].x = __uint_as_float(xr[u][i].x); xv[i].y = __uint_as_float(xr[u][i].y);
;             xv[i].z = __uint_as_float(xr[u][i].z); xv[i].w = __uint_as_float(xr[u][i].w);
;           }
;         }
;         if (hasY) {
;           float4 yv[4];
;           float ss = 0.f;
; #pragma unroll
;           for (int i = 0; i < 4; ++i) {
;             const uint2 raw = yy[u][i];
;             yv[i].x = bf2f((u16)(raw.x & 0xffff)); yv[i].y = bf2f((u16)(raw.x >> 16));
;             yv[i].z = bf2f((u16)(raw.y & 0xffff)); yv[i].w = bf2f((u16)(raw.y >> 16));
;             ss += yv[i].x * yv[i].x + yv[i].y * yv[i].y + yv[i].z * yv[i].z + yv[i].w * yv[i].w;
;           }
;           ss = wave_sum(ss);
;           const float rstd = __builtin_amdgcn_rsqf(ss * (1.f / 1024.f) + EPSF);
; #pragma unroll
;           for (int i = 0; i < 4; ++i) {
;             const int col = (i * 64 + lane) * 4;
;             const float4 gt = *reinterpret_cast<const float4*>(modg + gate_idx * 1024 + col);
;             const float4 gp = *reinterpret_cast<const float4*>(gpost + col);
;             xv[i].x += gt.x * (yv[i].x * rstd * gp.x); xv[i].y += gt.y * (yv[i].y * rstd * gp.y);
;             xv[i].z += gt.z * (yv[i].z * rstd * gp.z); xv[i].w += gt.w * (yv[i].w * rstd * gp.w);
;           }
;         }
	v_mul_f32_e32 v131, v43, v140
	v_mul_f32_e32 v132, v44, v140
	v_mul_f32_e32 v133, v45, v140
	v_mul_f32_e32 v134, v46, v140
	v_mul_f32_e32 v135, v47, v140
	v_fma_f32 v120, v120, v88, v104
	v_fma_f32 v121, v121, v89, v105
	v_fma_f32 v122, v122, v90, v106
	v_fma_f32 v123, v123, v91, v107
	v_fma_f32 v124, v124, v92, v108
	v_fma_f32 v125, v125, v93, v109
	v_fma_f32 v126, v126, v94, v110
	v_fma_f32 v127, v127, v95, v111
	v_fma_f32 v128, v128, v96, v112
	v_fma_f32 v129, v129, v97, v113
	v_fma_f32 v130, v130, v98, v114
	v_fma_f32 v131, v131, v99, v115
	v_fma_f32 v132, v132, v100, v116
	v_fma_f32 v133, v133, v101, v117
	v_fma_f32 v134, v134, v102, v118
	v_fma_f32 v135, v135, v103, v119
	v_cvt_pk_bf16_f32 v156, v120, v121
	v_cvt_pk_bf16_f32 v157, v122, v123
	v_cvt_pk_bf16_f32 v158, v124, v125
	v_cvt_pk_bf16_f32 v159, v126, v127
	v_cvt_pk_bf16_f32 v160, v128, v129
	v_cvt_pk_bf16_f32 v161, v130, v131
	v_cvt_pk_bf16_f32 v162, v132, v133
	v_cvt_pk_bf16_f32 v163, v134, v135
	s_lshl_b32 vcc_lo, s19, 11
	s_add_u32 vcc_lo, vcc_lo, 0x2c00000
	s_add_u32 s100, s14, vcc_lo
	s_addc_u32 s101, s15, 0
	global_store_dwordx2 v137, v[156:157], s[100:101] offset:0
	global_store_dwordx2 v137, v[158:159], s[100:101] offset:512
	global_store_dwordx2 v137, v[160:161], s[100:101] offset:1024
	global_store_dwordx2 v137, v[162:163], s[100:101] offset:1536
	s_add_u32 s100, s20, 0x17000
	s_addc_u32 s101, s21, 0
	global_load_dwordx4 v[72:75], v136, s[100:101] offset:0
	global_load_dwordx4 v[76:79], v136, s[100:101] offset:1024
	global_load_dwordx4 v[80:83], v136, s[100:101] offset:2048
	global_load_dwordx4 v[84:87], v136, s[100:101] offset:3072
	s_load_dwordx2 s[98:99], s[4:5], 0x48
	s_waitcnt lgkmcnt(0)
	global_load_dwordx4 v[120:123], v136, s[98:99] offset:0
	global_load_dwordx4 v[124:127], v136, s[98:99] offset:1024
	global_load_dwordx4 v[128:131], v136, s[98:99] offset:2048
	global_load_dwordx4 v[132:135], v136, s[98:99] offset:3072
	s_add_u32 s100, s20, 0x30000
	s_addc_u32 s101, s21, 0
	global_load_dwordx4 v[104:107], v136, s[100:101] offset:0
	global_load_dwordx4 v[108:111], v136, s[100:101] offset:1024
	global_load_dwordx4 v[112:115], v136, s[100:101] offset:2048
	global_load_dwordx4 v[116:119], v136, s[100:101] offset:3072
	s_add_u32 s100, s100, 0x1000
	s_addc_u32 s101, s101, 0
	global_load_dwordx4 v[32:35], v136, s[100:101] offset:0
	global_load_dwordx4 v[36:39], v136, s[100:101] offset:1024
	global_load_dwordx4 v[40:43], v136, s[100:101] offset:2048
	global_load_dwordx4 v[44:47], v136, s[100:101] offset:3072
	s_load_dwordx2 s[98:99], s[4:5], 0x30
	s_waitcnt lgkmcnt(0)
	s_add_u32 s98, s98, 0x1000
	s_addc_u32 s99, s99, 0
	global_load_dwordx4 v[88:91], v136, s[98:99] offset:0
	global_load_dwordx4 v[92:95], v136, s[98:99] offset:1024
	global_load_dwordx4 v[96:99], v136, s[98:99] offset:2048
	global_load_dwordx4 v[100:103], v136, s[98:99] offset:3072
	s_waitcnt vmcnt(0)
	v_mul_f32_e32 v72, v72, v120
	v_mul_f32_e32 v73, v73, v121
	v_mul_f32_e32 v74, v74, v122
	v_mul_f32_e32 v75, v75, v123
	v_mul_f32_e32 v76, v76, v124
	v_mul_f32_e32 v77, v77, v125
	v_mul_f32_e32 v78, v78, v126
	v_mul_f32_e32 v79, v79, v127
	v_mul_f32_e32 v80, v80, v128
	v_mul_f32_e32 v81, v81, v129
	v_mul_f32_e32 v82, v82, v130
	v_mul_f32_e32 v83, v83, v131
	v_mul_f32_e32 v84, v84, v132
	v_mul_f32_e32 v85, v85, v133
	v_mul_f32_e32 v86, v86, v134
	v_mul_f32_e32 v87, v87, v135
	v_fma_f32 v88, v88, v32, v88
	v_fma_f32 v89, v89, v33, v89
	v_fma_f32 v90, v90, v34, v90
	v_fma_f32 v91, v91, v35, v91
	v_fma_f32 v92, v92, v36, v92
	v_fma_f32 v93, v93, v37, v93
	v_fma_f32 v94, v94, v38, v94
	v_fma_f32 v95, v95, v39, v95
	v_fma_f32 v96, v96, v40, v96
	v_fma_f32 v97, v97, v41, v97
	v_fma_f32 v98, v98, v42, v98
	v_fma_f32 v99, v99, v43, v99
	v_fma_f32 v100, v100, v44, v100
	v_fma_f32 v101, v101, v45, v101
	v_fma_f32 v102, v102, v46, v102
	v_fma_f32 v103, v103, v47, v103
	s_lshl_b32 vcc_lo, s19, 11
	s_add_u32 vcc_lo, vcc_lo, 0x3800000
	s_add_u32 s100, s12, vcc_lo
	s_addc_u32 s101, s13, 0
	global_load_dwordx2 v[40:41], v137, s[100:101] offset:0
	global_load_dwordx2 v[42:43], v137, s[100:101] offset:512
	global_load_dwordx2 v[44:45], v137, s[100:101] offset:1024
	global_load_dwordx2 v[46:47], v137, s[100:101] offset:1536
	s_lshl_b32 vcc_lo, s19, 11
	s_add_u32 vcc_lo, vcc_lo, 0x3800000
	s_add_u32 s100, s14, vcc_lo
	s_addc_u32 s101, s15, 0
	global_load_dwordx2 v[64:65], v137, s[100:101] offset:0
	global_load_dwordx2 v[66:67], v137, s[100:101] offset:512
	global_load_dwordx2 v[68:69], v137, s[100:101] offset:1024
	global_load_dwordx2 v[70:71], v137, s[100:101] offset:1536
	v_lshlrev_b32_e32 v120, 16, v48
	v_and_b32_e32 v121, 0xffff0000, v48
	v_lshlrev_b32_e32 v122, 16, v49
	v_and_b32_e32 v123, 0xffff0000, v49
	v_lshlrev_b32_e32 v124, 16, v50
	v_and_b32_e32 v125, 0xffff0000, v50
	v_lshlrev_b32_e32 v126, 16, v51
	v_and_b32_e32 v127, 0xffff0000, v51
	v_lshlrev_b32_e32 v128, 16, v52
	v_and_b32_e32 v129, 0xffff0000, v52
	v_lshlrev_b32_e32 v130, 16, v53
	v_and_b32_e32 v131, 0xffff0000, v53
	v_lshlrev_b32_e32 v132, 16, v54
	v_and_b32_e32 v133, 0xffff0000, v54
	v_lshlrev_b32_e32 v134, 16, v55
	v_and_b32_e32 v135, 0xffff0000, v55
	v_mul_f32_e32 v138, v120, v120
	v_mul_f32_e32 v149, v121, v121
	v_mul_f32_e32 v150, v122, v122
	v_mul_f32_e32 v154, v123, v123
	v_fma_f32 v138, v124, v124, v138
	v_fma_f32 v149, v125, v125, v149
	v_fma_f32 v150, v126, v126, v150
	v_fma_f32 v154, v127, v127, v154
	v_fma_f32 v138, v128, v128, v138
	v_fma_f32 v149, v129, v129, v149
	v_fma_f32 v150, v130, v130, v150
	v_fma_f32 v154, v131, v131, v154
	v_fma_f32 v138, v132, v132, v138
	v_fma_f32 v149, v133, v133, v149
	v_fma_f32 v150, v134, v134, v150
; __device__ __forceinline__ void row_phase(const Params& P, int glayer, int layer, int xsrc, bool hasY, int gate_idx, const float* gpost,
;                           int xdst, bool doH, const float* gpre, int sh_idx, int nrows) {
;     ...
;         if (hasY) {
;           float4 yv[4];
;           float ss = 0.f;
; #pragma unroll
;           for (int i = 0; i < 4; ++i) {
;             const uint2 raw = yy[u][i];
;             yv[i].x = bf2f((u16)(raw.x & 0xffff)); yv[i].y = bf2f((u16)(raw.x >> 16));
;             yv[i].z = bf2f((u16)(raw.y & 0xffff)); yv[i].w = bf2f((u16)(raw.y >> 16));
;             ss += yv[i].x * yv[i].x + yv[i].y * yv[i].y + yv[i].z * yv[i].z + yv[i].w * yv[i].w;
;           }
;           ss = wave_sum(ss);
;           const float rstd = __builtin_amdgcn_rsqf(ss * (1.f / 1024.f) + EPSF);
; #pragma unroll
;           for (int i = 0; i < 4; ++i) {
;             const int col = (i * 64 + lane) * 4;
;             const float4 gt = *reinterpret_cast<const float4*>(modg + gate_idx * 1024 + col);
;             const float4 gp = *reinterpret_cast<const float4*>(gpost + col);
;             xv[i].x += gt.x * (yv[i].x * rstd * gp.x); xv[i].y += gt.y * (yv[i].y * rstd * gp.y);
;             xv[i].z += gt.z * (yv[i].z * rstd * gp.z); xv[i].w += gt.w * (yv[i].w * rstd * gp.w);
;           }
;         }
;         if (xdst == 3 || (xdst == 1 && row >= N_X)) {
;           float* xout = (xdst == 3) ? P.out + (long)row * 1024 : P.xc + (long)(row - N_X) * 1024;
; #pragma unroll
;           for (int i = 0; i < 4; ++i) *reinterpret_cast<float4*>(xout + (i * 64 + lane) * 4) = xv[i];
;         } else if (xdst != 0) {
;           u16* xo = ((xdst == 1) ? resA : P.zf) + (long)row * 1024;
; #pragma unroll
;           for (int i = 0; i < 4; ++i) {
;             const unsigned b0 = f2bf(xv[i].x), b1 = f2bf(xv[i].y), b2 = f2bf(xv[i].z), b3 = f2bf(xv[i].w);
;             *reinterpret_cast<uint2*>(xo + (i * 64 + lane) * 4) = make_uint2(b0 | (b1 << 16), b2 | (b3 << 16));
;           }
;         }
;         if (doH) {
;           float ss = 0.f;
; #pragma unroll
;           for (int i = 0; i < 4; ++i) ss += xv[i].x * xv[i].x + xv[i].y * xv[i].y + xv[i].z * xv[i].z + xv[i].w * xv[i].w;
;           ss = wave_sum(ss);
;           const float rstd = __builtin_amdgcn_rsqf(ss * (1.f / 1024.f) + EPSF);
;           u16* h = P.hy + (long)row * 1024;
; #pragma unroll
	v_fma_f32 v154, v135, v135, v154
	v_add_f32_e32 v138, v138, v149
	v_add_f32_e32 v150, v150, v154
	v_add_f32_e32 v138, v138, v150
	s_nop 1
	v_add_f32_dpp v138, v138, v138 quad_perm:[1,0,3,2] row_mask:0xf bank_mask:0xf
	s_nop 1
	v_add_f32_dpp v138, v138, v138 quad_perm:[2,3,0,1] row_mask:0xf bank_mask:0xf
	s_nop 1
	v_add_f32_dpp v138, v138, v138 row_half_mirror row_mask:0xf bank_mask:0xf
	s_nop 1
	v_add_f32_dpp v138, v138, v138 row_mirror row_mask:0xf bank_mask:0xf
	v_mov_b32_e32 v139, v138
	s_nop 1
	v_permlane16_swap_b32_e32 v138, v139
	v_add_f32_e32 v138, v138, v139
	v_mov_b32_e32 v139, v138
	s_nop 1
	v_permlane32_swap_b32_e32 v138, v139
	v_add_f32_e32 v138, v138, v139
	v_mul_f32_e32 v138, 0x3a800000, v138
	v_add_f32_e32 v138, 0x358637bd, v138
	v_rsq_f32_e32 v140, v138
	v_lshlrev_b32_e32 v0, 16, v8
	v_and_b32_e32 v1, 0xffff0000, v8
	v_lshlrev_b32_e32 v2, 16, v9
	v_and_b32_e32 v3, 0xffff0000, v9
	v_lshlrev_b32_e32 v4, 16, v10
	v_and_b32_e32 v5, 0xffff0000, v10
	v_lshlrev_b32_e32 v6, 16, v11
	v_and_b32_e32 v7, 0xffff0000, v11
	v_lshlrev_b32_e32 v8, 16, v12
	v_and_b32_e32 v9, 0xffff0000, v12
	v_lshlrev_b32_e32 v10, 16, v13
	v_and_b32_e32 v11, 0xffff0000, v13
	v_lshlrev_b32_e32 v12, 16, v14
	v_and_b32_e32 v13, 0xffff0000, v14
	v_lshlrev_b32_e32 v14, 16, v15
	v_and_b32_e32 v15, 0xffff0000, v15
	s_nop 0
	v_mul_f32_e32 v120, v120, v140
	v_mul_f32_e32 v121, v121, v140
	v_mul_f32_e32 v122, v122, v140
	v_mul_f32_e32 v123, v123, v140
	v_mul_f32_e32 v124, v124, v140
	v_mul_f32_e32 v125, v125, v140
	v_mul_f32_e32 v126, v126, v140
	v_mul_f32_e32 v127, v127, v140
	v_mul_f32_e32 v128, v128, v140
	v_mul_f32_e32 v129, v129, v140
	v_mul_f32_e32 v130, v130, v140
	v_mul_f32_e32 v131, v131, v140
	v_mul_f32_e32 v132, v132, v140
	v_mul_f32_e32 v133, v133, v140
	v_mul_f32_e32 v134, v134, v140
	v_mul_f32_e32 v135, v135, v140
	v_fma_f32 v0, v120, v72, v0
	v_fma_f32 v1, v121, v73, v1
	v_fma_f32 v2, v122, v74, v2
	v_fma_f32 v3, v123, v75, v3
	v_fma_f32 v4, v124, v76, v4
	v_fma_f32 v5, v125, v77, v5
	v_fma_f32 v6, v126, v78, v6
	v_fma_f32 v7, v127, v79, v7
	v_fma_f32 v8, v128, v80, v8
	v_fma_f32 v9, v129, v81, v9
	v_fma_f32 v10, v130, v82, v10
	v_fma_f32 v11, v131, v83, v11
	v_fma_f32 v12, v132, v84, v12
	v_fma_f32 v13, v133, v85, v13
	v_fma_f32 v14, v134, v86, v14
	v_fma_f32 v15, v135, v87, v15
	v_cvt_pk_bf16_f32 v156, v0, v1
	v_cvt_pk_bf16_f32 v157, v2, v3
	v_cvt_pk_bf16_f32 v158, v4, v5
	v_cvt_pk_bf16_f32 v159, v6, v7
	v_cvt_pk_bf16_f32 v160, v8, v9
	v_cvt_pk_bf16_f32 v161, v10, v11
	v_cvt_pk_bf16_f32 v162, v12, v13
	v_cvt_pk_bf16_f32 v163, v14, v15
	s_lshl_b32 vcc_lo, s19, 11
	s_add_u32 vcc_lo, vcc_lo, 0x3000000
	s_add_u32 s100, s16, vcc_lo
	s_addc_u32 s101, s17, 0
	global_store_dwordx2 v137, v[156:157], s[100:101] offset:0
	global_store_dwordx2 v137, v[158:159], s[100:101] offset:512
	global_store_dwordx2 v137, v[160:161], s[100:101] offset:1024
	global_store_dwordx2 v137, v[162:163], s[100:101] offset:1536
	v_mul_f32_e32 v138, v0, v0
	v_mul_f32_e32 v149, v1, v1
	v_mul_f32_e32 v150, v2, v2
	v_mul_f32_e32 v154, v3, v3
	v_fma_f32 v138, v4, v4, v138
	v_fma_f32 v149, v5, v5, v149
	v_fma_f32 v150, v6, v6, v150
	v_fma_f32 v154, v7, v7, v154
	v_fma_f32 v138, v8, v8, v138
	v_fma_f32 v149, v9, v9, v149
	v_fma_f32 v150, v10, v10, v150
	v_fma_f32 v154, v11, v11, v154
	v_fma_f32 v138, v12, v12, v138
	v_fma_f32 v149, v13, v13, v149
	v_fma_f32 v150, v14, v14, v150
	v_fma_f32 v154, v15, v15, v154
	v_add_f32_e32 v138, v138, v149
	v_add_f32_e32 v150, v150, v154
	v_add_f32_e32 v138, v138, v150
	s_nop 1
	v_add_f32_dpp v138, v138, v138 quad_perm:[1,0,3,2] row_mask:0xf bank_mask:0xf
	s_nop 1
	v_add_f32_dpp v138, v138, v138 quad_perm:[2,3,0,1] row_mask:0xf bank_mask:0xf
	s_nop 1
	v_add_f32_dpp v138, v138, v138 row_half_mirror row_mask:0xf bank_mask:0xf
	s_nop 1
	v_add_f32_dpp v138, v138, v138 row_mirror row_mask:0xf bank_mask:0xf
	v_mov_b32_e32 v139, v138
	s_nop 1
	v_permlane16_swap_b32_e32 v138, v139
	v_add_f32_e32 v138, v138, v139
	v_mov_b32_e32 v139, v138
	s_nop 1
	v_permlane32_swap_b32_e32 v138, v139
	v_add_f32_e32 v138, v138, v139
	v_mul_f32_e32 v138, 0x3a800000, v138
	v_add_f32_e32 v138, 0x358637bd, v138
	v_rsq_f32_e32 v140, v138
	s_nop 0
	v_mul_f32_e32 v120, v0, v140
	v_mul_f32_e32 v121, v1, v140
	v_mul_f32_e32 v122, v2, v140
	v_mul_f32_e32 v123, v3, v140
	v_mul_f32_e32 v124, v4, v140
	v_mul_f32_e32 v125, v5, v140
	v_mul_f32_e32 v126, v6, v140
	v_mul_f32_e32 v127, v7, v140
	v_mul_f32_e32 v128, v8, v140
	v_mul_f32_e32 v129, v9, v140
	v_mul_f32_e32 v130, v10, v140
	v_mul_f32_e32 v131, v11, v140
	v_mul_f32_e32 v132, v12, v140
	v_mul_f32_e32 v133, v13, v140
	v_mul_f32_e32 v134, v14, v140
	v_mul_f32_e32 v135, v15, v140
	v_fma_f32 v120, v120, v88, v104
	v_fma_f32 v121, v121, v89, v105
	v_fma_f32 v122, v122, v90, v106
	v_fma_f32 v123, v123, v91, v107
	v_fma_f32 v124, v124, v92, v108
	v_fma_f32 v125, v125, v93, v109
	v_fma_f32 v126, v126, v94, v110
	v_fma_f32 v127, v127, v95, v111
	v_fma_f32 v128, v128, v96, v112
	v_fma_f32 v129, v129, v97, v113
	v_fma_f32 v130, v130, v98, v114
	v_fma_f32 v131, v131, v99, v115
	v_fma_f32 v132, v132, v100, v116
	v_fma_f32 v133, v133, v101, v117
	v_fma_f32 v134, v134, v102, v118
	v_fma_f32 v135, v135, v103, v119
	v_cvt_pk_bf16_f32 v156, v120, v121
	v_cvt_pk_bf16_f32 v157, v122, v123
	v_cvt_pk_bf16_f32 v158, v124, v125
	v_cvt_pk_bf16_f32 v159, v126, v127
	v_cvt_pk_bf16_f32 v160, v128, v129
	v_cvt_pk_bf16_f32 v161, v130, v131
	v_cvt_pk_bf16_f32 v162, v132, v133
	v_cvt_pk_bf16_f32 v163, v134, v135
	s_lshl_b32 vcc_lo, s19, 11
	s_add_u32 vcc_lo, vcc_lo, 0x3000000
	s_add_u32 s100, s14, vcc_lo
	s_addc_u32 s101, s15, 0
	global_store_dwordx2 v137, v[156:157], s[100:101] offset:0
; __device__ __forceinline__ void row_phase(const Params& P, int glayer, int layer, int xsrc, bool hasY, int gate_idx, const float* gpost,
;                           int xdst, bool doH, const float* gpre, int sh_idx, int nrows) {
;     ...
;         if (hasY) {
;           float4 yv[4];
;           float ss = 0.f;
; #pragma unroll
;           for (int i = 0; i < 4; ++i) {
;             const uint2 raw = yy[u][i];
;             yv[i].x = bf2f((u16)(raw.x & 0xffff)); yv[i].y = bf2f((u16)(raw.x >> 16));
;             yv[i].z = bf2f((u16)(raw.y & 0xffff)); yv[i].w = bf2f((u16)(raw.y >> 16));
;             ss += yv[i].x * yv[i].x + yv[i].y * yv[i].y + yv[i].z * yv[i].z + yv[i].w * yv[i].w;
;           }
;           ss = wave_sum(ss);
;           const float rstd = __builtin_amdgcn_rsqf(ss * (1.f / 1024.f) + EPSF);
; #pragma unroll
;           for (int i = 0; i < 4; ++i) {
;             const int col = (i * 64 + lane) * 4;
;             const float4 gt = *reinterpret_cast<const float4*>(modg + gate_idx * 1024 + col);
;             const float4 gp = *reinterpret_cast<const float4*>(gpost + col);
;             xv[i].x += gt.x * (yv[i].x * rstd * gp.x); xv[i].y += gt.y * (yv[i].y * rstd * gp.y);
;             xv[i].z += gt.z * (yv[i].z * rstd * gp.z); xv[i].w += gt.w * (yv[i].w * rstd * gp.w);
;           }
;         }
;         if (xdst == 3 || (xdst == 1 && row >= N_X)) {
;           float* xout = (xdst == 3) ? P.out + (long)row * 1024 : P.xc + (long)(row - N_X) * 1024;
; #pragma unroll
;           for (int i = 0; i < 4; ++i) *reinterpret_cast<float4*>(xout + (i * 64 + lane) * 4) = xv[i];
;         } else if (xdst != 0) {
;           u16* xo = ((xdst == 1) ? resA : P.zf) + (long)row * 1024;
; #pragma unroll
;           for (int i = 0; i < 4; ++i) {
;             const unsigned b0 = f2bf(xv[i].x), b1 = f2bf(xv[i].y), b2 = f2bf(xv[i].z), b3 = f2bf(xv[i].w);
;             *reinterpret_cast<uint2*>(xo + (i * 64 + lane) * 4) = make_uint2(b0 | (b1 << 16), b2 | (b3 << 16));
;           }
;         }
;         if (doH) {
;           float ss = 0.f;
; #pragma unroll
;           for (int i = 0; i < 4; ++i) ss += xv[i].x * xv[i].x + xv[i].y * xv[i].y + xv[i].z * xv[i].z + xv[i].w * xv[i].w;
;           ss = wave_sum(ss);
;           const float rstd = __builtin_amdgcn_rsqf(ss * (1.f / 1024.f) + EPSF);
;           u16* h = P.hy + (long)row * 1024;
; #pragma unroll
	global_store_dwordx2 v137, v[158:159], s[100:101] offset:512
	global_store_dwordx2 v137, v[160:161], s[100:101] offset:1024
	global_store_dwordx2 v137, v[162:163], s[100:101] offset:1536
	s_lshl_b32 vcc_lo, s19, 11
	s_add_u32 vcc_lo, vcc_lo, 0x3c00000
	s_add_u32 s100, s12, vcc_lo
	s_addc_u32 s101, s13, 0
	global_load_dwordx2 v[8:9], v137, s[100:101] offset:0
	global_load_dwordx2 v[10:11], v137, s[100:101] offset:512
	global_load_dwordx2 v[12:13], v137, s[100:101] offset:1024
	global_load_dwordx2 v[14:15], v137, s[100:101] offset:1536
	s_lshl_b32 vcc_lo, s19, 11
	s_add_u32 vcc_lo, vcc_lo, 0x3c00000
	s_add_u32 s100, s14, vcc_lo
	s_addc_u32 s101, s15, 0
	global_load_dwordx2 v[48:49], v137, s[100:101] offset:0
	global_load_dwordx2 v[50:51], v137, s[100:101] offset:512
	global_load_dwordx2 v[52:53], v137, s[100:101] offset:1024
	global_load_dwordx2 v[54:55], v137, s[100:101] offset:1536
	v_lshlrev_b32_e32 v120, 16, v56
	v_and_b32_e32 v121, 0xffff0000, v56
	v_lshlrev_b32_e32 v122, 16, v57
	v_and_b32_e32 v123, 0xffff0000, v57
	v_lshlrev_b32_e32 v124, 16, v58
	v_and_b32_e32 v125, 0xffff0000, v58
	v_lshlrev_b32_e32 v126, 16, v59
	v_and_b32_e32 v127, 0xffff0000, v59
	v_lshlrev_b32_e32 v128, 16, v60
	v_and_b32_e32 v129, 0xffff0000, v60
	v_lshlrev_b32_e32 v130, 16, v61
	v_and_b32_e32 v131, 0xffff0000, v61
	v_lshlrev_b32_e32 v132, 16, v62
	v_and_b32_e32 v133, 0xffff0000, v62
	v_lshlrev_b32_e32 v134, 16, v63
	v_and_b32_e32 v135, 0xffff0000, v63
	v_mul_f32_e32 v138, v120, v120
	v_mul_f32_e32 v149, v121, v121
	v_mul_f32_e32 v150, v122, v122
	v_mul_f32_e32 v154, v123, v123
	v_fma_f32 v138, v124, v124, v138
	v_fma_f32 v149, v125, v125, v149
	v_fma_f32 v150, v126, v126, v150
	v_fma_f32 v154, v127, v127, v154
	v_fma_f32 v138, v128, v128, v138
	v_fma_f32 v149, v129, v129, v149
	v_fma_f32 v150, v130, v130, v150
	v_fma_f32 v154, v131, v131, v154
	v_fma_f32 v138, v132, v132, v138
	v_fma_f32 v149, v133, v133, v149
	v_fma_f32 v150, v134, v134, v150
	v_fma_f32 v154, v135, v135, v154
	v_add_f32_e32 v138, v138, v149
	v_add_f32_e32 v150, v150, v154
	v_add_f32_e32 v138, v138, v150
	s_nop 1
	v_add_f32_dpp v138, v138, v138 quad_perm:[1,0,3,2] row_mask:0xf bank_mask:0xf
	s_nop 1
	v_add_f32_dpp v138, v138, v138 quad_perm:[2,3,0,1] row_mask:0xf bank_mask:0xf
	s_nop 1
	v_add_f32_dpp v138, v138, v138 row_half_mirror row_mask:0xf bank_mask:0xf
	s_nop 1
	v_add_f32_dpp v138, v138, v138 row_mirror row_mask:0xf bank_mask:0xf
	v_mov_b32_e32 v139, v138
	s_nop 1
	v_permlane16_swap_b32_e32 v138, v139
	v_add_f32_e32 v138, v138, v139
	v_mov_b32_e32 v139, v138
	s_nop 1
	v_permlane32_swap_b32_e32 v138, v139
	v_add_f32_e32 v138, v138, v139
	v_mul_f32_e32 v138, 0x3a800000, v138
	v_add_f32_e32 v138, 0x358637bd, v138
	v_rsq_f32_e32 v140, v138
	v_lshlrev_b32_e32 v16, 16, v24
	v_and_b32_e32 v17, 0xffff0000, v24
	v_lshlrev_b32_e32 v18, 16, v25
	v_and_b32_e32 v19, 0xffff0000, v25
	v_lshlrev_b32_e32 v20, 16, v26
	v_and_b32_e32 v21, 0xffff0000, v26
	v_lshlrev_b32_e32 v22, 16, v27
	v_and_b32_e32 v23, 0xffff0000, v27
	v_lshlrev_b32_e32 v24, 16, v28
	v_and_b32_e32 v25, 0xffff0000, v28
	v_lshlrev_b32_e32 v26, 16, v29
	v_and_b32_e32 v27, 0xffff0000, v29
	v_lshlrev_b32_e32 v28, 16, v30
	v_and_b32_e32 v29, 0xffff0000, v30
	v_lshlrev_b32_e32 v30, 16, v31
	v_and_b32_e32 v31, 0xffff0000, v31
	s_nop 0
	v_mul_f32_e32 v120, v120, v140
	v_mul_f32_e32 v121, v121, v140
	v_mul_f32_e32 v122, v122, v140
	v_mul_f32_e32 v123, v123, v140
	v_mul_f32_e32 v124, v124, v140
	v_mul_f32_e32 v125, v125, v140
	v_mul_f32_e32 v126, v126, v140
	v_mul_f32_e32 v127, v127, v140
	v_mul_f32_e32 v128, v128, v140
	v_mul_f32_e32 v129, v129, v140
	v_mul_f32_e32 v130, v130, v140
	v_mul_f32_e32 v131, v131, v140
	v_mul_f32_e32 v132, v132, v140
	v_mul_f32_e32 v133, v133, v140
	v_mul_f32_e32 v134, v134, v140
	v_mul_f32_e32 v135, v135, v140
	v_fma_f32 v16, v120, v72, v16
	v_fma_f32 v17, v121, v73, v17
	v_fma_f32 v18, v122, v74, v18
	v_fma_f32 v19, v123, v75, v19
	v_fma_f32 v20, v124, v76, v20
	v_fma_f32 v21, v125, v77, v21
	v_fma_f32 v22, v126, v78, v22
	v_fma_f32 v23, v127, v79, v23
	v_fma_f32 v24, v128, v80, v24
	v_fma_f32 v25, v129, v81, v25
	v_fma_f32 v26, v130, v82, v26
	v_fma_f32 v27, v131, v83, v27
	v_fma_f32 v28, v132, v84, v28
	v_fma_f32 v29, v133, v85, v29
	v_fma_f32 v30, v134, v86, v30
	v_fma_f32 v31, v135, v87, v31
	v_cvt_pk_bf16_f32 v156, v16, v17
	v_cvt_pk_bf16_f32 v157, v18, v19
	v_cvt_pk_bf16_f32 v158, v20, v21
	v_cvt_pk_bf16_f32 v159, v22, v23
	v_cvt_pk_bf16_f32 v160, v24, v25
	v_cvt_pk_bf16_f32 v161, v26, v27
	v_cvt_pk_bf16_f32 v162, v28, v29
	v_cvt_pk_bf16_f32 v163, v30, v31
	s_lshl_b32 vcc_lo, s19, 11
	s_add_u32 vcc_lo, vcc_lo, 0x3400000
	s_add_u32 s100, s16, vcc_lo
	s_addc_u32 s101, s17, 0
	global_store_dwordx2 v137, v[156:157], s[100:101] offset:0
	global_store_dwordx2 v137, v[158:159], s[100:101] offset:512
	global_store_dwordx2 v137, v[160:161], s[100:101] offset:1024
	global_store_dwordx2 v137, v[162:163], s[100:101] offset:1536
	v_mul_f32_e32 v138, v16, v16
	v_mul_f32_e32 v149, v17, v17
	v_mul_f32_e32 v150, v18, v18
	v_mul_f32_e32 v154, v19, v19
	v_fma_f32 v138, v20, v20, v138
	v_fma_f32 v149, v21, v21, v149
	v_fma_f32 v150, v22, v22, v150
	v_fma_f32 v154, v23, v23, v154
	v_fma_f32 v138, v24, v24, v138
	v_fma_f32 v149, v25, v25, v149
	v_fma_f32 v150, v26, v26, v150
	v_fma_f32 v154, v27, v27, v154
	v_fma_f32 v138, v28, v28, v138
	v_fma_f32 v149, v29, v29, v149
	v_fma_f32 v150, v30, v30, v150
	v_fma_f32 v154, v31, v31, v154
	v_add_f32_e32 v138, v138, v149
	v_add_f32_e32 v150, v150, v154
	v_add_f32_e32 v138, v138, v150
	s_nop 1
	v_add_f32_dpp v138, v138, v138 quad_perm:[1,0,3,2] row_mask:0xf bank_mask:0xf
	s_nop 1
; __device__ __forceinline__ void row_phase(const Params& P, int glayer, int layer, int xsrc, bool hasY, int gate_idx, const float* gpost,
;                           int xdst, bool doH, const float* gpre, int sh_idx, int nrows) {
;     ...
;         if (hasY) {
;           float4 yv[4];
;           float ss = 0.f;
; #pragma unroll
;           for (int i = 0; i < 4; ++i) {
;             const uint2 raw = yy[u][i];
;             yv[i].x = bf2f((u16)(raw.x & 0xffff)); yv[i].y = bf2f((u16)(raw.x >> 16));
;             yv[i].z = bf2f((u16)(raw.y & 0xffff)); yv[i].w = bf2f((u16)(raw.y >> 16));
;             ss += yv[i].x * yv[i].x + yv[i].y * yv[i].y + yv[i].z * yv[i].z + yv[i].w * yv[i].w;
;           }
;           ss = wave_sum(ss);
;           const float rstd = __builtin_amdgcn_rsqf(ss * (1.f / 1024.f) + EPSF);
; #pragma unroll
;           for (int i = 0; i < 4; ++i) {
;             const int col = (i * 64 + lane) * 4;
;             const float4 gt = *reinterpret_cast<const float4*>(modg + gate_idx * 1024 + col);
;             const float4 gp = *reinterpret_cast<const float4*>(gpost + col);
;             xv[i].x += gt.x * (yv[i].x * rstd * gp.x); xv[i].y += gt.y * (yv[i].y * rstd * gp.y);
;             xv[i].z += gt.z * (yv[i].z * rstd * gp.z); xv[i].w += gt.w * (yv[i].w * rstd * gp.w);
;           }
;         }
;         if (xdst == 3 || (xdst == 1 && row >= N_X)) {
;           float* xout = (xdst == 3) ? P.out + (long)row * 1024 : P.xc + (long)(row - N_X) * 1024;
; #pragma unroll
;           for (int i = 0; i < 4; ++i) *reinterpret_cast<float4*>(xout + (i * 64 + lane) * 4) = xv[i];
;         } else if (xdst != 0) {
;           u16* xo = ((xdst == 1) ? resA : P.zf) + (long)row * 1024;
; #pragma unroll
;           for (int i = 0; i < 4; ++i) {
;             const unsigned b0 = f2bf(xv[i].x), b1 = f2bf(xv[i].y), b2 = f2bf(xv[i].z), b3 = f2bf(xv[i].w);
;             *reinterpret_cast<uint2*>(xo + (i * 64 + lane) * 4) = make_uint2(b0 | (b1 << 16), b2 | (b3 << 16));
;           }
;         }
;         if (doH) {
;           float ss = 0.f;
; #pragma unroll
;           for (int i = 0; i < 4; ++i) ss += xv[i].x * xv[i].x + xv[i].y * xv[i].y + xv[i].z * xv[i].z + xv[i].w * xv[i].w;
;           ss = wave_sum(ss);
;           const float rstd = __builtin_amdgcn_rsqf(ss * (1.f / 1024.f) + EPSF);
;           u16* h = P.hy + (long)row * 1024;
; #pragma unroll
	v_add_f32_dpp v138, v138, v138 quad_perm:[2,3,0,1] row_mask:0xf bank_mask:0xf
	s_nop 1
	v_add_f32_dpp v138, v138, v138 row_half_mirror row_mask:0xf bank_mask:0xf
	s_nop 1
	v_add_f32_dpp v138, v138, v138 row_mirror row_mask:0xf bank_mask:0xf
	v_mov_b32_e32 v139, v138
	s_nop 1
	v_permlane16_swap_b32_e32 v138, v139
	v_add_f32_e32 v138, v138, v139
	v_mov_b32_e32 v139, v138
	s_nop 1
	v_permlane32_swap_b32_e32 v138, v139
	v_add_f32_e32 v138, v138, v139
	v_mul_f32_e32 v138, 0x3a800000, v138
	v_add_f32_e32 v138, 0x358637bd, v138
	v_rsq_f32_e32 v140, v138
	s_nop 0
	v_mul_f32_e32 v120, v16, v140
	v_mul_f32_e32 v121, v17, v140
	v_mul_f32_e32 v122, v18, v140
	v_mul_f32_e32 v123, v19, v140
	v_mul_f32_e32 v124, v20, v140
	v_mul_f32_e32 v125, v21, v140
	v_mul_f32_e32 v126, v22, v140
	v_mul_f32_e32 v127, v23, v140
	v_mul_f32_e32 v128, v24, v140
	v_mul_f32_e32 v129, v25, v140
	v_mul_f32_e32 v130, v26, v140
	v_mul_f32_e32 v131, v27, v140
	v_mul_f32_e32 v132, v28, v140
	v_mul_f32_e32 v133, v29, v140
	v_mul_f32_e32 v134, v30, v140
	v_mul_f32_e32 v135, v31, v140
	v_fma_f32 v120, v120, v88, v104
	v_fma_f32 v121, v121, v89, v105
	v_fma_f32 v122, v122, v90, v106
	v_fma_f32 v123, v123, v91, v107
	v_fma_f32 v124, v124, v92, v108
	v_fma_f32 v125, v125, v93, v109
	v_fma_f32 v126, v126, v94, v110
	v_fma_f32 v127, v127, v95, v111
	v_fma_f32 v128, v128, v96, v112
	v_fma_f32 v129, v129, v97, v113
	v_fma_f32 v130, v130, v98, v114
	v_fma_f32 v131, v131, v99, v115
	v_fma_f32 v132, v132, v100, v116
	v_fma_f32 v133, v133, v101, v117
	v_fma_f32 v134, v134, v102, v118
	v_fma_f32 v135, v135, v103, v119
	v_cvt_pk_bf16_f32 v156, v120, v121
	v_cvt_pk_bf16_f32 v157, v122, v123
	v_cvt_pk_bf16_f32 v158, v124, v125
	v_cvt_pk_bf16_f32 v159, v126, v127
	v_cvt_pk_bf16_f32 v160, v128, v129
	v_cvt_pk_bf16_f32 v161, v130, v131
	v_cvt_pk_bf16_f32 v162, v132, v133
	v_cvt_pk_bf16_f32 v163, v134, v135
	s_lshl_b32 vcc_lo, s19, 11
	s_add_u32 vcc_lo, vcc_lo, 0x3400000
	s_add_u32 s100, s14, vcc_lo
	s_addc_u32 s101, s15, 0
	global_store_dwordx2 v137, v[156:157], s[100:101] offset:0
	global_store_dwordx2 v137, v[158:159], s[100:101] offset:512
	global_store_dwordx2 v137, v[160:161], s[100:101] offset:1024
	global_store_dwordx2 v137, v[162:163], s[100:101] offset:1536
	s_waitcnt vmcnt(24)
	v_lshlrev_b32_e32 v120, 16, v64
	v_and_b32_e32 v121, 0xffff0000, v64
	v_lshlrev_b32_e32 v122, 16, v65
	v_and_b32_e32 v123, 0xffff0000, v65
	v_lshlrev_b32_e32 v124, 16, v66
	v_and_b32_e32 v125, 0xffff0000, v66
	v_lshlrev_b32_e32 v126, 16, v67
	v_and_b32_e32 v127, 0xffff0000, v67
	v_lshlrev_b32_e32 v128, 16, v68
	v_and_b32_e32 v129, 0xffff0000, v68
	v_lshlrev_b32_e32 v130, 16, v69
	v_and_b32_e32 v131, 0xffff0000, v69
	v_lshlrev_b32_e32 v132, 16, v70
	v_and_b32_e32 v133, 0xffff0000, v70
	v_lshlrev_b32_e32 v134, 16, v71
	v_and_b32_e32 v135, 0xffff0000, v71
	v_mul_f32_e32 v138, v120, v120
	v_mul_f32_e32 v149, v121, v121
	v_mul_f32_e32 v150, v122, v122
	v_mul_f32_e32 v154, v123, v123
	v_fma_f32 v138, v124, v124, v138
	v_fma_f32 v149, v125, v125, v149
	v_fma_f32 v150, v126, v126, v150
	v_fma_f32 v154, v127, v127, v154
	v_fma_f32 v138, v128, v128, v138
	v_fma_f32 v149, v129, v129, v149
	v_fma_f32 v150, v130, v130, v150
	v_fma_f32 v154, v131, v131, v154
	v_fma_f32 v138, v132, v132, v138
	v_fma_f32 v149, v133, v133, v149
	v_fma_f32 v150, v134, v134, v150
	v_fma_f32 v154, v135, v135, v154
	v_add_f32_e32 v138, v138, v149
	v_add_f32_e32 v150, v150, v154
	v_add_f32_e32 v138, v138, v150
	s_nop 1
	v_add_f32_dpp v138, v138, v138 quad_perm:[1,0,3,2] row_mask:0xf bank_mask:0xf
	s_nop 1
	v_add_f32_dpp v138, v138, v138 quad_perm:[2,3,0,1] row_mask:0xf bank_mask:0xf
	s_nop 1
	v_add_f32_dpp v138, v138, v138 row_half_mirror row_mask:0xf bank_mask:0xf
	s_nop 1
	v_add_f32_dpp v138, v138, v138 row_mirror row_mask:0xf bank_mask:0xf
	v_mov_b32_e32 v139, v138
	s_nop 1
	v_permlane16_swap_b32_e32 v138, v139
	v_add_f32_e32 v138, v138, v139
	v_mov_b32_e32 v139, v138
	s_nop 1
	v_permlane32_swap_b32_e32 v138, v139
	v_add_f32_e32 v138, v138, v139
	v_mul_f32_e32 v138, 0x3a800000, v138
	v_add_f32_e32 v138, 0x358637bd, v138
	v_rsq_f32_e32 v140, v138
	v_lshlrev_b32_e32 v32, 16, v40
	v_and_b32_e32 v33, 0xffff0000, v40
	v_lshlrev_b32_e32 v34, 16, v41
	v_and_b32_e32 v35, 0xffff0000, v41
	v_lshlrev_b32_e32 v36, 16, v42
	v_and_b32_e32 v37, 0xffff0000, v42
	v_lshlrev_b32_e32 v38, 16, v43
	v_and_b32_e32 v39, 0xffff0000, v43
	v_lshlrev_b32_e32 v40, 16, v44
	v_and_b32_e32 v41, 0xffff0000, v44
	v_lshlrev_b32_e32 v42, 16, v45
	v_and_b32_e32 v43, 0xffff0000, v45
	v_lshlrev_b32_e32 v44, 16, v46
	v_and_b32_e32 v45, 0xffff0000, v46
	v_lshlrev_b32_e32 v46, 16, v47
	v_and_b32_e32 v47, 0xffff0000, v47
	s_nop 0
	v_mul_f32_e32 v120, v120, v140
	v_mul_f32_e32 v121, v121, v140
	v_mul_f32_e32 v122, v122, v140
	v_mul_f32_e32 v123, v123, v140
	v_mul_f32_e32 v124, v124, v140
	v_mul_f32_e32 v125, v125, v140
	v_mul_f32_e32 v126, v126, v140
	v_mul_f32_e32 v127, v127, v140
	v_mul_f32_e32 v128, v128, v140
	v_mul_f32_e32 v129, v129, v140
	v_mul_f32_e32 v130, v130, v140
	v_mul_f32_e32 v131, v131, v140
	v_mul_f32_e32 v132, v132, v140
	v_mul_f32_e32 v133, v133, v140
	v_mul_f32_e32 v134, v134, v140
	v_mul_f32_e32 v135, v135, v140
	v_fma_f32 v32, v120, v72, v32
	v_fma_f32 v33, v121, v73, v33
	v_fma_f32 v34, v122, v74, v34
	v_fma_f32 v35, v123, v75, v35
	v_fma_f32 v36, v124, v76, v36
	v_fma_f32 v37, v125, v77, v37
	v_fma_f32 v38, v126, v78, v38
	v_fma_f32 v39, v127, v79, v39
	v_fma_f32 v40, v128, v80, v40
	v_fma_f32 v41, v129, v81, v41
	v_fma_f32 v42, v130, v82, v42
	v_fma_f32 v43, v131, v83, v43
	v_fma_f32 v44, v132, v84, v44
	v_fma_f32 v45, v133, v85, v45
	v_fma_f32 v46, v134, v86, v46
; __device__ __forceinline__ void row_phase(const Params& P, int glayer, int layer, int xsrc, bool hasY, int gate_idx, const float* gpost,
;                           int xdst, bool doH, const float* gpre, int sh_idx, int nrows) {
;     ...
;         if (hasY) {
;           float4 yv[4];
;           float ss = 0.f;
; #pragma unroll
;           for (int i = 0; i < 4; ++i) {
;             const uint2 raw = yy[u][i];
;             yv[i].x = bf2f((u16)(raw.x & 0xffff)); yv[i].y = bf2f((u16)(raw.x >> 16));
;             yv[i].z = bf2f((u16)(raw.y & 0xffff)); yv[i].w = bf2f((u16)(raw.y >> 16));
;             ss += yv[i].x * yv[i].x + yv[i].y * yv[i].y + yv[i].z * yv[i].z + yv[i].w * yv[i].w;
;           }
;           ss = wave_sum(ss);
;           const float rstd = __builtin_amdgcn_rsqf(ss * (1.f / 1024.f) + EPSF);
; #pragma unroll
;           for (int i = 0; i < 4; ++i) {
;             const int col = (i * 64 + lane) * 4;
;             const float4 gt = *reinterpret_cast<const float4*>(modg + gate_idx * 1024 + col);
;             const float4 gp = *reinterpret_cast<const float4*>(gpost + col);
;             xv[i].x += gt.x * (yv[i].x * rstd * gp.x); xv[i].y += gt.y * (yv[i].y * rstd * gp.y);
;             xv[i].z += gt.z * (yv[i].z * rstd * gp.z); xv[i].w += gt.w * (yv[i].w * rstd * gp.w);
;           }
;         }
;         if (xdst == 3 || (xdst == 1 && row >= N_X)) {
;           float* xout = (xdst == 3) ? P.out + (long)row * 1024 : P.xc + (long)(row - N_X) * 1024;
; #pragma unroll
;           for (int i = 0; i < 4; ++i) *reinterpret_cast<float4*>(xout + (i * 64 + lane) * 4) = xv[i];
;         } else if (xdst != 0) {
;           u16* xo = ((xdst == 1) ? resA : P.zf) + (long)row * 1024;
; #pragma unroll
;           for (int i = 0; i < 4; ++i) {
;             const unsigned b0 = f2bf(xv[i].x), b1 = f2bf(xv[i].y), b2 = f2bf(xv[i].z), b3 = f2bf(xv[i].w);
;             *reinterpret_cast<uint2*>(xo + (i * 64 + lane) * 4) = make_uint2(b0 | (b1 << 16), b2 | (b3 << 16));
;           }
;         }
;         if (doH) {
;           float ss = 0.f;
; #pragma unroll
;           for (int i = 0; i < 4; ++i) ss += xv[i].x * xv[i].x + xv[i].y * xv[i].y + xv[i].z * xv[i].z + xv[i].w * xv[i].w;
;           ss = wave_sum(ss);
;           const float rstd = __builtin_amdgcn_rsqf(ss * (1.f / 1024.f) + EPSF);
;           u16* h = P.hy + (long)row * 1024;
; #pragma unroll
	v_fma_f32 v47, v135, v87, v47
	v_cvt_pk_bf16_f32 v156, v32, v33
	v_cvt_pk_bf16_f32 v157, v34, v35
	v_cvt_pk_bf16_f32 v158, v36, v37
	v_cvt_pk_bf16_f32 v159, v38, v39
	v_cvt_pk_bf16_f32 v160, v40, v41
	v_cvt_pk_bf16_f32 v161, v42, v43
	v_cvt_pk_bf16_f32 v162, v44, v45
	v_cvt_pk_bf16_f32 v163, v46, v47
	s_lshl_b32 vcc_lo, s19, 11
	s_add_u32 vcc_lo, vcc_lo, 0x3800000
	s_add_u32 s100, s16, vcc_lo
	s_addc_u32 s101, s17, 0
	global_store_dwordx2 v137, v[156:157], s[100:101] offset:0
	global_store_dwordx2 v137, v[158:159], s[100:101] offset:512
	global_store_dwordx2 v137, v[160:161], s[100:101] offset:1024
	global_store_dwordx2 v137, v[162:163], s[100:101] offset:1536
	v_mul_f32_e32 v138, v32, v32
	v_mul_f32_e32 v149, v33, v33
	v_mul_f32_e32 v150, v34, v34
	v_mul_f32_e32 v154, v35, v35
	v_fma_f32 v138, v36, v36, v138
	v_fma_f32 v149, v37, v37, v149
	v_fma_f32 v150, v38, v38, v150
	v_fma_f32 v154, v39, v39, v154
	v_fma_f32 v138, v40, v40, v138
	v_fma_f32 v149, v41, v41, v149
	v_fma_f32 v150, v42, v42, v150
	v_fma_f32 v154, v43, v43, v154
	v_fma_f32 v138, v44, v44, v138
	v_fma_f32 v149, v45, v45, v149
	v_fma_f32 v150, v46, v46, v150
	v_fma_f32 v154, v47, v47, v154
	v_add_f32_e32 v138, v138, v149
	v_add_f32_e32 v150, v150, v154
	v_add_f32_e32 v138, v138, v150
	s_nop 1
	v_add_f32_dpp v138, v138, v138 quad_perm:[1,0,3,2] row_mask:0xf bank_mask:0xf
	s_nop 1
	v_add_f32_dpp v138, v138, v138 quad_perm:[2,3,0,1] row_mask:0xf bank_mask:0xf
	s_nop 1
	v_add_f32_dpp v138, v138, v138 row_half_mirror row_mask:0xf bank_mask:0xf
	s_nop 1
	v_add_f32_dpp v138, v138, v138 row_mirror row_mask:0xf bank_mask:0xf
	v_mov_b32_e32 v139, v138
	s_nop 1
	v_permlane16_swap_b32_e32 v138, v139
	v_add_f32_e32 v138, v138, v139
	v_mov_b32_e32 v139, v138
	s_nop 1
	v_permlane32_swap_b32_e32 v138, v139
	v_add_f32_e32 v138, v138, v139
	v_mul_f32_e32 v138, 0x3a800000, v138
	v_add_f32_e32 v138, 0x358637bd, v138
	v_rsq_f32_e32 v140, v138
	s_nop 0
	v_mul_f32_e32 v120, v32, v140
	v_mul_f32_e32 v121, v33, v140
	v_mul_f32_e32 v122, v34, v140
	v_mul_f32_e32 v123, v35, v140
	v_mul_f32_e32 v124, v36, v140
	v_mul_f32_e32 v125, v37, v140
	v_mul_f32_e32 v126, v38, v140
	v_mul_f32_e32 v127, v39, v140
	v_mul_f32_e32 v128, v40, v140
	v_mul_f32_e32 v129, v41, v140
	v_mul_f32_e32 v130, v42, v140
	v_mul_f32_e32 v131, v43, v140
	v_mul_f32_e32 v132, v44, v140
	v_mul_f32_e32 v133, v45, v140
	v_mul_f32_e32 v134, v46, v140
	v_mul_f32_e32 v135, v47, v140
	v_fma_f32 v120, v120, v88, v104
	v_fma_f32 v121, v121, v89, v105
	v_fma_f32 v122, v122, v90, v106
	v_fma_f32 v123, v123, v91, v107
	v_fma_f32 v124, v124, v92, v108
	v_fma_f32 v125, v125, v93, v109
	v_fma_f32 v126, v126, v94, v110
	v_fma_f32 v127, v127, v95, v111
	v_fma_f32 v128, v128, v96, v112
	v_fma_f32 v129, v129, v97, v113
	v_fma_f32 v130, v130, v98, v114
	v_fma_f32 v131, v131, v99, v115
	v_fma_f32 v132, v132, v100, v116
	v_fma_f32 v133, v133, v101, v117
	v_fma_f32 v134, v134, v102, v118
	v_fma_f32 v135, v135, v103, v119
	v_cvt_pk_bf16_f32 v156, v120, v121
	v_cvt_pk_bf16_f32 v157, v122, v123
	v_cvt_pk_bf16_f32 v158, v124, v125
	v_cvt_pk_bf16_f32 v159, v126, v127
	v_cvt_pk_bf16_f32 v160, v128, v129
	v_cvt_pk_bf16_f32 v161, v130, v131
	v_cvt_pk_bf16_f32 v162, v132, v133
	v_cvt_pk_bf16_f32 v163, v134, v135
	s_lshl_b32 vcc_lo, s19, 11
	s_add_u32 vcc_lo, vcc_lo, 0x3800000
	s_add_u32 s100, s14, vcc_lo
	s_addc_u32 s101, s15, 0
	global_store_dwordx2 v137, v[156:157], s[100:101] offset:0
	global_store_dwordx2 v137, v[158:159], s[100:101] offset:512
	global_store_dwordx2 v137, v[160:161], s[100:101] offset:1024
	global_store_dwordx2 v137, v[162:163], s[100:101] offset:1536
	s_waitcnt vmcnt(16)
	v_lshlrev_b32_e32 v120, 16, v48
	v_and_b32_e32 v121, 0xffff0000, v48
	v_lshlrev_b32_e32 v122, 16, v49
	v_and_b32_e32 v123, 0xffff0000, v49
	v_lshlrev_b32_e32 v124, 16, v50
	v_and_b32_e32 v125, 0xffff0000, v50
	v_lshlrev_b32_e32 v126, 16, v51
	v_and_b32_e32 v127, 0xffff0000, v51
	v_lshlrev_b32_e32 v128, 16, v52
	v_and_b32_e32 v129, 0xffff0000, v52
	v_lshlrev_b32_e32 v130, 16, v53
	v_and_b32_e32 v131, 0xffff0000, v53
	v_lshlrev_b32_e32 v132, 16, v54
	v_and_b32_e32 v133, 0xffff0000, v54
	v_lshlrev_b32_e32 v134, 16, v55
	v_and_b32_e32 v135, 0xffff0000, v55
	v_mul_f32_e32 v138, v120, v120
	v_mul_f32_e32 v149, v121, v121
	v_mul_f32_e32 v150, v122, v122
	v_mul_f32_e32 v154, v123, v123
	v_fma_f32 v138, v124, v124, v138
	v_fma_f32 v149, v125, v125, v149
	v_fma_f32 v150, v126, v126, v150
	v_fma_f32 v154, v127, v127, v154
	v_fma_f32 v138, v128, v128, v138
	v_fma_f32 v149, v129, v129, v149
	v_fma_f32 v150, v130, v130, v150
	v_fma_f32 v154, v131, v131, v154
	v_fma_f32 v138, v132, v132, v138
	v_fma_f32 v149, v133, v133, v149
	v_fma_f32 v150, v134, v134, v150
	v_fma_f32 v154, v135, v135, v154
	v_add_f32_e32 v138, v138, v149
	v_add_f32_e32 v150, v150, v154
	v_add_f32_e32 v138, v138, v150
	s_nop 1
	v_add_f32_dpp v138, v138, v138 quad_perm:[1,0,3,2] row_mask:0xf bank_mask:0xf
	s_nop 1
	v_add_f32_dpp v138, v138, v138 quad_perm:[2,3,0,1] row_mask:0xf bank_mask:0xf
	s_nop 1
	v_add_f32_dpp v138, v138, v138 row_half_mirror row_mask:0xf bank_mask:0xf
	s_nop 1
	v_add_f32_dpp v138, v138, v138 row_mirror row_mask:0xf bank_mask:0xf
	v_mov_b32_e32 v139, v138
	s_nop 1
	v_permlane16_swap_b32_e32 v138, v139
	v_add_f32_e32 v138, v138, v139
	v_mov_b32_e32 v139, v138
	s_nop 1
	v_permlane32_swap_b32_e32 v138, v139
	v_add_f32_e32 v138, v138, v139
	v_mul_f32_e32 v138, 0x3a800000, v138
	v_add_f32_e32 v138, 0x358637bd, v138
	v_rsq_f32_e32 v140, v138
	v_lshlrev_b32_e32 v0, 16, v8
	v_and_b32_e32 v1, 0xffff0000, v8
	v_lshlrev_b32_e32 v2, 16, v9
	v_and_b32_e32 v3, 0xffff0000, v9
	v_lshlrev_b32_e32 v4, 16, v10
; __device__ __forceinline__ void row_phase(const Params& P, int glayer, int layer, int xsrc, bool hasY, int gate_idx, const float* gpost,
;                           int xdst, bool doH, const float* gpre, int sh_idx, int nrows) {
;     ...
;         if (hasY) {
;           float4 yv[4];
;           float ss = 0.f;
; #pragma unroll
;           for (int i = 0; i < 4; ++i) {
;             const uint2 raw = yy[u][i];
;             yv[i].x = bf2f((u16)(raw.x & 0xffff)); yv[i].y = bf2f((u16)(raw.x >> 16));
;             yv[i].z = bf2f((u16)(raw.y & 0xffff)); yv[i].w = bf2f((u16)(raw.y >> 16));
;             ss += yv[i].x * yv[i].x + yv[i].y * yv[i].y + yv[i].z * yv[i].z + yv[i].w * yv[i].w;
;           }
;           ss = wave_sum(ss);
;           const float rstd = __builtin_amdgcn_rsqf(ss * (1.f / 1024.f) + EPSF);
; #pragma unroll
;           for (int i = 0; i < 4; ++i) {
;             const int col = (i * 64 + lane) * 4;
;             const float4 gt = *reinterpret_cast<const float4*>(modg + gate_idx * 1024 + col);
;             const float4 gp = *reinterpret_cast<const float4*>(gpost + col);
;             xv[i].x += gt.x * (yv[i].x * rstd * gp.x); xv[i].y += gt.y * (yv[i].y * rstd * gp.y);
;             xv[i].z += gt.z * (yv[i].z * rstd * gp.z); xv[i].w += gt.w * (yv[i].w * rstd * gp.w);
;           }
;         }
;         if (xdst == 3 || (xdst == 1 && row >= N_X)) {
;           float* xout = (xdst == 3) ? P.out + (long)row * 1024 : P.xc + (long)(row - N_X) * 1024;
; #pragma unroll
;           for (int i = 0; i < 4; ++i) *reinterpret_cast<float4*>(xout + (i * 64 + lane) * 4) = xv[i];
;         } else if (xdst != 0) {
;           u16* xo = ((xdst == 1) ? resA : P.zf) + (long)row * 1024;
; #pragma unroll
;           for (int i = 0; i < 4; ++i) {
;             const unsigned b0 = f2bf(xv[i].x), b1 = f2bf(xv[i].y), b2 = f2bf(xv[i].z), b3 = f2bf(xv[i].w);
;             *reinterpret_cast<uint2*>(xo + (i * 64 + lane) * 4) = make_uint2(b0 | (b1 << 16), b2 | (b3 << 16));
;           }
;         }
;         if (doH) {
;           float ss = 0.f;
; #pragma unroll
;           for (int i = 0; i < 4; ++i) ss += xv[i].x * xv[i].x + xv[i].y * xv[i].y + xv[i].z * xv[i].z + xv[i].w * xv[i].w;
;           ss = wave_sum(ss);
;           const float rstd = __builtin_amdgcn_rsqf(ss * (1.f / 1024.f) + EPSF);
;           u16* h = P.hy + (long)row * 1024;
; #pragma unroll
	v_and_b32_e32 v5, 0xffff0000, v10
	v_lshlrev_b32_e32 v6, 16, v11
	v_and_b32_e32 v7, 0xffff0000, v11
	v_lshlrev_b32_e32 v8, 16, v12
	v_and_b32_e32 v9, 0xffff0000, v12
	v_lshlrev_b32_e32 v10, 16, v13
	v_and_b32_e32 v11, 0xffff0000, v13
	v_lshlrev_b32_e32 v12, 16, v14
	v_and_b32_e32 v13, 0xffff0000, v14
	v_lshlrev_b32_e32 v14, 16, v15
	v_and_b32_e32 v15, 0xffff0000, v15
	s_nop 0
	v_mul_f32_e32 v120, v120, v140
	v_mul_f32_e32 v121, v121, v140
	v_mul_f32_e32 v122, v122, v140
	v_mul_f32_e32 v123, v123, v140
	v_mul_f32_e32 v124, v124, v140
	v_mul_f32_e32 v125, v125, v140
	v_mul_f32_e32 v126, v126, v140
	v_mul_f32_e32 v127, v127, v140
	v_mul_f32_e32 v128, v128, v140
	v_mul_f32_e32 v129, v129, v140
	v_mul_f32_e32 v130, v130, v140
	v_mul_f32_e32 v131, v131, v140
	v_mul_f32_e32 v132, v132, v140
	v_mul_f32_e32 v133, v133, v140
	v_mul_f32_e32 v134, v134, v140
	v_mul_f32_e32 v135, v135, v140
	v_fma_f32 v0, v120, v72, v0
	v_fma_f32 v1, v121, v73, v1
	v_fma_f32 v2, v122, v74, v2
	v_fma_f32 v3, v123, v75, v3
	v_fma_f32 v4, v124, v76, v4
	v_fma_f32 v5, v125, v77, v5
	v_fma_f32 v6, v126, v78, v6
	v_fma_f32 v7, v127, v79, v7
	v_fma_f32 v8, v128, v80, v8
	v_fma_f32 v9, v129, v81, v9
	v_fma_f32 v10, v130, v82, v10
	v_fma_f32 v11, v131, v83, v11
	v_fma_f32 v12, v132, v84, v12
	v_fma_f32 v13, v133, v85, v13
	v_fma_f32 v14, v134, v86, v14
	v_fma_f32 v15, v135, v87, v15
	v_cvt_pk_bf16_f32 v156, v0, v1
	v_cvt_pk_bf16_f32 v157, v2, v3
	v_cvt_pk_bf16_f32 v158, v4, v5
	v_cvt_pk_bf16_f32 v159, v6, v7
	v_cvt_pk_bf16_f32 v160, v8, v9
	v_cvt_pk_bf16_f32 v161, v10, v11
	v_cvt_pk_bf16_f32 v162, v12, v13
	v_cvt_pk_bf16_f32 v163, v14, v15
	s_lshl_b32 vcc_lo, s19, 11
	s_add_u32 vcc_lo, vcc_lo, 0x3c00000
	s_add_u32 s100, s16, vcc_lo
	s_addc_u32 s101, s17, 0
	global_store_dwordx2 v137, v[156:157], s[100:101] offset:0
	global_store_dwordx2 v137, v[158:159], s[100:101] offset:512
	global_store_dwordx2 v137, v[160:161], s[100:101] offset:1024
	global_store_dwordx2 v137, v[162:163], s[100:101] offset:1536
	v_mul_f32_e32 v138, v0, v0
	v_mul_f32_e32 v149, v1, v1
	v_mul_f32_e32 v150, v2, v2
	v_mul_f32_e32 v154, v3, v3
	v_fma_f32 v138, v4, v4, v138
	v_fma_f32 v149, v5, v5, v149
	v_fma_f32 v150, v6, v6, v150
	v_fma_f32 v154, v7, v7, v154
	v_fma_f32 v138, v8, v8, v138
	v_fma_f32 v149, v9, v9, v149
	v_fma_f32 v150, v10, v10, v150
	v_fma_f32 v154, v11, v11, v154
	v_fma_f32 v138, v12, v12, v138
	v_fma_f32 v149, v13, v13, v149
	v_fma_f32 v150, v14, v14, v150
	v_fma_f32 v154, v15, v15, v154
	v_add_f32_e32 v138, v138, v149
	v_add_f32_e32 v150, v150, v154
	v_add_f32_e32 v138, v138, v150
	s_nop 1
	v_add_f32_dpp v138, v138, v138 quad_perm:[1,0,3,2] row_mask:0xf bank_mask:0xf
	s_nop 1
	v_add_f32_dpp v138, v138, v138 quad_perm:[2,3,0,1] row_mask:0xf bank_mask:0xf
	s_nop 1
	v_add_f32_dpp v138, v138, v138 row_half_mirror row_mask:0xf bank_mask:0xf
	s_nop 1
	v_add_f32_dpp v138, v138, v138 row_mirror row_mask:0xf bank_mask:0xf
	v_mov_b32_e32 v139, v138
	s_nop 1
	v_permlane16_swap_b32_e32 v138, v139
	v_add_f32_e32 v138, v138, v139
	v_mov_b32_e32 v139, v138
	s_nop 1
	v_permlane32_swap_b32_e32 v138, v139
	v_add_f32_e32 v138, v138, v139
	v_mul_f32_e32 v138, 0x3a800000, v138
	v_add_f32_e32 v138, 0x358637bd, v138
	v_rsq_f32_e32 v140, v138
	s_nop 0
	v_mul_f32_e32 v120, v0, v140
	v_mul_f32_e32 v121, v1, v140
	v_mul_f32_e32 v122, v2, v140
	v_mul_f32_e32 v123, v3, v140
	v_mul_f32_e32 v124, v4, v140
	v_mul_f32_e32 v125, v5, v140
	v_mul_f32_e32 v126, v6, v140
	v_mul_f32_e32 v127, v7, v140
	v_mul_f32_e32 v128, v8, v140
	v_mul_f32_e32 v129, v9, v140
	v_mul_f32_e32 v130, v10, v140
	v_mul_f32_e32 v131, v11, v140
	v_mul_f32_e32 v132, v12, v140
	v_mul_f32_e32 v133, v13, v140
	v_mul_f32_e32 v134, v14, v140
	v_mul_f32_e32 v135, v15, v140
	v_fma_f32 v120, v120, v88, v104
	v_fma_f32 v121, v121, v89, v105
	v_fma_f32 v122, v122, v90, v106
	v_fma_f32 v123, v123, v91, v107
	v_fma_f32 v124, v124, v92, v108
	v_fma_f32 v125, v125, v93, v109
	v_fma_f32 v126, v126, v94, v110
	v_fma_f32 v127, v127, v95, v111
	v_fma_f32 v128, v128, v96, v112
	v_fma_f32 v129, v129, v97, v113
	v_fma_f32 v130, v130, v98, v114
	v_fma_f32 v131, v131, v99, v115
	v_fma_f32 v132, v132, v100, v116
	v_fma_f32 v133, v133, v101, v117
	v_fma_f32 v134, v134, v102, v118
	v_fma_f32 v135, v135, v103, v119
	v_cvt_pk_bf16_f32 v156, v120, v121
	v_cvt_pk_bf16_f32 v157, v122, v123
	v_cvt_pk_bf16_f32 v158, v124, v125
	v_cvt_pk_bf16_f32 v159, v126, v127
	v_cvt_pk_bf16_f32 v160, v128, v129
	v_cvt_pk_bf16_f32 v161, v130, v131
	v_cvt_pk_bf16_f32 v162, v132, v133
	v_cvt_pk_bf16_f32 v163, v134, v135
	s_lshl_b32 vcc_lo, s19, 11
	s_add_u32 vcc_lo, vcc_lo, 0x3c00000
	s_add_u32 s100, s14, vcc_lo
	s_addc_u32 s101, s15, 0
	global_store_dwordx2 v137, v[156:157], s[100:101] offset:0
	global_store_dwordx2 v137, v[158:159], s[100:101] offset:512
	global_store_dwordx2 v137, v[160:161], s[100:101] offset:1024
	global_store_dwordx2 v137, v[162:163], s[100:101] offset:1536
	s_waitcnt vmcnt(0)
	s_cmp_lt_u32 s19, 0x400
	s_cbranch_scc0 .Lmy_r10_done
; __device__ __forceinline__ void row_phase(const Params& P, int glayer, int layer, int xsrc, bool hasY, int gate_idx, const float* gpost,
;                           int xdst, bool doH, const float* gpre, int sh_idx, int nrows) {
;     ...
;           if (xsrc == 0) xin_ = R < N_X ? P.x + (long)R * 1024 : P.ctx + (long)(R - N_X) * 1024;
;           else           xin_ = P.xc + (long)(R - N_X) * 1024;
; #pragma unroll
;           for (int i = 0; i < 4; ++i) xr[u][i] = *reinterpret_cast<const uint4*>(xin_ + (i * 64 + lane) * 4);
;         }
;         if (hasY) {
;           const u16* y_ = P.hy + (long)R * 1024;
; #pragma unroll
;           for (int i = 0; i < 4; ++i) yy[u][i] = *reinterpret_cast<const uint2*>(y_ + (i * 64 + lane) * 4);
;         }
;       }
;     }
; #pragma unroll
;     for (int u = 0; u < 4; ++u) {
;       const int row = rb + u * stride;
;       if (row < nrows) {
;         const int mi = row < N_X ? (row >> 13) : 4;
;         const float* modp = P.mod + (long)(layer * 5 + mi) * 6144;
;         const float* modg = P.mod + (long)(glayer * 5 + mi) * 6144;
;         float4 xv[4];
;         if (xsrc != 0 && row < N_X) {
; #pragma unroll
;           for (int i = 0; i < 4; ++i) {
;             const uint4 raw = xr[u][i];
;             xv[i].x = bf2f((u16)(raw.x & 0xffff)); xv[i].y = bf2f((u16)(raw.x >> 16));
;             xv[i].z = bf2f((u16)(raw.y & 0xffff)); xv[i].w = bf2f((u16)(raw.y >> 16));
;           }
;         } else {
; #pragma unroll
;           for (int i = 0; i < 4; ++i) {
;             xv[i].x = __uint_as_float(xr[u][i].x); xv[i].y = __uint_as_float(xr[u][i].y);
;             xv[i].z = __uint_as_float(xr[u][i].z); xv[i].w = __uint_as_float(xr[u][i].w);
;           }
;         }
;         if (hasY) {
;           float4 yv[4];
;           float ss = 0.f;
; #pragma unroll
;           for (int i = 0; i < 4; ++i) {
;             const uint2 raw = yy[u][i];
;             yv[i].x = bf2f((u16)(raw.x & 0xffff)); yv[i].y = bf2f((u16)(raw.x >> 16));
;             yv[i].z = bf2f((u16)(raw.y & 0xffff)); yv[i].w = bf2f((u16)(raw.y >> 16));
;             ss += yv[i].x * yv[i].x + yv[i].y * yv[i].y + yv[i].z * yv[i].z + yv[i].w * yv[i].w;
;           }
;           ss = wave_sum(ss);
;           const float rstd = __builtin_amdgcn_rsqf(ss * (1.f / 1024.f) + EPSF);
; #pragma unroll
;           for (int i = 0; i < 4; ++i) {
	s_load_dwordx2 s[12:13], s[4:5], 0x138
	s_waitcnt lgkmcnt(0)
	s_add_u32 s100, s20, 0x1d000
	s_addc_u32 s101, s21, 0
	global_load_dwordx4 v[72:75], v136, s[100:101] offset:0
	global_load_dwordx4 v[76:79], v136, s[100:101] offset:1024
	global_load_dwordx4 v[80:83], v136, s[100:101] offset:2048
	global_load_dwordx4 v[84:87], v136, s[100:101] offset:3072
	s_load_dwordx2 s[98:99], s[4:5], 0x48
	s_waitcnt lgkmcnt(0)
	global_load_dwordx4 v[120:123], v136, s[98:99] offset:0
	global_load_dwordx4 v[124:127], v136, s[98:99] offset:1024
	global_load_dwordx4 v[128:131], v136, s[98:99] offset:2048
	global_load_dwordx4 v[132:135], v136, s[98:99] offset:3072
	s_add_u32 s100, s20, 0x36000
	s_addc_u32 s101, s21, 0
	global_load_dwordx4 v[104:107], v136, s[100:101] offset:0
	global_load_dwordx4 v[108:111], v136, s[100:101] offset:1024
	global_load_dwordx4 v[112:115], v136, s[100:101] offset:2048
	global_load_dwordx4 v[116:119], v136, s[100:101] offset:3072
	s_add_u32 s100, s100, 0x1000
	s_addc_u32 s101, s101, 0
	global_load_dwordx4 v[16:19], v136, s[100:101] offset:0
	global_load_dwordx4 v[20:23], v136, s[100:101] offset:1024
	global_load_dwordx4 v[24:27], v136, s[100:101] offset:2048
	global_load_dwordx4 v[28:31], v136, s[100:101] offset:3072
	s_load_dwordx2 s[98:99], s[4:5], 0x30
	s_waitcnt lgkmcnt(0)
	s_add_u32 s98, s98, 0x1000
	s_addc_u32 s99, s99, 0
	global_load_dwordx4 v[88:91], v136, s[98:99] offset:0
	global_load_dwordx4 v[92:95], v136, s[98:99] offset:1024
	global_load_dwordx4 v[96:99], v136, s[98:99] offset:2048
	global_load_dwordx4 v[100:103], v136, s[98:99] offset:3072
	s_waitcnt vmcnt(0)
	v_mul_f32_e32 v72, v72, v120
	v_mul_f32_e32 v73, v73, v121
	v_mul_f32_e32 v74, v74, v122
	v_mul_f32_e32 v75, v75, v123
	v_mul_f32_e32 v76, v76, v124
	v_mul_f32_e32 v77, v77, v125
	v_mul_f32_e32 v78, v78, v126
	v_mul_f32_e32 v79, v79, v127
	v_mul_f32_e32 v80, v80, v128
	v_mul_f32_e32 v81, v81, v129
	v_mul_f32_e32 v82, v82, v130
	v_mul_f32_e32 v83, v83, v131
	v_mul_f32_e32 v84, v84, v132
	v_mul_f32_e32 v85, v85, v133
	v_mul_f32_e32 v86, v86, v134
	v_mul_f32_e32 v87, v87, v135
	v_fma_f32 v88, v88, v16, v88
	v_fma_f32 v89, v89, v17, v89
	v_fma_f32 v90, v90, v18, v90
	v_fma_f32 v91, v91, v19, v91
	v_fma_f32 v92, v92, v20, v92
	v_fma_f32 v93, v93, v21, v93
	v_fma_f32 v94, v94, v22, v94
	v_fma_f32 v95, v95, v23, v95
	v_fma_f32 v96, v96, v24, v96
	v_fma_f32 v97, v97, v25, v97
	v_fma_f32 v98, v98, v26, v98
	v_fma_f32 v99, v99, v27, v99
	v_fma_f32 v100, v100, v28, v100
	v_fma_f32 v101, v101, v29, v101
	v_fma_f32 v102, v102, v30, v102
	v_fma_f32 v103, v103, v31, v103
	s_lshl_b32 vcc_lo, s19, 12
	s_add_u32 s100, s12, vcc_lo
	s_addc_u32 s101, s13, 0
	global_load_dwordx4 v[0:3], v136, s[100:101] offset:0
	global_load_dwordx4 v[4:7], v136, s[100:101] offset:1024
	global_load_dwordx4 v[8:11], v136, s[100:101] offset:2048
	global_load_dwordx4 v[12:15], v136, s[100:101] offset:3072
	s_load_dwordx2 s[98:99], s[4:5], 0x158
	s_waitcnt lgkmcnt(0)
	s_lshl_b32 vcc_lo, s19, 12
	s_add_u32 s100, s98, vcc_lo
	s_addc_u32 s101, s99, 0
	global_load_dwordx4 v[120:123], v136, s[100:101] offset:0
	global_load_dwordx4 v[124:127], v136, s[100:101] offset:1024
	global_load_dwordx4 v[128:131], v136, s[100:101] offset:2048
	global_load_dwordx4 v[132:135], v136, s[100:101] offset:3072
	s_add_u32 s100, s100, 0x400000
	s_addc_u32 s101, s101, 0
	global_load_dwordx4 v[16:19], v136, s[100:101] offset:0
	global_load_dwordx4 v[20:23], v136, s[100:101] offset:1024
	global_load_dwordx4 v[24:27], v136, s[100:101] offset:2048
	global_load_dwordx4 v[28:31], v136, s[100:101] offset:3072
	s_add_u32 s100, s100, 0x400000
	s_addc_u32 s101, s101, 0
	global_load_dwordx4 v[32:35], v136, s[100:101] offset:0
	global_load_dwordx4 v[36:39], v136, s[100:101] offset:1024
	global_load_dwordx4 v[40:43], v136, s[100:101] offset:2048
	global_load_dwordx4 v[44:47], v136, s[100:101] offset:3072
	s_add_u32 s100, s100, 0x400000
	s_addc_u32 s101, s101, 0
	global_load_dwordx4 v[48:51], v136, s[100:101] offset:0
	global_load_dwordx4 v[52:55], v136, s[100:101] offset:1024
	global_load_dwordx4 v[56:59], v136, s[100:101] offset:2048
	global_load_dwordx4 v[60:63], v136, s[100:101] offset:3072
	s_add_u32 s100, s100, 0x400000
	s_addc_u32 s101, s101, 0
	s_waitcnt vmcnt(8)
	v_add_f32_e32 v120, v120, v16
	v_add_f32_e32 v121, v121, v17
	v_add_f32_e32 v122, v122, v18
	v_add_f32_e32 v123, v123, v19
	v_add_f32_e32 v124, v124, v20
	v_add_f32_e32 v125, v125, v21
	v_add_f32_e32 v126, v126, v22
	v_add_f32_e32 v127, v127, v23
	v_add_f32_e32 v128, v128, v24
	v_add_f32_e32 v129, v129, v25
	v_add_f32_e32 v130, v130, v26
	v_add_f32_e32 v131, v131, v27
	v_add_f32_e32 v132, v132, v28
	v_add_f32_e32 v133, v133, v29
	v_add_f32_e32 v134, v134, v30
	v_add_f32_e32 v135, v135, v31
	global_load_dwordx4 v[16:19], v136, s[100:101] offset:0
	global_load_dwordx4 v[20:23], v136, s[100:101] offset:1024
	global_load_dwordx4 v[24:27], v136, s[100:101] offset:2048
	global_load_dwordx4 v[28:31], v136, s[100:101] offset:3072
	s_add_u32 s100, s100, 0x400000
	s_addc_u32 s101, s101, 0
	s_waitcnt vmcnt(8)
	v_add_f32_e32 v120, v120, v32
	v_add_f32_e32 v121, v121, v33
	v_add_f32_e32 v122, v122, v34
	v_add_f32_e32 v123, v123, v35
	v_add_f32_e32 v124, v124, v36
	v_add_f32_e32 v125, v125, v37
	v_add_f32_e32 v126, v126, v38
	v_add_f32_e32 v127, v127, v39
	v_add_f32_e32 v128, v128, v40
	v_add_f32_e32 v129, v129, v41
	v_add_f32_e32 v130, v130, v42
	v_add_f32_e32 v131, v131, v43
	v_add_f32_e32 v132, v132, v44
	v_add_f32_e32 v133, v133, v45
	v_add_f32_e32 v134, v134, v46
	v_add_f32_e32 v135, v135, v47
	global_load_dwordx4 v[32:35], v136, s[100:101] offset:0
	global_load_dwordx4 v[36:39], v136, s[100:101] offset:1024
	global_load_dwordx4 v[40:43], v136, s[100:101] offset:2048
	global_load_dwordx4 v[44:47], v136, s[100:101] offset:3072
	s_add_u32 s100, s100, 0x400000
	s_addc_u32 s101, s101, 0
	s_waitcnt vmcnt(8)
; __device__ __forceinline__ float bf2f(u16 h) { return __uint_as_float(((unsigned)h) << 16); }
; __device__ __forceinline__ void row_phase(const Params& P, int glayer, int layer, int xsrc, bool hasY, int gate_idx, const float* gpost,
;                           int xdst, bool doH, const float* gpre, int sh_idx, int nrows) {
;     ...
;         if (hasY) {
;           float4 yv[4];
;           float ss = 0.f;
; #pragma unroll
;           for (int i = 0; i < 4; ++i) {
;             const uint2 raw = yy[u][i];
;             yv[i].x = bf2f((u16)(raw.x & 0xffff)); yv[i].y = bf2f((u16)(raw.x >> 16));
;             yv[i].z = bf2f((u16)(raw.y & 0xffff)); yv[i].w = bf2f((u16)(raw.y >> 16));
;             ss += yv[i].x * yv[i].x + yv[i].y * yv[i].y + yv[i].z * yv[i].z + yv[i].w * yv[i].w;
;           }
;           ss = wave_sum(ss);
;           const float rstd = __builtin_amdgcn_rsqf(ss * (1.f / 1024.f) + EPSF);
; #pragma unroll
;           for (int i = 0; i < 4; ++i) {
;             const int col = (i * 64 + lane) * 4;
;             const float4 gt = *reinterpret_cast<const float4*>(modg + gate_idx * 1024 + col);
;             const float4 gp = *reinterpret_cast<const float4*>(gpost + col);
;             xv[i].x += gt.x * (yv[i].x * rstd * gp.x); xv[i].y += gt.y * (yv[i].y * rstd * gp.y);
;             xv[i].z += gt.z * (yv[i].z * rstd * gp.z); xv[i].w += gt.w * (yv[i].w * rstd * gp.w);
;           }
	v_add_f32_e32 v120, v120, v48
	v_add_f32_e32 v121, v121, v49
	v_add_f32_e32 v122, v122, v50
	v_add_f32_e32 v123, v123, v51
	v_add_f32_e32 v124, v124, v52
	v_add_f32_e32 v125, v125, v53
	v_add_f32_e32 v126, v126, v54
	v_add_f32_e32 v127, v127, v55
	v_add_f32_e32 v128, v128, v56
	v_add_f32_e32 v129, v129, v57
	v_add_f32_e32 v130, v130, v58
	v_add_f32_e32 v131, v131, v59
	v_add_f32_e32 v132, v132, v60
	v_add_f32_e32 v133, v133, v61
	v_add_f32_e32 v134, v134, v62
	v_add_f32_e32 v135, v135, v63
	global_load_dwordx4 v[48:51], v136, s[100:101] offset:0
	global_load_dwordx4 v[52:55], v136, s[100:101] offset:1024
	global_load_dwordx4 v[56:59], v136, s[100:101] offset:2048
	global_load_dwordx4 v[60:63], v136, s[100:101] offset:3072
	s_add_u32 s100, s100, 0x400000
	s_addc_u32 s101, s101, 0
	s_waitcnt vmcnt(8)
	v_add_f32_e32 v120, v120, v16
	v_add_f32_e32 v121, v121, v17
	v_add_f32_e32 v122, v122, v18
	v_add_f32_e32 v123, v123, v19
	v_add_f32_e32 v124, v124, v20
	v_add_f32_e32 v125, v125, v21
	v_add_f32_e32 v126, v126, v22
	v_add_f32_e32 v127, v127, v23
	v_add_f32_e32 v128, v128, v24
	v_add_f32_e32 v129, v129, v25
	v_add_f32_e32 v130, v130, v26
	v_add_f32_e32 v131, v131, v27
	v_add_f32_e32 v132, v132, v28
	v_add_f32_e32 v133, v133, v29
	v_add_f32_e32 v134, v134, v30
	v_add_f32_e32 v135, v135, v31
	global_load_dwordx4 v[16:19], v136, s[100:101] offset:0
	global_load_dwordx4 v[20:23], v136, s[100:101] offset:1024
	global_load_dwordx4 v[24:27], v136, s[100:101] offset:2048
	global_load_dwordx4 v[28:31], v136, s[100:101] offset:3072
	s_add_u32 s100, s100, 0x400000
	s_addc_u32 s101, s101, 0
	s_waitcnt vmcnt(8)
	v_add_f32_e32 v120, v120, v32
	v_add_f32_e32 v121, v121, v33
	v_add_f32_e32 v122, v122, v34
	v_add_f32_e32 v123, v123, v35
	v_add_f32_e32 v124, v124, v36
	v_add_f32_e32 v125, v125, v37
	v_add_f32_e32 v126, v126, v38
	v_add_f32_e32 v127, v127, v39
	v_add_f32_e32 v128, v128, v40
	v_add_f32_e32 v129, v129, v41
	v_add_f32_e32 v130, v130, v42
	v_add_f32_e32 v131, v131, v43
	v_add_f32_e32 v132, v132, v44
	v_add_f32_e32 v133, v133, v45
	v_add_f32_e32 v134, v134, v46
	v_add_f32_e32 v135, v135, v47
	s_waitcnt vmcnt(4)
	v_add_f32_e32 v120, v120, v48
	v_add_f32_e32 v121, v121, v49
	v_add_f32_e32 v122, v122, v50
	v_add_f32_e32 v123, v123, v51
	v_add_f32_e32 v124, v124, v52
	v_add_f32_e32 v125, v125, v53
	v_add_f32_e32 v126, v126, v54
	v_add_f32_e32 v127, v127, v55
	v_add_f32_e32 v128, v128, v56
	v_add_f32_e32 v129, v129, v57
	v_add_f32_e32 v130, v130, v58
	v_add_f32_e32 v131, v131, v59
	v_add_f32_e32 v132, v132, v60
	v_add_f32_e32 v133, v133, v61
	v_add_f32_e32 v134, v134, v62
	v_add_f32_e32 v135, v135, v63
	s_waitcnt vmcnt(0)
	v_add_f32_e32 v120, v120, v16
	v_add_f32_e32 v121, v121, v17
	v_add_f32_e32 v122, v122, v18
	v_add_f32_e32 v123, v123, v19
	v_add_f32_e32 v124, v124, v20
	v_add_f32_e32 v125, v125, v21
	v_add_f32_e32 v126, v126, v22
	v_add_f32_e32 v127, v127, v23
	v_add_f32_e32 v128, v128, v24
	v_add_f32_e32 v129, v129, v25
	v_add_f32_e32 v130, v130, v26
	v_add_f32_e32 v131, v131, v27
	v_add_f32_e32 v132, v132, v28
	v_add_f32_e32 v133, v133, v29
	v_add_f32_e32 v134, v134, v30
	v_add_f32_e32 v135, v135, v31
	v_cvt_pk_bf16_f32 v149, v120, v121
	v_lshlrev_b32_e32 v120, 16, v149
	v_and_b32_e32 v121, 0xffff0000, v149
	v_cvt_pk_bf16_f32 v149, v122, v123
	v_lshlrev_b32_e32 v122, 16, v149
	v_and_b32_e32 v123, 0xffff0000, v149
	v_cvt_pk_bf16_f32 v149, v124, v125
	v_lshlrev_b32_e32 v124, 16, v149
	v_and_b32_e32 v125, 0xffff0000, v149
	v_cvt_pk_bf16_f32 v149, v126, v127
	v_lshlrev_b32_e32 v126, 16, v149
	v_and_b32_e32 v127, 0xffff0000, v149
	v_cvt_pk_bf16_f32 v149, v128, v129
	v_lshlrev_b32_e32 v128, 16, v149
	v_and_b32_e32 v129, 0xffff0000, v149
	v_cvt_pk_bf16_f32 v149, v130, v131
	v_lshlrev_b32_e32 v130, 16, v149
	v_and_b32_e32 v131, 0xffff0000, v149
	v_cvt_pk_bf16_f32 v149, v132, v133
	v_lshlrev_b32_e32 v132, 16, v149
	v_and_b32_e32 v133, 0xffff0000, v149
	v_cvt_pk_bf16_f32 v149, v134, v135
	v_lshlrev_b32_e32 v134, 16, v149
	v_and_b32_e32 v135, 0xffff0000, v149
	v_mul_f32_e32 v138, v120, v120
	v_mul_f32_e32 v149, v121, v121
	v_mul_f32_e32 v150, v122, v122
	v_mul_f32_e32 v154, v123, v123
	v_fma_f32 v138, v124, v124, v138
	v_fma_f32 v149, v125, v125, v149
	v_fma_f32 v150, v126, v126, v150
	v_fma_f32 v154, v127, v127, v154
	v_fma_f32 v138, v128, v128, v138
	v_fma_f32 v149, v129, v129, v149
	v_fma_f32 v150, v130, v130, v150
	v_fma_f32 v154, v131, v131, v154
	v_fma_f32 v138, v132, v132, v138
	v_fma_f32 v149, v133, v133, v149
	v_fma_f32 v150, v134, v134, v150
	v_fma_f32 v154, v135, v135, v154
	v_add_f32_e32 v138, v138, v149
	v_add_f32_e32 v150, v150, v154
	v_add_f32_e32 v138, v138, v150
	s_nop 1
	v_add_f32_dpp v138, v138, v138 quad_perm:[1,0,3,2] row_mask:0xf bank_mask:0xf
	s_nop 1
	v_add_f32_dpp v138, v138, v138 quad_perm:[2,3,0,1] row_mask:0xf bank_mask:0xf
	s_nop 1
	v_add_f32_dpp v138, v138, v138 row_half_mirror row_mask:0xf bank_mask:0xf
	s_nop 1
	v_add_f32_dpp v138, v138, v138 row_mirror row_mask:0xf bank_mask:0xf
	v_mov_b32_e32 v139, v138
	s_nop 1
	v_permlane16_swap_b32_e32 v138, v139
	v_add_f32_e32 v138, v138, v139
	v_mov_b32_e32 v139, v138
	s_nop 1
	v_permlane32_swap_b32_e32 v138, v139
	v_add_f32_e32 v138, v138, v139
	v_mul_f32_e32 v138, 0x3a800000, v138
	v_add_f32_e32 v138, 0x358637bd, v138
	v_rsq_f32_e32 v140, v138
	s_nop 0
	v_mul_f32_e32 v120, v120, v140
	v_mul_f32_e32 v121, v121, v140
	v_mul_f32_e32 v122, v122, v140
	v_mul_f32_e32 v123, v123, v140
	v_mul_f32_e32 v124, v124, v140
	v_mul_f32_e32 v125, v125, v140
	v_mul_f32_e32 v126, v126, v140
	v_mul_f32_e32 v127, v127, v140
	v_mul_f32_e32 v128, v128, v140
	v_mul_f32_e32 v129, v129, v140
	v_mul_f32_e32 v130, v130, v140
	v_mul_f32_e32 v131, v131, v140
	v_mul_f32_e32 v132, v132, v140
	v_mul_f32_e32 v133, v133, v140
	v_mul_f32_e32 v134, v134, v140
	v_mul_f32_e32 v135, v135, v140
	v_fma_f32 v0, v120, v72, v0
	v_fma_f32 v1, v121, v73, v1
	v_fma_f32 v2, v122, v74, v2
	v_fma_f32 v3, v123, v75, v3
	v_fma_f32 v4, v124, v76, v4
	v_fma_f32 v5, v125, v77, v5
	v_fma_f32 v6, v126, v78, v6
	v_fma_f32 v7, v127, v79, v7
	v_fma_f32 v8, v128, v80, v8
	v_fma_f32 v9, v129, v81, v9
	v_fma_f32 v10, v130, v82, v10
	v_fma_f32 v11, v131, v83, v11
	v_fma_f32 v12, v132, v84, v12
	v_fma_f32 v13, v133, v85, v13
	v_fma_f32 v14, v134, v86, v14
	v_fma_f32 v15, v135, v87, v15
	s_load_dwordx2 s[98:99], s[4:5], 0x138
	s_waitcnt lgkmcnt(0)
; __device__ __forceinline__ void row_phase(const Params& P, int glayer, int layer, int xsrc, bool hasY, int gate_idx, const float* gpost,
;                           int xdst, bool doH, const float* gpre, int sh_idx, int nrows) {
;     ...
;         if (xdst == 3 || (xdst == 1 && row >= N_X)) {
;           float* xout = (xdst == 3) ? P.out + (long)row * 1024 : P.xc + (long)(row - N_X) * 1024;
; #pragma unroll
;           for (int i = 0; i < 4; ++i) *reinterpret_cast<float4*>(xout + (i * 64 + lane) * 4) = xv[i];
;         } else if (xdst != 0) {
;           u16* xo = ((xdst == 1) ? resA : P.zf) + (long)row * 1024;
; #pragma unroll
;           for (int i = 0; i < 4; ++i) {
;             const unsigned b0 = f2bf(xv[i].x), b1 = f2bf(xv[i].y), b2 = f2bf(xv[i].z), b3 = f2bf(xv[i].w);
;             *reinterpret_cast<uint2*>(xo + (i * 64 + lane) * 4) = make_uint2(b0 | (b1 << 16), b2 | (b3 << 16));
;           }
;         }
;         if (doH) {
;           float ss = 0.f;
; #pragma unroll
;           for (int i = 0; i < 4; ++i) ss += xv[i].x * xv[i].x + xv[i].y * xv[i].y + xv[i].z * xv[i].z + xv[i].w * xv[i].w;
;           ss = wave_sum(ss);
;           const float rstd = __builtin_amdgcn_rsqf(ss * (1.f / 1024.f) + EPSF);
;           u16* h = P.hy + (long)row * 1024;
; #pragma unroll
;           for (int i = 0; i < 4; ++i) {
;             const int col = (i * 64 + lane) * 4;
;             const float4 g = *reinterpret_cast<const float4*>(gpre + col);
;             const float4 sh = *reinterpret_cast<const float4*>(modp + sh_idx * 1024 + col);
;             const float4 sc = *reinterpret_cast<const float4*>(modp + (sh_idx + 1) * 1024 + col);
;             const unsigned h0 = f2bf(xv[i].x * rstd * g.x * (1.f + sc.x) + sh.x);
;             const unsigned h1 = f2bf(xv[i].y * rstd * g.y * (1.f + sc.y) + sh.y);
;             const unsigned h2 = f2bf(xv[i].z * rstd * g.z * (1.f + sc.z) + sh.z);
;             const unsigned h3 = f2bf(xv[i].w * rstd * g.w * (1.f + sc.w) + sh.w);
;             *reinterpret_cast<uint2*>(h + col) = make_uint2(h0 | (h1 << 16), h2 | (h3 << 16));
;           }
	s_lshl_b32 vcc_lo, s19, 12
	s_add_u32 s100, s98, vcc_lo
	s_addc_u32 s101, s99, 0
	global_store_dwordx4 v136, v[0:3], s[100:101] offset:0
	global_store_dwordx4 v136, v[4:7], s[100:101] offset:1024
	global_store_dwordx4 v136, v[8:11], s[100:101] offset:2048
	global_store_dwordx4 v136, v[12:15], s[100:101] offset:3072
	v_mul_f32_e32 v138, v0, v0
	v_mul_f32_e32 v149, v1, v1
	v_mul_f32_e32 v150, v2, v2
	v_mul_f32_e32 v154, v3, v3
	v_fma_f32 v138, v4, v4, v138
	v_fma_f32 v149, v5, v5, v149
	v_fma_f32 v150, v6, v6, v150
	v_fma_f32 v154, v7, v7, v154
	v_fma_f32 v138, v8, v8, v138
	v_fma_f32 v149, v9, v9, v149
	v_fma_f32 v150, v10, v10, v150
	v_fma_f32 v154, v11, v11, v154
	v_fma_f32 v138, v12, v12, v138
	v_fma_f32 v149, v13, v13, v149
	v_fma_f32 v150, v14, v14, v150
	v_fma_f32 v154, v15, v15, v154
	v_add_f32_e32 v138, v138, v149
	v_add_f32_e32 v150, v150, v154
	v_add_f32_e32 v138, v138, v150
	s_nop 1
	v_add_f32_dpp v138, v138, v138 quad_perm:[1,0,3,2] row_mask:0xf bank_mask:0xf
	s_nop 1
	v_add_f32_dpp v138, v138, v138 quad_perm:[2,3,0,1] row_mask:0xf bank_mask:0xf
	s_nop 1
	v_add_f32_dpp v138, v138, v138 row_half_mirror row_mask:0xf bank_mask:0xf
	s_nop 1
	v_add_f32_dpp v138, v138, v138 row_mirror row_mask:0xf bank_mask:0xf
	v_mov_b32_e32 v139, v138
	s_nop 1
	v_permlane16_swap_b32_e32 v138, v139
	v_add_f32_e32 v138, v138, v139
	v_mov_b32_e32 v139, v138
	s_nop 1
	v_permlane32_swap_b32_e32 v138, v139
	v_add_f32_e32 v138, v138, v139
	v_mul_f32_e32 v138, 0x3a800000, v138
	v_add_f32_e32 v138, 0x358637bd, v138
	v_rsq_f32_e32 v140, v138
	s_nop 0
	v_mul_f32_e32 v120, v0, v140
	v_mul_f32_e32 v121, v1, v140
	v_mul_f32_e32 v122, v2, v140
	v_mul_f32_e32 v123, v3, v140
	v_mul_f32_e32 v124, v4, v140
	v_mul_f32_e32 v125, v5, v140
	v_mul_f32_e32 v126, v6, v140
	v_mul_f32_e32 v127, v7, v140
	v_mul_f32_e32 v128, v8, v140
	v_mul_f32_e32 v129, v9, v140
	v_mul_f32_e32 v130, v10, v140
	v_mul_f32_e32 v131, v11, v140
	v_mul_f32_e32 v132, v12, v140
	v_mul_f32_e32 v133, v13, v140
	v_mul_f32_e32 v134, v14, v140
	v_mul_f32_e32 v135, v15, v140
	v_fma_f32 v120, v120, v88, v104
	v_fma_f32 v121, v121, v89, v105
	v_fma_f32 v122, v122, v90, v106
	v_fma_f32 v123, v123, v91, v107
	v_fma_f32 v124, v124, v92, v108
	v_fma_f32 v125, v125, v93, v109
	v_fma_f32 v126, v126, v94, v110
	v_fma_f32 v127, v127, v95, v111
	v_fma_f32 v128, v128, v96, v112
	v_fma_f32 v129, v129, v97, v113
	v_fma_f32 v130, v130, v98, v114
	v_fma_f32 v131, v131, v99, v115
	v_fma_f32 v132, v132, v100, v116
	v_fma_f32 v133, v133, v101, v117
	v_fma_f32 v134, v134, v102, v118
	v_fma_f32 v135, v135, v103, v119
	v_cvt_pk_bf16_f32 v156, v120, v121
	v_cvt_pk_bf16_f32 v157, v122, v123
	v_cvt_pk_bf16_f32 v158, v124, v125
	v_cvt_pk_bf16_f32 v159, v126, v127
	v_cvt_pk_bf16_f32 v160, v128, v129
	v_cvt_pk_bf16_f32 v161, v130, v131
	v_cvt_pk_bf16_f32 v162, v132, v133
	v_cvt_pk_bf16_f32 v163, v134, v135
	s_lshl_b32 vcc_lo, s19, 11
	s_add_u32 vcc_lo, vcc_lo, 0x4000000
	s_add_u32 s100, s14, vcc_lo
	s_addc_u32 s101, s15, 0
	global_store_dwordx2 v137, v[156:157], s[100:101] offset:0
	global_store_dwordx2 v137, v[158:159], s[100:101] offset:512
	global_store_dwordx2 v137, v[160:161], s[100:101] offset:1024
	global_store_dwordx2 v137, v[162:163], s[100:101] offset:1536
